# hazard-free N=1 handoff: post-barrier MFMA reads operand copies in v[248:255]
# speedup vs baseline: 1.0066x; 1.0066x over previous
; #define PG8_STAGE(bufoff, gbase, voff) do { _Pragma("unroll") for (int _i = 0; _i < 2; ++_i) \
;         asm volatile("s_mov_b32 m0, %2\n\ts_nop 0\n\tglobal_load_lds_dwordx4 %0, %1" :: "v"((voff)[_i]), "s"((const char*)(gbase)), "s"(ldsbase + (unsigned)(bufoff) + ldsw + (unsigned)_i * 8192u) : "memory", "m0"); } while (0)
; #define PG8_LDA(dst, b, h) do { _Pragma("unroll") for (int m = 0; m < 4; ++m) _Pragma("unroll") for (int k = 0; k < 2; ++k) dst[m][k] = *(const PG8_LAS bf16x8*)(lds + PG8_SA(b, h) + aoff + m * 2048 + k * 1024); } while (0)
; #define PG8_LDB(dst, b, h) do { _Pragma("unroll") for (int n = 0; n < 2; ++n) _Pragma("unroll") for (int k = 0; k < 2; ++k) dst[n][k] = *(const PG8_LAS bf16x8*)(lds + PG8_SB(b, h) + boff + n * 2048 + k * 1024); } while (0)
; #define PG8_MMA(ai, bj, At, Bt) do { __builtin_amdgcn_s_setprio(1); _Pragma("unroll") for (int m = 0; m < 4; ++m) _Pragma("unroll") for (int n = 0; n < 2; ++n) _Pragma("unroll") for (int k = 0; k < 2; ++k) \
;         acc[ai][bj][m][n] = __builtin_amdgcn_mfma_f32_16x16x32_bf16(Bt[n][k], At[m][k], acc[ai][bj][m][n], 0, 0, 0); __builtin_amdgcn_s_setprio(0); } while (0)
; template <class Epi, class Sched, bool ALIGN_EPI = false, bool SP2 = false>
; __device__ __forceinline__ void gemm_phase(PG8_LAS unsigned char* lds, const Gemm g, const Sched& S, const Epi& E) {
;     ...
;             PG8_LDB(B0, 0, 0); PG8_LDB(B1, 0, 1); PG8_SCHED; PG8_LDA(At, 0, 0); PG8_STAGE(PG8_SA(1, 1), a1 + hstep, voffA);
;             PG8_WAIT_V(8); PG8_WAIT_L(0); PG8_BAR; PG8_MMA(0, 0, At, B0); PG8_MMA(0, 1, At, B1); PG8_BAR; PG8_SCHED;
;             PG8_LDA(At, 0, 1); PG8_STAGE(PG8_SB(0, 0), b2, voffB); PG8_STAGE(PG8_SB(0, 1), b2 + hstep, voffB); PG8_STAGE(PG8_SA(0, 0), a2, voffA);
;             PG8_WAIT_V(8); PG8_WAIT_L(0); PG8_BAR; PG8_MMA(1, 0, At, B0); PG8_MMA(1, 1, At, B1); PG8_BAR; PG8_SCHED;
;             PG8_LDB(B0, 1, 0); PG8_LDB(B1, 1, 1); PG8_SCHED; PG8_LDA(At, 1, 0); PG8_STAGE(PG8_SA(0, 1), a2 + hstep, voffA);
;             PG8_WAIT_V(8); PG8_WAIT_L(0); PG8_BAR; PG8_MMA(0, 0, At, B0); PG8_MMA(0, 1, At, B1); PG8_BAR; PG8_SCHED;
;             PG8_LDA(At, 1, 1); PG8_STAGE(PG8_SB(1, 0), b3, voffB); PG8_STAGE(PG8_SB(1, 1), b3 + hstep, voffB); PG8_STAGE(PG8_SA(1, 0), a3, voffA);
;             PG8_WAIT_V(8); PG8_WAIT_L(0); PG8_BAR; PG8_MMA(1, 0, At, B0); PG8_MMA(1, 1, At, B1); PG8_BAR; PG8_SCHED;
.LBB0_138:
	ds_read_b128 v[148:151], v142
	ds_read_b128 v[152:155], v142 offset:1024
	ds_read_b128 v[156:159], v142 offset:2048
	ds_read_b128 v[160:163], v142 offset:3072
	ds_read_b128 v[164:167], v143
	ds_read_b128 v[168:171], v143 offset:1024
	ds_read_b128 v[172:175], v143 offset:2048
	ds_read_b128 v[176:179], v143 offset:3072
	s_add_u32 s62, s66, 0x100
	s_addc_u32 s63, s67, 0
	s_cmp_eq_u32 s96, 60
	s_cselect_b32 s86, s92, s62
	s_cselect_b32 s87, s13, s63
	s_cselect_b32 s84, s93, s94
	s_cselect_b32 s85, s11, s95
	s_add_u32 s76, s86, 0x80
	s_addc_u32 s77, s87, 0
	ds_read_b128 v[180:183], v144
	ds_read_b128 v[184:187], v144 offset:1024
	ds_read_b128 v[188:191], v144 offset:2048
	ds_read_b128 v[192:195], v144 offset:3072
	ds_read_b128 v[196:199], v144 offset:4096
	ds_read_b128 v[200:203], v144 offset:5120
	ds_read_b128 v[204:207], v144 offset:6144
	ds_read_b128 v[208:211], v144 offset:7168
	s_add_u32 s66, s66, 0x100080
	s_addc_u32 s67, s67, 0
	s_mov_b32 m0, s83
	s_nop 0
	global_load_lds_dwordx4 v136, s[66:67]
	s_nop 0
	s_mov_b32 m0, s88
	s_nop 0
	global_load_lds_dwordx4 v138, s[66:67]
	s_waitcnt vmcnt(8)
	s_waitcnt lgkmcnt(0)
	s_barrier
	s_setprio 1
	s_waitcnt lgkmcnt(7)
	v_mfma_f32_16x16x32_bf16 v[126:129], v[148:151], v[180:183], v[126:129]
	v_mfma_f32_16x16x32_bf16 v[122:125], v[156:159], v[180:183], v[122:125]
	s_waitcnt lgkmcnt(5)
	v_mfma_f32_16x16x32_bf16 v[110:113], v[148:151], v[188:191], v[110:113]
	v_mfma_f32_16x16x32_bf16 v[106:109], v[156:159], v[188:191], v[106:109]
	s_waitcnt lgkmcnt(3)
	v_mfma_f32_16x16x32_bf16 v[94:97], v[148:151], v[196:199], v[94:97]
	v_mfma_f32_16x16x32_bf16 v[90:93], v[156:159], v[196:199], v[90:93]
	s_waitcnt lgkmcnt(1)
	v_mfma_f32_16x16x32_bf16 v[78:81], v[148:151], v[204:207], v[78:81]
	v_mfma_f32_16x16x32_bf16 v[74:77], v[156:159], v[204:207], v[74:77]
	v_mfma_f32_16x16x32_bf16 v[126:129], v[152:155], v[184:187], v[126:129]
	v_mfma_f32_16x16x32_bf16 v[122:125], v[160:163], v[184:187], v[122:125]
	v_mfma_f32_16x16x32_bf16 v[110:113], v[152:155], v[192:195], v[110:113]
	v_mfma_f32_16x16x32_bf16 v[106:109], v[160:163], v[192:195], v[106:109]
	v_mfma_f32_16x16x32_bf16 v[94:97], v[152:155], v[200:203], v[94:97]
	v_mfma_f32_16x16x32_bf16 v[90:93], v[160:163], v[200:203], v[90:93]
	s_waitcnt lgkmcnt(0)
	v_mfma_f32_16x16x32_bf16 v[78:81], v[152:155], v[208:211], v[78:81]
	v_mfma_f32_16x16x32_bf16 v[74:77], v[160:163], v[208:211], v[74:77]
	s_setprio 0
	s_setprio 1
	v_mfma_f32_16x16x32_bf16 v[118:121], v[164:167], v[180:183], v[118:121]
	v_mfma_f32_16x16x32_bf16 v[114:117], v[172:175], v[180:183], v[114:117]
	v_mfma_f32_16x16x32_bf16 v[102:105], v[164:167], v[188:191], v[102:105]
	v_mfma_f32_16x16x32_bf16 v[98:101], v[172:175], v[188:191], v[98:101]
	v_mfma_f32_16x16x32_bf16 v[86:89], v[164:167], v[196:199], v[86:89]
	v_mfma_f32_16x16x32_bf16 v[82:85], v[172:175], v[196:199], v[82:85]
	v_mfma_f32_16x16x32_bf16 v[70:73], v[164:167], v[204:207], v[70:73]
	v_mfma_f32_16x16x32_bf16 v[66:69], v[172:175], v[204:207], v[66:69]
	v_mfma_f32_16x16x32_bf16 v[118:121], v[168:171], v[184:187], v[118:121]
	v_mfma_f32_16x16x32_bf16 v[114:117], v[176:179], v[184:187], v[114:117]
	v_mfma_f32_16x16x32_bf16 v[102:105], v[168:171], v[192:195], v[102:105]
	v_mov_b32_e32 v248, v176
	v_mov_b32_e32 v249, v177
	v_mfma_f32_16x16x32_bf16 v[98:101], v[176:179], v[192:195], v[98:101]
	v_mov_b32_e32 v250, v178
	v_mov_b32_e32 v251, v179
	v_mfma_f32_16x16x32_bf16 v[86:89], v[168:171], v[200:203], v[86:89]
	v_mov_b32_e32 v252, v208
	v_mov_b32_e32 v253, v209
	v_mfma_f32_16x16x32_bf16 v[82:85], v[176:179], v[200:203], v[82:85]
	v_mov_b32_e32 v254, v210
	v_mov_b32_e32 v255, v211
	v_mfma_f32_16x16x32_bf16 v[70:73], v[168:171], v[208:211], v[70:73]
	s_setprio 2
	s_barrier
	v_mfma_f32_16x16x32_bf16 v[66:69], v[248:251], v[252:255], v[66:69]
	s_setprio 0
	ds_read_b128 v[180:183], v144 offset:16384
	ds_read_b128 v[184:187], v144 offset:17408
	ds_read_b128 v[188:191], v144 offset:18432
	ds_read_b128 v[192:195], v144 offset:19456
	ds_read_b128 v[196:199], v144 offset:20480
	ds_read_b128 v[200:203], v144 offset:21504
	ds_read_b128 v[204:207], v144 offset:22528
	ds_read_b128 v[208:211], v144 offset:23552
	s_mov_b32 m0, s55
	s_nop 0
	global_load_lds_dwordx4 v137, s[84:85]
	s_add_u32 s66, s84, 0x100000
	s_mov_b32 m0, s56
	s_nop 0
	global_load_lds_dwordx4 v139, s[84:85]
	s_addc_u32 s67, s85, 0
	s_mov_b32 m0, s57
	s_nop 0
	global_load_lds_dwordx4 v137, s[66:67]
	s_nop 0
	s_mov_b32 m0, s58
	s_nop 0
	global_load_lds_dwordx4 v139, s[66:67]
	s_nop 0
	s_mov_b32 m0, s54
	s_nop 0
	global_load_lds_dwordx4 v136, s[86:87]
	s_nop 0
	s_mov_b32 m0, s59
	s_nop 0
	global_load_lds_dwordx4 v138, s[86:87]
	s_waitcnt vmcnt(8)
	s_waitcnt lgkmcnt(0)
	s_barrier
; #define PG8_STAGE(bufoff, gbase, voff) do { _Pragma("unroll") for (int _i = 0; _i < 2; ++_i) \
;         asm volatile("s_mov_b32 m0, %2\n\ts_nop 0\n\tglobal_load_lds_dwordx4 %0, %1" :: "v"((voff)[_i]), "s"((const char*)(gbase)), "s"(ldsbase + (unsigned)(bufoff) + ldsw + (unsigned)_i * 8192u) : "memory", "m0"); } while (0)
; #define PG8_LDA(dst, b, h) do { _Pragma("unroll") for (int m = 0; m < 4; ++m) _Pragma("unroll") for (int k = 0; k < 2; ++k) dst[m][k] = *(const PG8_LAS bf16x8*)(lds + PG8_SA(b, h) + aoff + m * 2048 + k * 1024); } while (0)
; #define PG8_LDB(dst, b, h) do { _Pragma("unroll") for (int n = 0; n < 2; ++n) _Pragma("unroll") for (int k = 0; k < 2; ++k) dst[n][k] = *(const PG8_LAS bf16x8*)(lds + PG8_SB(b, h) + boff + n * 2048 + k * 1024); } while (0)
; #define PG8_MMA(ai, bj, At, Bt) do { __builtin_amdgcn_s_setprio(1); _Pragma("unroll") for (int m = 0; m < 4; ++m) _Pragma("unroll") for (int n = 0; n < 2; ++n) _Pragma("unroll") for (int k = 0; k < 2; ++k) \
;         acc[ai][bj][m][n] = __builtin_amdgcn_mfma_f32_16x16x32_bf16(Bt[n][k], At[m][k], acc[ai][bj][m][n], 0, 0, 0); __builtin_amdgcn_s_setprio(0); } while (0)
; template <class Epi, class Sched, bool ALIGN_EPI = false, bool SP2 = false>
; __device__ __forceinline__ void gemm_phase(PG8_LAS unsigned char* lds, const Gemm g, const Sched& S, const Epi& E) {
;     ...
;             PG8_LDB(B0, 0, 0); PG8_LDB(B1, 0, 1); PG8_SCHED; PG8_LDA(At, 0, 0); PG8_STAGE(PG8_SA(1, 1), a1 + hstep, voffA);
;             PG8_WAIT_V(8); PG8_WAIT_L(0); PG8_BAR; PG8_MMA(0, 0, At, B0); PG8_MMA(0, 1, At, B1); PG8_BAR; PG8_SCHED;
;             PG8_LDA(At, 0, 1); PG8_STAGE(PG8_SB(0, 0), b2, voffB); PG8_STAGE(PG8_SB(0, 1), b2 + hstep, voffB); PG8_STAGE(PG8_SA(0, 0), a2, voffA);
;             PG8_WAIT_V(8); PG8_WAIT_L(0); PG8_BAR; PG8_MMA(1, 0, At, B0); PG8_MMA(1, 1, At, B1); PG8_BAR; PG8_SCHED;
;             PG8_LDB(B0, 1, 0); PG8_LDB(B1, 1, 1); PG8_SCHED; PG8_LDA(At, 1, 0); PG8_STAGE(PG8_SA(0, 1), a2 + hstep, voffA);
;             PG8_WAIT_V(8); PG8_WAIT_L(0); PG8_BAR; PG8_MMA(0, 0, At, B0); PG8_MMA(0, 1, At, B1); PG8_BAR; PG8_SCHED;
;             PG8_LDA(At, 1, 1); PG8_STAGE(PG8_SB(1, 0), b3, voffB); PG8_STAGE(PG8_SB(1, 1), b3 + hstep, voffB); PG8_STAGE(PG8_SA(1, 0), a3, voffA);
;             PG8_WAIT_V(8); PG8_WAIT_L(0); PG8_BAR; PG8_MMA(1, 0, At, B0); PG8_MMA(1, 1, At, B1); PG8_BAR; PG8_SCHED;
	s_setprio 1
	s_waitcnt lgkmcnt(7)
	v_mfma_f32_16x16x32_bf16 v[62:65], v[148:151], v[180:183], v[62:65]
	v_mfma_f32_16x16x32_bf16 v[58:61], v[156:159], v[180:183], v[58:61]
	s_waitcnt lgkmcnt(5)
	v_mfma_f32_16x16x32_bf16 v[46:49], v[148:151], v[188:191], v[46:49]
	v_mfma_f32_16x16x32_bf16 v[42:45], v[156:159], v[188:191], v[42:45]
	s_waitcnt lgkmcnt(3)
	v_mfma_f32_16x16x32_bf16 v[30:33], v[148:151], v[196:199], v[30:33]
	v_mfma_f32_16x16x32_bf16 v[26:29], v[156:159], v[196:199], v[26:29]
	s_waitcnt lgkmcnt(1)
	v_mfma_f32_16x16x32_bf16 v[14:17], v[148:151], v[204:207], v[14:17]
	v_mfma_f32_16x16x32_bf16 v[10:13], v[156:159], v[204:207], v[10:13]
	v_mfma_f32_16x16x32_bf16 v[62:65], v[152:155], v[184:187], v[62:65]
	v_mfma_f32_16x16x32_bf16 v[58:61], v[160:163], v[184:187], v[58:61]
	v_mfma_f32_16x16x32_bf16 v[46:49], v[152:155], v[192:195], v[46:49]
	v_mfma_f32_16x16x32_bf16 v[42:45], v[160:163], v[192:195], v[42:45]
	v_mfma_f32_16x16x32_bf16 v[30:33], v[152:155], v[200:203], v[30:33]
	v_mfma_f32_16x16x32_bf16 v[26:29], v[160:163], v[200:203], v[26:29]
	s_waitcnt lgkmcnt(0)
	v_mfma_f32_16x16x32_bf16 v[14:17], v[152:155], v[208:211], v[14:17]
	v_mfma_f32_16x16x32_bf16 v[10:13], v[160:163], v[208:211], v[10:13]
	s_setprio 0
	s_setprio 1
	v_mfma_f32_16x16x32_bf16 v[54:57], v[164:167], v[180:183], v[54:57]
	v_mfma_f32_16x16x32_bf16 v[50:53], v[172:175], v[180:183], v[50:53]
	v_mfma_f32_16x16x32_bf16 v[38:41], v[164:167], v[188:191], v[38:41]
	v_mfma_f32_16x16x32_bf16 v[34:37], v[172:175], v[188:191], v[34:37]
	v_mfma_f32_16x16x32_bf16 v[22:25], v[164:167], v[196:199], v[22:25]
	v_mfma_f32_16x16x32_bf16 v[18:21], v[172:175], v[196:199], v[18:21]
	v_mfma_f32_16x16x32_bf16 v[6:9], v[164:167], v[204:207], v[6:9]
	v_mfma_f32_16x16x32_bf16 v[2:5], v[172:175], v[204:207], v[2:5]
	v_mfma_f32_16x16x32_bf16 v[54:57], v[168:171], v[184:187], v[54:57]
	v_mfma_f32_16x16x32_bf16 v[50:53], v[176:179], v[184:187], v[50:53]
	v_mfma_f32_16x16x32_bf16 v[38:41], v[168:171], v[192:195], v[38:41]
	v_mov_b32_e32 v248, v176
	v_mov_b32_e32 v249, v177
	v_mfma_f32_16x16x32_bf16 v[34:37], v[176:179], v[192:195], v[34:37]
	v_mov_b32_e32 v250, v178
	v_mov_b32_e32 v251, v179
	v_mfma_f32_16x16x32_bf16 v[22:25], v[168:171], v[200:203], v[22:25]
	v_mov_b32_e32 v252, v208
	v_mov_b32_e32 v253, v209
	v_mfma_f32_16x16x32_bf16 v[18:21], v[176:179], v[200:203], v[18:21]
	v_mov_b32_e32 v254, v210
	v_mov_b32_e32 v255, v211
	v_mfma_f32_16x16x32_bf16 v[6:9], v[168:171], v[208:211], v[6:9]
	s_setprio 2
	s_barrier
	v_mfma_f32_16x16x32_bf16 v[2:5], v[248:251], v[252:255], v[2:5]
	s_setprio 0
	ds_read_b128 v[148:151], v145
	ds_read_b128 v[152:155], v145 offset:1024
	ds_read_b128 v[156:159], v145 offset:2048
	ds_read_b128 v[160:163], v145 offset:3072
	ds_read_b128 v[164:167], v146
	ds_read_b128 v[168:171], v146 offset:1024
	ds_read_b128 v[172:175], v146 offset:2048
	ds_read_b128 v[176:179], v146 offset:3072
	ds_read_b128 v[180:183], v144 offset:32768
	ds_read_b128 v[184:187], v144 offset:33792
	ds_read_b128 v[188:191], v144 offset:34816
	ds_read_b128 v[192:195], v144 offset:35840
	ds_read_b128 v[196:199], v144 offset:36864
	ds_read_b128 v[200:203], v144 offset:37888
	ds_read_b128 v[204:207], v144 offset:38912
	ds_read_b128 v[208:211], v144 offset:39936
	s_add_u32 s66, s86, 0x100000
	s_addc_u32 s67, s87, 0
	s_mov_b32 m0, s60
	s_nop 0
	global_load_lds_dwordx4 v136, s[66:67]
	s_nop 0
	s_mov_b32 m0, s61
	s_nop 0
	global_load_lds_dwordx4 v138, s[66:67]
	s_waitcnt vmcnt(8)
	s_waitcnt lgkmcnt(0)
	s_barrier
	s_setprio 1
	s_waitcnt lgkmcnt(7)
	v_mfma_f32_16x16x32_bf16 v[126:129], v[148:151], v[180:183], v[126:129]
	v_mfma_f32_16x16x32_bf16 v[122:125], v[156:159], v[180:183], v[122:125]
	s_waitcnt lgkmcnt(5)
	v_mfma_f32_16x16x32_bf16 v[110:113], v[148:151], v[188:191], v[110:113]
	v_mfma_f32_16x16x32_bf16 v[106:109], v[156:159], v[188:191], v[106:109]
	s_waitcnt lgkmcnt(3)
	v_mfma_f32_16x16x32_bf16 v[94:97], v[148:151], v[196:199], v[94:97]
	v_mfma_f32_16x16x32_bf16 v[90:93], v[156:159], v[196:199], v[90:93]
	s_waitcnt lgkmcnt(1)
	v_mfma_f32_16x16x32_bf16 v[78:81], v[148:151], v[204:207], v[78:81]
	v_mfma_f32_16x16x32_bf16 v[74:77], v[156:159], v[204:207], v[74:77]
	v_mfma_f32_16x16x32_bf16 v[126:129], v[152:155], v[184:187], v[126:129]
	v_mfma_f32_16x16x32_bf16 v[122:125], v[160:163], v[184:187], v[122:125]
	v_mfma_f32_16x16x32_bf16 v[110:113], v[152:155], v[192:195], v[110:113]
	v_mfma_f32_16x16x32_bf16 v[106:109], v[160:163], v[192:195], v[106:109]
	v_mfma_f32_16x16x32_bf16 v[94:97], v[152:155], v[200:203], v[94:97]
	v_mfma_f32_16x16x32_bf16 v[90:93], v[160:163], v[200:203], v[90:93]
	s_waitcnt lgkmcnt(0)
	v_mfma_f32_16x16x32_bf16 v[78:81], v[152:155], v[208:211], v[78:81]
	v_mfma_f32_16x16x32_bf16 v[74:77], v[160:163], v[208:211], v[74:77]
	s_setprio 0
	s_setprio 1
	v_mfma_f32_16x16x32_bf16 v[118:121], v[164:167], v[180:183], v[118:121]
	v_mfma_f32_16x16x32_bf16 v[114:117], v[172:175], v[180:183], v[114:117]
	v_mfma_f32_16x16x32_bf16 v[102:105], v[164:167], v[188:191], v[102:105]
	v_mfma_f32_16x16x32_bf16 v[98:101], v[172:175], v[188:191], v[98:101]
	v_mfma_f32_16x16x32_bf16 v[86:89], v[164:167], v[196:199], v[86:89]
	v_mfma_f32_16x16x32_bf16 v[82:85], v[172:175], v[196:199], v[82:85]
	v_mfma_f32_16x16x32_bf16 v[70:73], v[164:167], v[204:207], v[70:73]
	v_mfma_f32_16x16x32_bf16 v[66:69], v[172:175], v[204:207], v[66:69]
	v_mfma_f32_16x16x32_bf16 v[118:121], v[168:171], v[184:187], v[118:121]
	v_mfma_f32_16x16x32_bf16 v[114:117], v[176:179], v[184:187], v[114:117]
	v_mfma_f32_16x16x32_bf16 v[102:105], v[168:171], v[192:195], v[102:105]
	v_mov_b32_e32 v248, v176
	v_mov_b32_e32 v249, v177
	v_mfma_f32_16x16x32_bf16 v[98:101], v[176:179], v[192:195], v[98:101]
	v_mov_b32_e32 v250, v178
	v_mov_b32_e32 v251, v179
	v_mfma_f32_16x16x32_bf16 v[86:89], v[168:171], v[200:203], v[86:89]
	v_mov_b32_e32 v252, v208
	v_mov_b32_e32 v253, v209
	v_mfma_f32_16x16x32_bf16 v[82:85], v[176:179], v[200:203], v[82:85]
	v_mov_b32_e32 v254, v210
	v_mov_b32_e32 v255, v211
	v_mfma_f32_16x16x32_bf16 v[70:73], v[168:171], v[208:211], v[70:73]
	s_setprio 2
	s_barrier
; __device__ __forceinline__ unsigned cvt_pk_bf16(float lo, float hi) { unsigned r; asm volatile("v_cvt_pk_bf16_f32 %0, %1, %2" : "=v"(r) : "v"(lo), "v"(hi)); return r; }
; __device__ __forceinline__ float silu_f(float x) { return x * sigmoid_f(x); }
;     __device__ __forceinline__ void operator()(const f32x4 (&acc)[2][2][4][2], const Unit& u, int wr, int wc, int fr, int fq) const {
;         const int row0 = u.pm * BM + wr * 64 + fr, col0 = u.pn * HALF + wc * 32 + 8 * fq;
; #pragma unroll
;         for (int ai = 0; ai < 2; ++ai)
; #pragma unroll
;             for (int m = 0; m < 4; ++m) { bf16_t* rowp = O + (size_t)(row0 + ai * HALF + m * 16) * ldc + col0;
;                 const f32x4 g0 = acc[ai][0][m][0], g1 = acc[ai][0][m][1], u0 = acc[ai][1][m][0], u1 = acc[ai][1][m][1];
;                 f32x4 v0, v1;
; #pragma unroll
;                 for (int j = 0; j < 4; ++j) { v0[j] = silu_f(g0[j]) * u0[j]; v1[j] = silu_f(g1[j]) * u1[j]; }
;                 u32x4 w; w.x = cvt_pk_bf16(v0[0], v0[1]); w.y = cvt_pk_bf16(v0[2], v0[3]); w.z = cvt_pk_bf16(v1[0], v1[1]); w.w = cvt_pk_bf16(v1[2], v1[3]);
;                 *(u32x4*)rowp = w; }
; template <class Epi, class Sched, bool ALIGN_EPI = false, bool SP2 = false>
; __device__ __forceinline__ void gemm_phase(PG8_LAS unsigned char* lds, const Gemm g, const Sched& S, const Epi& E) {
;     ...
;             PG8_LDB(B0, 0, 0); PG8_LDB(B1, 0, 1); PG8_SCHED; PG8_LDA(At, 0, 0); PG8_STAGE(PG8_SA(1, 1), a1 + hstep, voffA);
;             PG8_WAIT_V(8); PG8_WAIT_L(0); PG8_BAR; PG8_MMA(0, 0, At, B0); PG8_MMA(0, 1, At, B1); PG8_BAR; PG8_SCHED;
;             PG8_LDA(At, 0, 1); PG8_STAGE(PG8_SB(0, 0), b2, voffB); PG8_STAGE(PG8_SB(0, 1), b2 + hstep, voffB); PG8_STAGE(PG8_SA(0, 0), a2, voffA);
;             PG8_WAIT_V(8); PG8_WAIT_L(0); PG8_BAR; PG8_MMA(1, 0, At, B0); PG8_MMA(1, 1, At, B1); PG8_BAR; PG8_SCHED;
;             PG8_LDB(B0, 1, 0); PG8_LDB(B1, 1, 1); PG8_SCHED; PG8_LDA(At, 1, 0); PG8_STAGE(PG8_SA(0, 1), a2 + hstep, voffA);
;             PG8_WAIT_V(8); PG8_WAIT_L(0); PG8_BAR; PG8_MMA(0, 0, At, B0); PG8_MMA(0, 1, At, B1); PG8_BAR; PG8_SCHED;
;             PG8_LDA(At, 1, 1); PG8_STAGE(PG8_SB(1, 0), b3, voffB); PG8_STAGE(PG8_SB(1, 1), b3 + hstep, voffB); PG8_STAGE(PG8_SA(1, 0), a3, voffA);
;             PG8_WAIT_V(8); PG8_WAIT_L(0); PG8_BAR; PG8_MMA(1, 0, At, B0); PG8_MMA(1, 1, At, B1); PG8_BAR; PG8_SCHED;
	v_mfma_f32_16x16x32_bf16 v[66:69], v[248:251], v[252:255], v[66:69]
	s_setprio 0
	ds_read_b128 v[180:183], v144 offset:49152
	ds_read_b128 v[184:187], v144 offset:50176
	ds_read_b128 v[188:191], v144 offset:51200
	ds_read_b128 v[192:195], v144 offset:52224
	ds_read_b128 v[196:199], v144 offset:53248
	ds_read_b128 v[200:203], v144 offset:54272
	ds_read_b128 v[204:207], v144 offset:55296
	ds_read_b128 v[208:211], v144 offset:56320
	s_add_u32 s66, s84, 0x80
	s_addc_u32 s67, s85, 0
	s_mov_b32 m0, s64
	s_nop 0
	global_load_lds_dwordx4 v137, s[66:67]
	s_nop 0
	s_mov_b32 m0, s65
	s_nop 0
	global_load_lds_dwordx4 v139, s[66:67]
	s_add_u32 s66, s84, 0x100080
	s_addc_u32 s67, s85, 0
	s_mov_b32 m0, s70
	s_nop 0
	global_load_lds_dwordx4 v137, s[66:67]
	s_nop 0
	s_mov_b32 m0, s71
	s_nop 0
	global_load_lds_dwordx4 v139, s[66:67]
	s_nop 0
	s_mov_b32 m0, s68
	s_nop 0
	global_load_lds_dwordx4 v136, s[76:77]
	s_nop 0
	s_mov_b32 m0, s69
	s_nop 0
	global_load_lds_dwordx4 v138, s[76:77]
	s_waitcnt vmcnt(8)
	s_waitcnt lgkmcnt(0)
	s_barrier
	s_setprio 1
	s_waitcnt lgkmcnt(7)
	v_mfma_f32_16x16x32_bf16 v[62:65], v[148:151], v[180:183], v[62:65]
	v_mfma_f32_16x16x32_bf16 v[58:61], v[156:159], v[180:183], v[58:61]
	s_waitcnt lgkmcnt(5)
	v_mfma_f32_16x16x32_bf16 v[46:49], v[148:151], v[188:191], v[46:49]
	v_mfma_f32_16x16x32_bf16 v[42:45], v[156:159], v[188:191], v[42:45]
	s_waitcnt lgkmcnt(3)
	v_mfma_f32_16x16x32_bf16 v[30:33], v[148:151], v[196:199], v[30:33]
	v_mfma_f32_16x16x32_bf16 v[26:29], v[156:159], v[196:199], v[26:29]
	s_waitcnt lgkmcnt(1)
	v_mfma_f32_16x16x32_bf16 v[14:17], v[148:151], v[204:207], v[14:17]
	v_mfma_f32_16x16x32_bf16 v[10:13], v[156:159], v[204:207], v[10:13]
	v_mfma_f32_16x16x32_bf16 v[62:65], v[152:155], v[184:187], v[62:65]
	v_mfma_f32_16x16x32_bf16 v[58:61], v[160:163], v[184:187], v[58:61]
	v_mfma_f32_16x16x32_bf16 v[46:49], v[152:155], v[192:195], v[46:49]
	v_mfma_f32_16x16x32_bf16 v[42:45], v[160:163], v[192:195], v[42:45]
	v_mfma_f32_16x16x32_bf16 v[30:33], v[152:155], v[200:203], v[30:33]
	v_mfma_f32_16x16x32_bf16 v[26:29], v[160:163], v[200:203], v[26:29]
	s_waitcnt lgkmcnt(0)
	v_mfma_f32_16x16x32_bf16 v[14:17], v[152:155], v[208:211], v[14:17]
	v_mfma_f32_16x16x32_bf16 v[10:13], v[160:163], v[208:211], v[10:13]
	s_setprio 0
	s_setprio 1
	v_mfma_f32_16x16x32_bf16 v[54:57], v[164:167], v[180:183], v[54:57]
	v_mfma_f32_16x16x32_bf16 v[50:53], v[172:175], v[180:183], v[50:53]
	v_mfma_f32_16x16x32_bf16 v[38:41], v[164:167], v[188:191], v[38:41]
	v_mfma_f32_16x16x32_bf16 v[34:37], v[172:175], v[188:191], v[34:37]
	v_mfma_f32_16x16x32_bf16 v[22:25], v[164:167], v[196:199], v[22:25]
	v_mfma_f32_16x16x32_bf16 v[18:21], v[172:175], v[196:199], v[18:21]
	v_mfma_f32_16x16x32_bf16 v[6:9], v[164:167], v[204:207], v[6:9]
	v_mfma_f32_16x16x32_bf16 v[2:5], v[172:175], v[204:207], v[2:5]
	v_mfma_f32_16x16x32_bf16 v[54:57], v[168:171], v[184:187], v[54:57]
	v_mfma_f32_16x16x32_bf16 v[50:53], v[176:179], v[184:187], v[50:53]
	v_mfma_f32_16x16x32_bf16 v[38:41], v[168:171], v[192:195], v[38:41]
	v_mov_b32_e32 v248, v176
	v_mov_b32_e32 v249, v177
	v_mfma_f32_16x16x32_bf16 v[34:37], v[176:179], v[192:195], v[34:37]
	v_mov_b32_e32 v250, v178
	v_mov_b32_e32 v251, v179
	v_mfma_f32_16x16x32_bf16 v[22:25], v[168:171], v[200:203], v[22:25]
	v_mov_b32_e32 v252, v208
	v_mov_b32_e32 v253, v209
	v_mfma_f32_16x16x32_bf16 v[18:21], v[176:179], v[200:203], v[18:21]
	v_mov_b32_e32 v254, v210
	v_mov_b32_e32 v255, v211
	v_mfma_f32_16x16x32_bf16 v[6:9], v[168:171], v[208:211], v[6:9]
	s_setprio 2
	s_barrier
	v_mfma_f32_16x16x32_bf16 v[2:5], v[248:251], v[252:255], v[2:5]
	s_setprio 0
	s_add_i32 s96, s96, 2
	s_add_u32 s94, s94, 0x100
	s_addc_u32 s95, s95, 0
	s_cmp_gt_u32 s96, 61
	s_mov_b64 s[66:67], s[62:63]
	s_cbranch_scc0 .LBB0_138
	v_mul_f32_e32 v134, 0xbfb8aa3b, v126
	v_exp_f32_e32 v150, v134
	v_mul_f32_e32 v134, 0xbfb8aa3b, v122
	v_exp_f32_e32 v151, v134
	v_lshl_or_b32 v148, s91, 7, v141
	v_add_f32_e32 v150, 1.0, v150
	v_rcp_f32_e32 v152, v150
	v_add_f32_e32 v150, 1.0, v151
	v_rcp_f32_e32 v153, v150
	v_lshl_add_u32 v147, s82, 8, v140
	v_mul_f32_e32 v126, v126, v152
	v_mul_f32_e32 v118, v126, v118
	v_mul_f32_e32 v126, 0xbfb8aa3b, v127
	v_exp_f32_e32 v126, v126
	v_mul_f32_e32 v152, 0xbfb8aa3b, v123
	v_exp_f32_e32 v152, v152
	v_mul_f32_e32 v122, v122, v153
	v_mul_f32_e32 v122, v122, v114
	v_add_f32_e32 v114, 1.0, v126
	v_rcp_f32_e32 v114, v114
	v_add_f32_e32 v126, 1.0, v152
	v_mul_f32_e32 v152, 0xbfb8aa3b, v128
	v_rcp_f32_e32 v126, v126
	v_exp_f32_e32 v152, v152
	v_mul_f32_e32 v114, v127, v114
	v_mul_f32_e32 v119, v114, v119
	v_mul_f32_e32 v114, v123, v126
	v_add_f32_e32 v123, 1.0, v152
	v_rcp_f32_e32 v123, v123
	v_mul_f32_e32 v126, 0xbfb8aa3b, v124
	v_exp_f32_e32 v126, v126
	v_mul_f32_e32 v127, v114, v115
	v_mul_f32_e32 v114, v128, v123
	v_mul_f32_e32 v115, 0xbfb8aa3b, v129
	v_mul_f32_e32 v123, v114, v120
	v_exp_f32_e32 v115, v115
	v_mul_f32_e32 v120, 0xbfb8aa3b, v125
	v_exp_f32_e32 v120, v120
	v_add_f32_e32 v114, 1.0, v126
	v_rcp_f32_e32 v114, v114
	v_add_f32_e32 v115, 1.0, v115
	v_rcp_f32_e32 v115, v115
	v_add_f32_e32 v120, 1.0, v120
	v_rcp_f32_e32 v120, v120
	v_mul_f32_e32 v114, v124, v114
	v_mul_f32_e32 v124, v114, v116
	v_mul_f32_e32 v114, v129, v115
	v_ashrrev_i32_e32 v149, 31, v148
	v_mov_b64_e32 v[134:135], s[72:73]
	v_mul_f32_e32 v126, v114, v121
	v_mul_f32_e32 v114, v125, v120
	v_mad_i64_i32 v[150:151], s[62:63], v147, s90, v[134:135]
	v_mul_f32_e32 v125, v114, v117
	v_lshlrev_b64 v[114:115], 1, v[148:149]
	v_lshl_add_u64 v[120:121], v[150:151], 0, v[114:115]
	v_cvt_pk_bf16_f32 v116, v118, v119
	v_cvt_pk_bf16_f32 v117, v123, v126
	v_cvt_pk_bf16_f32 v118, v122, v127
; __device__ __forceinline__ unsigned cvt_pk_bf16(float lo, float hi) { unsigned r; asm volatile("v_cvt_pk_bf16_f32 %0, %1, %2" : "=v"(r) : "v"(lo), "v"(hi)); return r; }
; __device__ __forceinline__ float silu_f(float x) { return x * sigmoid_f(x); }
;     __device__ __forceinline__ void operator()(const f32x4 (&acc)[2][2][4][2], const Unit& u, int wr, int wc, int fr, int fq) const {
;         const int row0 = u.pm * BM + wr * 64 + fr, col0 = u.pn * HALF + wc * 32 + 8 * fq;
; #pragma unroll
;         for (int ai = 0; ai < 2; ++ai)
; #pragma unroll
;             for (int m = 0; m < 4; ++m) { bf16_t* rowp = O + (size_t)(row0 + ai * HALF + m * 16) * ldc + col0;
;                 const f32x4 g0 = acc[ai][0][m][0], g1 = acc[ai][0][m][1], u0 = acc[ai][1][m][0], u1 = acc[ai][1][m][1];
;                 f32x4 v0, v1;
; #pragma unroll
;                 for (int j = 0; j < 4; ++j) { v0[j] = silu_f(g0[j]) * u0[j]; v1[j] = silu_f(g1[j]) * u1[j]; }
;                 u32x4 w; w.x = cvt_pk_bf16(v0[0], v0[1]); w.y = cvt_pk_bf16(v0[2], v0[3]); w.z = cvt_pk_bf16(v1[0], v1[1]); w.w = cvt_pk_bf16(v1[2], v1[3]);
;                 *(u32x4*)rowp = w; }
	v_cvt_pk_bf16_f32 v119, v124, v125
	global_store_dwordx4 v[120:121], v[116:119], off
	s_and_b64 vcc, exec, s[0:1]
	s_mov_b32 s91, s10
	v_mul_f32_e32 v116, 0xbfb8aa3b, v110
	v_exp_f32_e32 v116, v116
	v_mul_f32_e32 v117, 0xbfb8aa3b, v106
	v_exp_f32_e32 v117, v117
	v_or_b32_e32 v118, 16, v147
	v_add_f32_e32 v116, 1.0, v116
	v_rcp_f32_e32 v119, v116
	v_add_f32_e32 v116, 1.0, v117
	v_rcp_f32_e32 v120, v116
	v_mad_i64_i32 v[116:117], s[62:63], v118, s90, v[134:135]
	v_mul_f32_e32 v110, v110, v119
	v_mul_f32_e32 v110, v110, v102
	v_mul_f32_e32 v102, v106, v120
	v_mul_f32_e32 v106, 0xbfb8aa3b, v111
	v_exp_f32_e32 v106, v106
	v_mul_f32_e32 v118, 0xbfb8aa3b, v107
	v_mul_f32_e32 v119, v102, v98
	v_exp_f32_e32 v118, v118
	v_add_f32_e32 v98, 1.0, v106
	v_rcp_f32_e32 v98, v98
	v_mul_f32_e32 v106, 0xbfb8aa3b, v112
	v_exp_f32_e32 v106, v106
	v_add_f32_e32 v102, 1.0, v118
	v_mul_f32_e32 v98, v111, v98
	v_rcp_f32_e32 v102, v102
	v_mul_f32_e32 v98, v98, v103
	v_add_f32_e32 v103, 1.0, v106
	v_rcp_f32_e32 v103, v103
	v_mul_f32_e32 v102, v107, v102
	v_mul_f32_e32 v106, 0xbfb8aa3b, v108
	v_mul_f32_e32 v107, v102, v99
	v_mul_f32_e32 v99, v112, v103
	v_exp_f32_e32 v106, v106
	v_mul_f32_e32 v99, v99, v104
	v_mul_f32_e32 v103, 0xbfb8aa3b, v113
	v_mul_f32_e32 v104, 0xbfb8aa3b, v109
	v_exp_f32_e32 v103, v103
	v_exp_f32_e32 v104, v104
	v_add_f32_e32 v102, 1.0, v106
	v_rcp_f32_e32 v102, v102
	v_add_f32_e32 v103, 1.0, v103
	v_add_f32_e32 v104, 1.0, v104
	v_rcp_f32_e32 v103, v103
	v_rcp_f32_e32 v104, v104
	v_mul_f32_e32 v102, v108, v102
	v_mul_f32_e32 v106, v102, v100
	v_mul_f32_e32 v100, v113, v103
	v_mul_f32_e32 v102, v109, v104
	v_mul_f32_e32 v100, v100, v105
	v_mul_f32_e32 v101, v102, v101
	v_lshl_add_u64 v[102:103], v[116:117], 0, v[114:115]
	v_cvt_pk_bf16_f32 v98, v110, v98
	v_cvt_pk_bf16_f32 v99, v99, v100
	v_cvt_pk_bf16_f32 v100, v119, v107
	v_cvt_pk_bf16_f32 v101, v106, v101
	global_store_dwordx4 v[102:103], v[98:101], off
	s_mov_b32 s82, s12
	s_mov_b64 s[66:67], s[14:15]
	v_mul_f32_e32 v98, 0xbfb8aa3b, v94
	v_exp_f32_e32 v98, v98
	v_mul_f32_e32 v99, 0xbfb8aa3b, v90
	v_exp_f32_e32 v99, v99
	v_or_b32_e32 v100, 32, v147
	v_add_f32_e32 v98, 1.0, v98
	v_rcp_f32_e32 v101, v98
	v_add_f32_e32 v98, 1.0, v99
	v_rcp_f32_e32 v102, v98
	v_mad_i64_i32 v[98:99], s[62:63], v100, s90, v[134:135]
	v_mul_f32_e32 v94, v94, v101
	v_mul_f32_e32 v94, v94, v86
	v_mul_f32_e32 v86, v90, v102
	v_mul_f32_e32 v90, 0xbfb8aa3b, v95
	v_exp_f32_e32 v90, v90
	v_mul_f32_e32 v100, 0xbfb8aa3b, v91
	v_mul_f32_e32 v101, v86, v82
	v_exp_f32_e32 v100, v100
	v_add_f32_e32 v82, 1.0, v90
	v_rcp_f32_e32 v82, v82
	v_mul_f32_e32 v90, 0xbfb8aa3b, v96
	v_exp_f32_e32 v90, v90
	v_add_f32_e32 v86, 1.0, v100
	v_mul_f32_e32 v82, v95, v82
	v_rcp_f32_e32 v86, v86
	v_mul_f32_e32 v82, v82, v87
	v_add_f32_e32 v87, 1.0, v90
	v_rcp_f32_e32 v87, v87
	v_mul_f32_e32 v86, v91, v86
	v_mul_f32_e32 v90, 0xbfb8aa3b, v92
	v_mul_f32_e32 v91, v86, v83
	v_mul_f32_e32 v83, v96, v87
	v_exp_f32_e32 v90, v90
	v_mul_f32_e32 v83, v83, v88
	v_mul_f32_e32 v87, 0xbfb8aa3b, v97
	v_mul_f32_e32 v88, 0xbfb8aa3b, v93
	v_exp_f32_e32 v87, v87
	v_exp_f32_e32 v88, v88
	v_add_f32_e32 v86, 1.0, v90
	v_rcp_f32_e32 v86, v86
	v_add_f32_e32 v87, 1.0, v87
	v_add_f32_e32 v88, 1.0, v88
	v_rcp_f32_e32 v87, v87
	v_rcp_f32_e32 v88, v88
	v_mul_f32_e32 v86, v92, v86
	v_mul_f32_e32 v90, v86, v84
	v_mul_f32_e32 v84, v97, v87
	v_mul_f32_e32 v86, v93, v88
	v_mul_f32_e32 v84, v84, v89
	v_mul_f32_e32 v85, v86, v85
	v_lshl_add_u64 v[86:87], v[98:99], 0, v[114:115]
	v_cvt_pk_bf16_f32 v82, v94, v82
	v_cvt_pk_bf16_f32 v83, v83, v84
	v_cvt_pk_bf16_f32 v84, v101, v91
	v_cvt_pk_bf16_f32 v85, v90, v85
	global_store_dwordx4 v[86:87], v[82:85], off
	s_nop 1
	v_mul_f32_e32 v82, 0xbfb8aa3b, v78
	v_exp_f32_e32 v82, v82
	v_mul_f32_e32 v83, 0xbfb8aa3b, v74
	v_exp_f32_e32 v83, v83
	v_or_b32_e32 v84, 48, v147
	v_add_f32_e32 v82, 1.0, v82
	v_rcp_f32_e32 v85, v82
	v_add_f32_e32 v82, 1.0, v83
	v_rcp_f32_e32 v86, v82
	v_mad_i64_i32 v[82:83], s[62:63], v84, s90, v[134:135]
	v_mul_f32_e32 v78, v78, v85
	v_mul_f32_e32 v78, v78, v70
	v_mul_f32_e32 v70, v74, v86
	v_mul_f32_e32 v74, 0xbfb8aa3b, v79
	v_exp_f32_e32 v74, v74
	v_mul_f32_e32 v84, 0xbfb8aa3b, v75
	v_mul_f32_e32 v85, v70, v66
	v_exp_f32_e32 v84, v84
	v_add_f32_e32 v66, 1.0, v74
	v_rcp_f32_e32 v66, v66
	v_mul_f32_e32 v74, 0xbfb8aa3b, v80
	v_exp_f32_e32 v74, v74
	v_add_f32_e32 v70, 1.0, v84
	v_mul_f32_e32 v66, v79, v66
	v_rcp_f32_e32 v70, v70
	v_mul_f32_e32 v66, v66, v71
	v_add_f32_e32 v71, 1.0, v74
	v_rcp_f32_e32 v71, v71
	v_mul_f32_e32 v70, v75, v70
	v_mul_f32_e32 v74, 0xbfb8aa3b, v76
	v_mul_f32_e32 v75, v70, v67
	v_mul_f32_e32 v67, v80, v71
	v_exp_f32_e32 v74, v74
	v_mul_f32_e32 v67, v67, v72
	v_mul_f32_e32 v71, 0xbfb8aa3b, v81
	v_mul_f32_e32 v72, 0xbfb8aa3b, v77
	v_exp_f32_e32 v71, v71
	v_exp_f32_e32 v72, v72
	v_add_f32_e32 v70, 1.0, v74
	v_rcp_f32_e32 v70, v70
	v_add_f32_e32 v71, 1.0, v71
	v_add_f32_e32 v72, 1.0, v72
	v_rcp_f32_e32 v71, v71
	v_rcp_f32_e32 v72, v72
	v_mul_f32_e32 v70, v76, v70
	v_mul_f32_e32 v74, v70, v68
	v_mul_f32_e32 v68, v81, v71
	v_mul_f32_e32 v70, v77, v72
	v_mul_f32_e32 v68, v68, v73
	v_mul_f32_e32 v69, v70, v69
	v_lshl_add_u64 v[70:71], v[82:83], 0, v[114:115]
	v_cvt_pk_bf16_f32 v66, v78, v66
	v_cvt_pk_bf16_f32 v67, v67, v68
	v_cvt_pk_bf16_f32 v68, v85, v75
	v_cvt_pk_bf16_f32 v69, v74, v69
	global_store_dwordx4 v[70:71], v[66:69], off
	s_nop 1
	v_mul_f32_e32 v66, 0xbfb8aa3b, v62
	v_exp_f32_e32 v66, v66
	v_mul_f32_e32 v67, 0xbfb8aa3b, v58
	v_exp_f32_e32 v67, v67
	v_add_u32_e32 v68, 0x80, v147
	v_add_f32_e32 v66, 1.0, v66
	v_rcp_f32_e32 v69, v66
	v_add_f32_e32 v66, 1.0, v67
	v_rcp_f32_e32 v70, v66
; __device__ __forceinline__ unsigned cvt_pk_bf16(float lo, float hi) { unsigned r; asm volatile("v_cvt_pk_bf16_f32 %0, %1, %2" : "=v"(r) : "v"(lo), "v"(hi)); return r; }
; __device__ __forceinline__ float silu_f(float x) { return x * sigmoid_f(x); }
; #define PG8_WAIT_V(n) asm volatile("s_waitcnt vmcnt(" #n ")" ::: "memory")
; #define PG8_BAR __builtin_amdgcn_s_barrier()
;     __device__ __forceinline__ void operator()(const f32x4 (&acc)[2][2][4][2], const Unit& u, int wr, int wc, int fr, int fq) const {
;     ...
;             for (int m = 0; m < 4; ++m) { bf16_t* rowp = O + (size_t)(row0 + ai * HALF + m * 16) * ldc + col0;
;                 const f32x4 g0 = acc[ai][0][m][0], g1 = acc[ai][0][m][1], u0 = acc[ai][1][m][0], u1 = acc[ai][1][m][1];
;                 f32x4 v0, v1;
; #pragma unroll
;                 for (int j = 0; j < 4; ++j) { v0[j] = silu_f(g0[j]) * u0[j]; v1[j] = silu_f(g1[j]) * u1[j]; }
;                 u32x4 w; w.x = cvt_pk_bf16(v0[0], v0[1]); w.y = cvt_pk_bf16(v0[2], v0[3]); w.z = cvt_pk_bf16(v1[0], v1[1]); w.w = cvt_pk_bf16(v1[2], v1[3]);
;                 *(u32x4*)rowp = w; }
; template <class Epi, class Sched, bool ALIGN_EPI = false, bool SP2 = false>
; __device__ __forceinline__ void gemm_phase(PG8_LAS unsigned char* lds, const Gemm g, const Sched& S, const Epi& E) {
;     ...
;     PG8_WAIT_V(0);
;     if constexpr (!ALIGN_EPI) { if (wr == 0) PG8_BAR; }
;     PG8_BAR;
	v_mad_i64_i32 v[66:67], s[62:63], v68, s90, v[134:135]
	v_mul_f32_e32 v62, v62, v69
	v_mul_f32_e32 v62, v62, v54
	v_mul_f32_e32 v54, v58, v70
	v_mul_f32_e32 v58, 0xbfb8aa3b, v63
	v_exp_f32_e32 v58, v58
	v_mul_f32_e32 v68, 0xbfb8aa3b, v59
	v_mul_f32_e32 v69, v54, v50
	v_exp_f32_e32 v68, v68
	v_add_f32_e32 v50, 1.0, v58
	v_rcp_f32_e32 v50, v50
	v_mul_f32_e32 v58, 0xbfb8aa3b, v64
	v_exp_f32_e32 v58, v58
	v_add_f32_e32 v54, 1.0, v68
	v_mul_f32_e32 v50, v63, v50
	v_rcp_f32_e32 v54, v54
	v_mul_f32_e32 v50, v50, v55
	v_add_f32_e32 v55, 1.0, v58
	v_rcp_f32_e32 v55, v55
	v_mul_f32_e32 v54, v59, v54
	v_mul_f32_e32 v58, 0xbfb8aa3b, v60
	v_mul_f32_e32 v59, v54, v51
	v_mul_f32_e32 v51, v64, v55
	v_exp_f32_e32 v58, v58
	v_mul_f32_e32 v51, v51, v56
	v_mul_f32_e32 v55, 0xbfb8aa3b, v65
	v_mul_f32_e32 v56, 0xbfb8aa3b, v61
	v_exp_f32_e32 v55, v55
	v_exp_f32_e32 v56, v56
	v_add_f32_e32 v54, 1.0, v58
	v_rcp_f32_e32 v54, v54
	v_add_f32_e32 v55, 1.0, v55
	v_add_f32_e32 v56, 1.0, v56
	v_rcp_f32_e32 v55, v55
	v_rcp_f32_e32 v56, v56
	v_mul_f32_e32 v54, v60, v54
	v_mul_f32_e32 v58, v54, v52
	v_mul_f32_e32 v52, v65, v55
	v_mul_f32_e32 v54, v61, v56
	v_mul_f32_e32 v52, v52, v57
	v_mul_f32_e32 v53, v54, v53
	v_lshl_add_u64 v[54:55], v[66:67], 0, v[114:115]
	v_cvt_pk_bf16_f32 v50, v62, v50
	v_cvt_pk_bf16_f32 v51, v51, v52
	v_cvt_pk_bf16_f32 v52, v69, v59
	v_cvt_pk_bf16_f32 v53, v58, v53
	global_store_dwordx4 v[54:55], v[50:53], off
	s_nop 1
	v_mul_f32_e32 v50, 0xbfb8aa3b, v46
	v_exp_f32_e32 v50, v50
	v_mul_f32_e32 v51, 0xbfb8aa3b, v42
	v_exp_f32_e32 v51, v51
	v_add_u32_e32 v52, 0x90, v147
	v_add_f32_e32 v50, 1.0, v50
	v_rcp_f32_e32 v53, v50
	v_add_f32_e32 v50, 1.0, v51
	v_rcp_f32_e32 v54, v50
	v_mad_i64_i32 v[50:51], s[62:63], v52, s90, v[134:135]
	v_mul_f32_e32 v46, v46, v53
	v_mul_f32_e32 v46, v46, v38
	v_mul_f32_e32 v38, v42, v54
	v_mul_f32_e32 v42, 0xbfb8aa3b, v47
	v_exp_f32_e32 v42, v42
	v_mul_f32_e32 v52, 0xbfb8aa3b, v43
	v_mul_f32_e32 v53, v38, v34
	v_exp_f32_e32 v52, v52
	v_add_f32_e32 v34, 1.0, v42
	v_rcp_f32_e32 v34, v34
	v_mul_f32_e32 v42, 0xbfb8aa3b, v48
	v_exp_f32_e32 v42, v42
	v_add_f32_e32 v38, 1.0, v52
	v_mul_f32_e32 v34, v47, v34
	v_rcp_f32_e32 v38, v38
	v_mul_f32_e32 v34, v34, v39
	v_add_f32_e32 v39, 1.0, v42
	v_rcp_f32_e32 v39, v39
	v_mul_f32_e32 v38, v43, v38
	v_mul_f32_e32 v42, 0xbfb8aa3b, v44
	v_mul_f32_e32 v43, v38, v35
	v_mul_f32_e32 v35, v48, v39
	v_exp_f32_e32 v42, v42
	v_mul_f32_e32 v35, v35, v40
	v_mul_f32_e32 v39, 0xbfb8aa3b, v49
	v_mul_f32_e32 v40, 0xbfb8aa3b, v45
	v_exp_f32_e32 v39, v39
	v_exp_f32_e32 v40, v40
	v_add_f32_e32 v38, 1.0, v42
	v_rcp_f32_e32 v38, v38
	v_add_f32_e32 v39, 1.0, v39
	v_add_f32_e32 v40, 1.0, v40
	v_rcp_f32_e32 v39, v39
	v_rcp_f32_e32 v40, v40
	v_mul_f32_e32 v38, v44, v38
	v_mul_f32_e32 v42, v38, v36
	v_mul_f32_e32 v36, v49, v39
	v_mul_f32_e32 v38, v45, v40
	v_mul_f32_e32 v36, v36, v41
	v_mul_f32_e32 v37, v38, v37
	v_lshl_add_u64 v[38:39], v[50:51], 0, v[114:115]
	v_cvt_pk_bf16_f32 v34, v46, v34
	v_cvt_pk_bf16_f32 v35, v35, v36
	v_cvt_pk_bf16_f32 v36, v53, v43
	v_cvt_pk_bf16_f32 v37, v42, v37
	global_store_dwordx4 v[38:39], v[34:37], off
	s_nop 1
	v_mul_f32_e32 v34, 0xbfb8aa3b, v30
	v_exp_f32_e32 v34, v34
	v_mul_f32_e32 v35, 0xbfb8aa3b, v26
	v_exp_f32_e32 v35, v35
	v_add_u32_e32 v36, 0xa0, v147
	v_add_f32_e32 v34, 1.0, v34
	v_rcp_f32_e32 v37, v34
	v_add_f32_e32 v34, 1.0, v35
	v_rcp_f32_e32 v38, v34
	v_mad_i64_i32 v[34:35], s[62:63], v36, s90, v[134:135]
	v_mul_f32_e32 v30, v30, v37
	v_mul_f32_e32 v30, v30, v22
	v_mul_f32_e32 v22, v26, v38
	v_mul_f32_e32 v26, 0xbfb8aa3b, v31
	v_exp_f32_e32 v26, v26
	v_mul_f32_e32 v36, 0xbfb8aa3b, v27
	v_mul_f32_e32 v37, v22, v18
	v_exp_f32_e32 v36, v36
	v_add_f32_e32 v18, 1.0, v26
	v_rcp_f32_e32 v18, v18
	v_mul_f32_e32 v26, 0xbfb8aa3b, v32
	v_exp_f32_e32 v26, v26
	v_add_f32_e32 v22, 1.0, v36
	v_mul_f32_e32 v18, v31, v18
	v_rcp_f32_e32 v22, v22
	v_mul_f32_e32 v18, v18, v23
	v_add_f32_e32 v23, 1.0, v26
	v_rcp_f32_e32 v23, v23
	v_mul_f32_e32 v22, v27, v22
	v_mul_f32_e32 v26, 0xbfb8aa3b, v28
	v_mul_f32_e32 v27, v22, v19
	v_mul_f32_e32 v19, v32, v23
	v_exp_f32_e32 v26, v26
	v_mul_f32_e32 v19, v19, v24
	v_mul_f32_e32 v23, 0xbfb8aa3b, v33
	v_mul_f32_e32 v24, 0xbfb8aa3b, v29
	v_exp_f32_e32 v23, v23
	v_exp_f32_e32 v24, v24
	v_add_f32_e32 v22, 1.0, v26
	v_rcp_f32_e32 v22, v22
	v_add_f32_e32 v23, 1.0, v23
	v_add_f32_e32 v24, 1.0, v24
	v_rcp_f32_e32 v23, v23
	v_rcp_f32_e32 v24, v24
	v_mul_f32_e32 v22, v28, v22
	v_mul_f32_e32 v26, v22, v20
	v_mul_f32_e32 v20, v33, v23
	v_mul_f32_e32 v22, v29, v24
	v_mul_f32_e32 v20, v20, v25
	v_mul_f32_e32 v21, v22, v21
	v_lshl_add_u64 v[22:23], v[34:35], 0, v[114:115]
	v_cvt_pk_bf16_f32 v18, v30, v18
	v_cvt_pk_bf16_f32 v19, v19, v20
	v_cvt_pk_bf16_f32 v20, v37, v27
	v_cvt_pk_bf16_f32 v21, v26, v21
	global_store_dwordx4 v[22:23], v[18:21], off
	s_nop 1
	v_mul_f32_e32 v18, 0xbfb8aa3b, v14
	v_exp_f32_e32 v18, v18
	v_mul_f32_e32 v19, 0xbfb8aa3b, v10
	v_exp_f32_e32 v19, v19
	v_add_u32_e32 v20, 0xb0, v147
	v_add_f32_e32 v18, 1.0, v18
	v_rcp_f32_e32 v21, v18
	v_add_f32_e32 v18, 1.0, v19
	v_rcp_f32_e32 v22, v18
	v_mad_i64_i32 v[18:19], s[62:63], v20, s90, v[134:135]
	v_mul_f32_e32 v14, v14, v21
	v_mul_f32_e32 v14, v14, v6
	v_mul_f32_e32 v6, v10, v22
	v_mul_f32_e32 v10, 0xbfb8aa3b, v15
	v_exp_f32_e32 v10, v10
	v_mul_f32_e32 v20, 0xbfb8aa3b, v11
	v_mul_f32_e32 v21, v6, v2
	v_exp_f32_e32 v20, v20
	v_add_f32_e32 v2, 1.0, v10
	v_rcp_f32_e32 v2, v2
	v_mul_f32_e32 v10, 0xbfb8aa3b, v16
	v_exp_f32_e32 v10, v10
	v_add_f32_e32 v6, 1.0, v20
	v_mul_f32_e32 v2, v15, v2
	v_rcp_f32_e32 v6, v6
	v_mul_f32_e32 v2, v2, v7
	v_add_f32_e32 v7, 1.0, v10
	v_rcp_f32_e32 v7, v7
	v_mul_f32_e32 v6, v11, v6
	v_mul_f32_e32 v10, 0xbfb8aa3b, v12
	v_mul_f32_e32 v11, v6, v3
	v_mul_f32_e32 v3, v16, v7
	v_exp_f32_e32 v10, v10
	v_mul_f32_e32 v3, v3, v8
	v_mul_f32_e32 v7, 0xbfb8aa3b, v17
	v_mul_f32_e32 v8, 0xbfb8aa3b, v13
	v_exp_f32_e32 v7, v7
	v_exp_f32_e32 v8, v8
	v_add_f32_e32 v6, 1.0, v10
	v_rcp_f32_e32 v6, v6
	v_add_f32_e32 v7, 1.0, v7
	v_add_f32_e32 v8, 1.0, v8
	v_rcp_f32_e32 v7, v7
	v_rcp_f32_e32 v8, v8
	v_mul_f32_e32 v6, v12, v6
	v_mul_f32_e32 v10, v6, v4
	v_mul_f32_e32 v4, v17, v7
	v_mul_f32_e32 v6, v13, v8
	v_mul_f32_e32 v4, v4, v9
	v_mul_f32_e32 v5, v6, v5
	v_lshl_add_u64 v[6:7], v[18:19], 0, v[114:115]
	s_mov_b64 s[62:63], s[16:17]
	v_cvt_pk_bf16_f32 v2, v14, v2
	v_cvt_pk_bf16_f32 v3, v3, v4
	v_cvt_pk_bf16_f32 v4, v21, v11
	v_cvt_pk_bf16_f32 v5, v10, v5
	global_store_dwordx4 v[6:7], v[2:5], off
	s_cbranch_vccz .LBB0_135
	s_waitcnt vmcnt(0)
	s_cmpk_gt_u32 s3, 0xff
	s_cbranch_scc1 .LBB0_142
	s_barrier

; #define PG8_STAGE(bufoff, gbase, voff) do { _Pragma("unroll") for (int _i = 0; _i < 2; ++_i) \
;         asm volatile("s_mov_b32 m0, %2\n\ts_nop 0\n\tglobal_load_lds_dwordx4 %0, %1" :: "v"((voff)[_i]), "s"((const char*)(gbase)), "s"(ldsbase + (unsigned)(bufoff) + ldsw + (unsigned)_i * 8192u) : "memory", "m0"); } while (0)
; #define PG8_LDA(dst, b, h) do { _Pragma("unroll") for (int m = 0; m < 4; ++m) _Pragma("unroll") for (int k = 0; k < 2; ++k) dst[m][k] = *(const PG8_LAS bf16x8*)(lds + PG8_SA(b, h) + aoff + m * 2048 + k * 1024); } while (0)
; #define PG8_LDB(dst, b, h) do { _Pragma("unroll") for (int n = 0; n < 2; ++n) _Pragma("unroll") for (int k = 0; k < 2; ++k) dst[n][k] = *(const PG8_LAS bf16x8*)(lds + PG8_SB(b, h) + boff + n * 2048 + k * 1024); } while (0)
; #define PG8_MMA(ai, bj, At, Bt) do { __builtin_amdgcn_s_setprio(1); _Pragma("unroll") for (int m = 0; m < 4; ++m) _Pragma("unroll") for (int n = 0; n < 2; ++n) _Pragma("unroll") for (int k = 0; k < 2; ++k) \
;         acc[ai][bj][m][n] = __builtin_amdgcn_mfma_f32_16x16x32_bf16(Bt[n][k], At[m][k], acc[ai][bj][m][n], 0, 0, 0); __builtin_amdgcn_s_setprio(0); } while (0)
; #define PG8_WAIT_V(n) asm volatile("s_waitcnt vmcnt(" #n ")" ::: "memory")
; #define PG8_WAIT_L(n) asm volatile("s_waitcnt lgkmcnt(" #n ")" ::: "memory")
; #define PG8_BAR __builtin_amdgcn_s_barrier()
; #define PG8_SCHED __builtin_amdgcn_sched_barrier(0)
; template <class Epi, class Sched, bool ALIGN_EPI = false, bool SP2 = false>
; __device__ __forceinline__ void gemm_phase(PG8_LAS unsigned char* lds, const Gemm g, const Sched& S, const Epi& E) {
;     ...
;             PG8_LDB(B0, 0, 0); PG8_LDB(B1, 0, 1); PG8_SCHED; PG8_LDA(At, 0, 0); PG8_STAGE(PG8_SA(1, 1), a1 + hstep, voffA);
;             PG8_WAIT_V(8); PG8_WAIT_L(0); PG8_BAR; PG8_MMA(0, 0, At, B0); PG8_MMA(0, 1, At, B1); PG8_BAR; PG8_SCHED;
;             PG8_LDA(At, 0, 1); PG8_STAGE(PG8_SB(0, 0), b2, voffB); PG8_STAGE(PG8_SB(0, 1), b2 + hstep, voffB); PG8_STAGE(PG8_SA(0, 0), a2, voffA);
.LBB0_234:
	ds_read_b128 v[134:137], v145
	ds_read_b128 v[152:155], v145 offset:1024
	ds_read_b128 v[156:159], v145 offset:2048
	ds_read_b128 v[160:163], v145 offset:3072
	ds_read_b128 v[164:167], v146
	ds_read_b128 v[168:171], v146 offset:1024
	ds_read_b128 v[172:175], v146 offset:2048
	ds_read_b128 v[176:179], v146 offset:3072
	s_cmpk_eq_i32 s57, 0xa8
	s_cselect_b32 s76, s4, s53
	s_cselect_b32 s77, s5, s54
	s_cselect_b32 s66, s46, s55
	s_cselect_b32 s67, s47, s56
	s_add_u32 s62, s76, 0x80
	s_addc_u32 s63, s77, 0
	ds_read_b128 v[180:183], v147
	ds_read_b128 v[184:187], v147 offset:1024
	ds_read_b128 v[188:191], v147 offset:2048
	ds_read_b128 v[192:195], v147 offset:3072
	ds_read_b128 v[196:199], v147 offset:4096
	ds_read_b128 v[200:203], v147 offset:5120
	ds_read_b128 v[204:207], v147 offset:6144
	ds_read_b128 v[208:211], v147 offset:7168
	s_mov_b32 m0, s94
	s_nop 0
	global_load_lds_dwordx4 v1, s[50:51]
	s_nop 0
	s_mov_b32 m0, s95
	s_nop 0
	global_load_lds_dwordx4 v141, s[50:51]
	s_waitcnt vmcnt(8)
	s_waitcnt lgkmcnt(0)
	s_barrier
	s_setprio 1
	s_waitcnt lgkmcnt(7)
	v_mfma_f32_16x16x32_bf16 v[126:129], v[134:137], v[180:183], v[126:129]
	v_mfma_f32_16x16x32_bf16 v[122:125], v[156:159], v[180:183], v[122:125]
	s_waitcnt lgkmcnt(5)
	v_mfma_f32_16x16x32_bf16 v[110:113], v[134:137], v[188:191], v[110:113]
	v_mfma_f32_16x16x32_bf16 v[106:109], v[156:159], v[188:191], v[106:109]
	s_waitcnt lgkmcnt(3)
	v_mfma_f32_16x16x32_bf16 v[94:97], v[134:137], v[196:199], v[94:97]
	v_mfma_f32_16x16x32_bf16 v[90:93], v[156:159], v[196:199], v[90:93]
	s_waitcnt lgkmcnt(1)
	v_mfma_f32_16x16x32_bf16 v[78:81], v[134:137], v[204:207], v[78:81]
	v_mfma_f32_16x16x32_bf16 v[74:77], v[156:159], v[204:207], v[74:77]
	v_mfma_f32_16x16x32_bf16 v[126:129], v[152:155], v[184:187], v[126:129]
	v_mfma_f32_16x16x32_bf16 v[122:125], v[160:163], v[184:187], v[122:125]
	v_mfma_f32_16x16x32_bf16 v[110:113], v[152:155], v[192:195], v[110:113]
	v_mfma_f32_16x16x32_bf16 v[106:109], v[160:163], v[192:195], v[106:109]
	v_mfma_f32_16x16x32_bf16 v[94:97], v[152:155], v[200:203], v[94:97]
	v_mfma_f32_16x16x32_bf16 v[90:93], v[160:163], v[200:203], v[90:93]
	s_waitcnt lgkmcnt(0)
	v_mfma_f32_16x16x32_bf16 v[78:81], v[152:155], v[208:211], v[78:81]
	v_mfma_f32_16x16x32_bf16 v[74:77], v[160:163], v[208:211], v[74:77]
	s_setprio 0
	s_setprio 1
	v_mfma_f32_16x16x32_bf16 v[118:121], v[164:167], v[180:183], v[118:121]
	v_mfma_f32_16x16x32_bf16 v[114:117], v[172:175], v[180:183], v[114:117]
	v_mfma_f32_16x16x32_bf16 v[102:105], v[164:167], v[188:191], v[102:105]
	v_mfma_f32_16x16x32_bf16 v[98:101], v[172:175], v[188:191], v[98:101]
	v_mfma_f32_16x16x32_bf16 v[86:89], v[164:167], v[196:199], v[86:89]
	v_mfma_f32_16x16x32_bf16 v[82:85], v[172:175], v[196:199], v[82:85]
	v_mfma_f32_16x16x32_bf16 v[70:73], v[164:167], v[204:207], v[70:73]
	v_mfma_f32_16x16x32_bf16 v[66:69], v[172:175], v[204:207], v[66:69]
	v_mfma_f32_16x16x32_bf16 v[118:121], v[168:171], v[184:187], v[118:121]
	v_mfma_f32_16x16x32_bf16 v[114:117], v[176:179], v[184:187], v[114:117]
	v_mfma_f32_16x16x32_bf16 v[102:105], v[168:171], v[192:195], v[102:105]
	v_mov_b32_e32 v248, v176
	v_mov_b32_e32 v249, v177
	v_mfma_f32_16x16x32_bf16 v[98:101], v[176:179], v[192:195], v[98:101]
	v_mov_b32_e32 v250, v178
	v_mov_b32_e32 v251, v179
	v_mfma_f32_16x16x32_bf16 v[86:89], v[168:171], v[200:203], v[86:89]
	v_mov_b32_e32 v252, v208
	v_mov_b32_e32 v253, v209
	v_mfma_f32_16x16x32_bf16 v[82:85], v[176:179], v[200:203], v[82:85]
	v_mov_b32_e32 v254, v210
	v_mov_b32_e32 v255, v211
	v_mfma_f32_16x16x32_bf16 v[70:73], v[168:171], v[208:211], v[70:73]
	s_setprio 2
	s_barrier
	v_mfma_f32_16x16x32_bf16 v[66:69], v[248:251], v[252:255], v[66:69]
	s_setprio 0
	ds_read_b128 v[180:183], v147 offset:16384
	ds_read_b128 v[184:187], v147 offset:17408
	ds_read_b128 v[188:191], v147 offset:18432
	ds_read_b128 v[192:195], v147 offset:19456
	ds_read_b128 v[196:199], v147 offset:20480
	ds_read_b128 v[200:203], v147 offset:21504
	ds_read_b128 v[204:207], v147 offset:22528
	ds_read_b128 v[208:211], v147 offset:23552
	s_mov_b32 m0, s64
	s_nop 0
	global_load_lds_dwordx4 v140, s[66:67]
	s_add_u32 s58, s66, 0x2b0000
	s_mov_b32 m0, s65
	s_nop 0
	global_load_lds_dwordx4 v142, s[66:67]
	s_addc_u32 s59, s67, 0
	s_mov_b32 m0, s82
	s_nop 0
	global_load_lds_dwordx4 v140, s[58:59]
	s_nop 0
	s_mov_b32 m0, s83
	s_nop 0
	global_load_lds_dwordx4 v142, s[58:59]
	s_nop 0
	s_mov_b32 m0, s35
	s_nop 0
	global_load_lds_dwordx4 v1, s[76:77]
	s_nop 0
	s_mov_b32 m0, s84
	s_nop 0
	global_load_lds_dwordx4 v141, s[76:77]
	s_waitcnt vmcnt(8)
	s_waitcnt lgkmcnt(0)
	s_barrier
; #define PG8_STAGE(bufoff, gbase, voff) do { _Pragma("unroll") for (int _i = 0; _i < 2; ++_i) \
;         asm volatile("s_mov_b32 m0, %2\n\ts_nop 0\n\tglobal_load_lds_dwordx4 %0, %1" :: "v"((voff)[_i]), "s"((const char*)(gbase)), "s"(ldsbase + (unsigned)(bufoff) + ldsw + (unsigned)_i * 8192u) : "memory", "m0"); } while (0)
; #define PG8_LDA(dst, b, h) do { _Pragma("unroll") for (int m = 0; m < 4; ++m) _Pragma("unroll") for (int k = 0; k < 2; ++k) dst[m][k] = *(const PG8_LAS bf16x8*)(lds + PG8_SA(b, h) + aoff + m * 2048 + k * 1024); } while (0)
; #define PG8_LDB(dst, b, h) do { _Pragma("unroll") for (int n = 0; n < 2; ++n) _Pragma("unroll") for (int k = 0; k < 2; ++k) dst[n][k] = *(const PG8_LAS bf16x8*)(lds + PG8_SB(b, h) + boff + n * 2048 + k * 1024); } while (0)
; #define PG8_MMA(ai, bj, At, Bt) do { __builtin_amdgcn_s_setprio(1); _Pragma("unroll") for (int m = 0; m < 4; ++m) _Pragma("unroll") for (int n = 0; n < 2; ++n) _Pragma("unroll") for (int k = 0; k < 2; ++k) \
;         acc[ai][bj][m][n] = __builtin_amdgcn_mfma_f32_16x16x32_bf16(Bt[n][k], At[m][k], acc[ai][bj][m][n], 0, 0, 0); __builtin_amdgcn_s_setprio(0); } while (0)
; #define PG8_WAIT_V(n) asm volatile("s_waitcnt vmcnt(" #n ")" ::: "memory")
; #define PG8_WAIT_L(n) asm volatile("s_waitcnt lgkmcnt(" #n ")" ::: "memory")
; #define PG8_BAR __builtin_amdgcn_s_barrier()
; #define PG8_SCHED __builtin_amdgcn_sched_barrier(0)
; template <class Epi, class Sched, bool ALIGN_EPI = false, bool SP2 = false>
; __device__ __forceinline__ void gemm_phase(PG8_LAS unsigned char* lds, const Gemm g, const Sched& S, const Epi& E) {
;     ...
;             PG8_WAIT_V(8); PG8_WAIT_L(0); PG8_BAR; PG8_MMA(0, 0, At, B0); PG8_MMA(0, 1, At, B1); PG8_BAR; PG8_SCHED;
;             PG8_LDA(At, 0, 1); PG8_STAGE(PG8_SB(0, 0), b2, voffB); PG8_STAGE(PG8_SB(0, 1), b2 + hstep, voffB); PG8_STAGE(PG8_SA(0, 0), a2, voffA);
;             PG8_WAIT_V(8); PG8_WAIT_L(0); PG8_BAR; PG8_MMA(1, 0, At, B0); PG8_MMA(1, 1, At, B1); PG8_BAR; PG8_SCHED;
;             PG8_LDB(B0, 1, 0); PG8_LDB(B1, 1, 1); PG8_SCHED; PG8_LDA(At, 1, 0); PG8_STAGE(PG8_SA(0, 1), a2 + hstep, voffA);
;             PG8_WAIT_V(8); PG8_WAIT_L(0); PG8_BAR; PG8_MMA(0, 0, At, B0); PG8_MMA(0, 1, At, B1); PG8_BAR; PG8_SCHED;
;             PG8_LDA(At, 1, 1); PG8_STAGE(PG8_SB(1, 0), b3, voffB); PG8_STAGE(PG8_SB(1, 1), b3 + hstep, voffB); PG8_STAGE(PG8_SA(1, 0), a3, voffA);
	s_setprio 1
	s_waitcnt lgkmcnt(7)
	v_mfma_f32_16x16x32_bf16 v[62:65], v[134:137], v[180:183], v[62:65]
	v_mfma_f32_16x16x32_bf16 v[58:61], v[156:159], v[180:183], v[58:61]
	s_waitcnt lgkmcnt(5)
	v_mfma_f32_16x16x32_bf16 v[46:49], v[134:137], v[188:191], v[46:49]
	v_mfma_f32_16x16x32_bf16 v[42:45], v[156:159], v[188:191], v[42:45]
	s_waitcnt lgkmcnt(3)
	v_mfma_f32_16x16x32_bf16 v[30:33], v[134:137], v[196:199], v[30:33]
	v_mfma_f32_16x16x32_bf16 v[26:29], v[156:159], v[196:199], v[26:29]
	s_waitcnt lgkmcnt(1)
	v_mfma_f32_16x16x32_bf16 v[14:17], v[134:137], v[204:207], v[14:17]
	v_mfma_f32_16x16x32_bf16 v[10:13], v[156:159], v[204:207], v[10:13]
	v_mfma_f32_16x16x32_bf16 v[62:65], v[152:155], v[184:187], v[62:65]
	v_mfma_f32_16x16x32_bf16 v[58:61], v[160:163], v[184:187], v[58:61]
	v_mfma_f32_16x16x32_bf16 v[46:49], v[152:155], v[192:195], v[46:49]
	v_mfma_f32_16x16x32_bf16 v[42:45], v[160:163], v[192:195], v[42:45]
	v_mfma_f32_16x16x32_bf16 v[30:33], v[152:155], v[200:203], v[30:33]
	v_mfma_f32_16x16x32_bf16 v[26:29], v[160:163], v[200:203], v[26:29]
	s_waitcnt lgkmcnt(0)
	v_mfma_f32_16x16x32_bf16 v[14:17], v[152:155], v[208:211], v[14:17]
	v_mfma_f32_16x16x32_bf16 v[10:13], v[160:163], v[208:211], v[10:13]
	s_setprio 0
	s_setprio 1
	v_mfma_f32_16x16x32_bf16 v[54:57], v[164:167], v[180:183], v[54:57]
	v_mfma_f32_16x16x32_bf16 v[50:53], v[172:175], v[180:183], v[50:53]
	v_mfma_f32_16x16x32_bf16 v[38:41], v[164:167], v[188:191], v[38:41]
	v_mfma_f32_16x16x32_bf16 v[34:37], v[172:175], v[188:191], v[34:37]
	v_mfma_f32_16x16x32_bf16 v[22:25], v[164:167], v[196:199], v[22:25]
	v_mfma_f32_16x16x32_bf16 v[18:21], v[172:175], v[196:199], v[18:21]
	v_mfma_f32_16x16x32_bf16 v[6:9], v[164:167], v[204:207], v[6:9]
	v_mfma_f32_16x16x32_bf16 v[2:5], v[172:175], v[204:207], v[2:5]
	v_mfma_f32_16x16x32_bf16 v[54:57], v[168:171], v[184:187], v[54:57]
	v_mfma_f32_16x16x32_bf16 v[50:53], v[176:179], v[184:187], v[50:53]
	v_mfma_f32_16x16x32_bf16 v[38:41], v[168:171], v[192:195], v[38:41]
	v_mov_b32_e32 v248, v176
	v_mov_b32_e32 v249, v177
	v_mfma_f32_16x16x32_bf16 v[34:37], v[176:179], v[192:195], v[34:37]
	v_mov_b32_e32 v250, v178
	v_mov_b32_e32 v251, v179
	v_mfma_f32_16x16x32_bf16 v[22:25], v[168:171], v[200:203], v[22:25]
	v_mov_b32_e32 v252, v208
	v_mov_b32_e32 v253, v209
	v_mfma_f32_16x16x32_bf16 v[18:21], v[176:179], v[200:203], v[18:21]
	v_mov_b32_e32 v254, v210
	v_mov_b32_e32 v255, v211
	v_mfma_f32_16x16x32_bf16 v[6:9], v[168:171], v[208:211], v[6:9]
	s_setprio 2
	s_barrier
	v_mfma_f32_16x16x32_bf16 v[2:5], v[248:251], v[252:255], v[2:5]
	s_setprio 0
	ds_read_b128 v[134:137], v148
	ds_read_b128 v[152:155], v148 offset:1024
	ds_read_b128 v[156:159], v148 offset:2048
	ds_read_b128 v[160:163], v148 offset:3072
	ds_read_b128 v[164:167], v149
	ds_read_b128 v[168:171], v149 offset:1024
	ds_read_b128 v[172:175], v149 offset:2048
	ds_read_b128 v[176:179], v149 offset:3072
	ds_read_b128 v[180:183], v147 offset:32768
	ds_read_b128 v[184:187], v147 offset:33792
	ds_read_b128 v[188:191], v147 offset:34816
	ds_read_b128 v[192:195], v147 offset:35840
	ds_read_b128 v[196:199], v147 offset:36864
	ds_read_b128 v[200:203], v147 offset:37888
	ds_read_b128 v[204:207], v147 offset:38912
	ds_read_b128 v[208:211], v147 offset:39936
	s_add_u32 s58, s76, 0x2b0000
	s_addc_u32 s59, s77, 0
	s_mov_b32 m0, s85
	s_nop 0
	global_load_lds_dwordx4 v1, s[58:59]
	s_nop 0
	s_mov_b32 m0, s86
	s_nop 0
	global_load_lds_dwordx4 v141, s[58:59]
	s_waitcnt vmcnt(8)
	s_waitcnt lgkmcnt(0)
	s_barrier
	s_setprio 1
	s_waitcnt lgkmcnt(7)
	v_mfma_f32_16x16x32_bf16 v[126:129], v[134:137], v[180:183], v[126:129]
	v_mfma_f32_16x16x32_bf16 v[122:125], v[156:159], v[180:183], v[122:125]
	s_waitcnt lgkmcnt(5)
	v_mfma_f32_16x16x32_bf16 v[110:113], v[134:137], v[188:191], v[110:113]
	v_mfma_f32_16x16x32_bf16 v[106:109], v[156:159], v[188:191], v[106:109]
	s_waitcnt lgkmcnt(3)
	v_mfma_f32_16x16x32_bf16 v[94:97], v[134:137], v[196:199], v[94:97]
	v_mfma_f32_16x16x32_bf16 v[90:93], v[156:159], v[196:199], v[90:93]
	s_waitcnt lgkmcnt(1)
	v_mfma_f32_16x16x32_bf16 v[78:81], v[134:137], v[204:207], v[78:81]
	v_mfma_f32_16x16x32_bf16 v[74:77], v[156:159], v[204:207], v[74:77]
	v_mfma_f32_16x16x32_bf16 v[126:129], v[152:155], v[184:187], v[126:129]
	v_mfma_f32_16x16x32_bf16 v[122:125], v[160:163], v[184:187], v[122:125]
	v_mfma_f32_16x16x32_bf16 v[110:113], v[152:155], v[192:195], v[110:113]
	v_mfma_f32_16x16x32_bf16 v[106:109], v[160:163], v[192:195], v[106:109]
	v_mfma_f32_16x16x32_bf16 v[94:97], v[152:155], v[200:203], v[94:97]
	v_mfma_f32_16x16x32_bf16 v[90:93], v[160:163], v[200:203], v[90:93]
	s_waitcnt lgkmcnt(0)
	v_mfma_f32_16x16x32_bf16 v[78:81], v[152:155], v[208:211], v[78:81]
	v_mfma_f32_16x16x32_bf16 v[74:77], v[160:163], v[208:211], v[74:77]
	s_setprio 0
	s_setprio 1
	v_mfma_f32_16x16x32_bf16 v[118:121], v[164:167], v[180:183], v[118:121]
	v_mfma_f32_16x16x32_bf16 v[114:117], v[172:175], v[180:183], v[114:117]
	v_mfma_f32_16x16x32_bf16 v[102:105], v[164:167], v[188:191], v[102:105]
	v_mfma_f32_16x16x32_bf16 v[98:101], v[172:175], v[188:191], v[98:101]
	v_mfma_f32_16x16x32_bf16 v[86:89], v[164:167], v[196:199], v[86:89]
	v_mfma_f32_16x16x32_bf16 v[82:85], v[172:175], v[196:199], v[82:85]
	v_mfma_f32_16x16x32_bf16 v[70:73], v[164:167], v[204:207], v[70:73]
	v_mfma_f32_16x16x32_bf16 v[66:69], v[172:175], v[204:207], v[66:69]
	v_mfma_f32_16x16x32_bf16 v[118:121], v[168:171], v[184:187], v[118:121]
	v_mfma_f32_16x16x32_bf16 v[114:117], v[176:179], v[184:187], v[114:117]
	v_mfma_f32_16x16x32_bf16 v[102:105], v[168:171], v[192:195], v[102:105]
	v_mov_b32_e32 v248, v176
	v_mov_b32_e32 v249, v177
	v_mfma_f32_16x16x32_bf16 v[98:101], v[176:179], v[192:195], v[98:101]
	v_mov_b32_e32 v250, v178
	v_mov_b32_e32 v251, v179
	v_mfma_f32_16x16x32_bf16 v[86:89], v[168:171], v[200:203], v[86:89]
	v_mov_b32_e32 v252, v208
	v_mov_b32_e32 v253, v209
	v_mfma_f32_16x16x32_bf16 v[82:85], v[176:179], v[200:203], v[82:85]
	v_mov_b32_e32 v254, v210
	v_mov_b32_e32 v255, v211
	v_mfma_f32_16x16x32_bf16 v[70:73], v[168:171], v[208:211], v[70:73]
	s_setprio 2
	s_barrier
; #define PG8_STAGE(bufoff, gbase, voff) do { _Pragma("unroll") for (int _i = 0; _i < 2; ++_i) \
;         asm volatile("s_mov_b32 m0, %2\n\ts_nop 0\n\tglobal_load_lds_dwordx4 %0, %1" :: "v"((voff)[_i]), "s"((const char*)(gbase)), "s"(ldsbase + (unsigned)(bufoff) + ldsw + (unsigned)_i * 8192u) : "memory", "m0"); } while (0)
; #define PG8_LDA(dst, b, h) do { _Pragma("unroll") for (int m = 0; m < 4; ++m) _Pragma("unroll") for (int k = 0; k < 2; ++k) dst[m][k] = *(const PG8_LAS bf16x8*)(lds + PG8_SA(b, h) + aoff + m * 2048 + k * 1024); } while (0)
; #define PG8_MMA(ai, bj, At, Bt) do { __builtin_amdgcn_s_setprio(1); _Pragma("unroll") for (int m = 0; m < 4; ++m) _Pragma("unroll") for (int n = 0; n < 2; ++n) _Pragma("unroll") for (int k = 0; k < 2; ++k) \
;         acc[ai][bj][m][n] = __builtin_amdgcn_mfma_f32_16x16x32_bf16(Bt[n][k], At[m][k], acc[ai][bj][m][n], 0, 0, 0); __builtin_amdgcn_s_setprio(0); } while (0)
; #define PG8_WAIT_V(n) asm volatile("s_waitcnt vmcnt(" #n ")" ::: "memory")
; #define PG8_WAIT_L(n) asm volatile("s_waitcnt lgkmcnt(" #n ")" ::: "memory")
; #define PG8_BAR __builtin_amdgcn_s_barrier()
; #define PG8_SCHED __builtin_amdgcn_sched_barrier(0)
; template <class Epi, class Sched, bool ALIGN_EPI = false, bool SP2 = false>
; __device__ __forceinline__ void gemm_phase(PG8_LAS unsigned char* lds, const Gemm g, const Sched& S, const Epi& E) {
;     ...
;             PG8_WAIT_V(8); PG8_WAIT_L(0); PG8_BAR; PG8_MMA(0, 0, At, B0); PG8_MMA(0, 1, At, B1); PG8_BAR; PG8_SCHED;
;             PG8_LDA(At, 1, 1); PG8_STAGE(PG8_SB(1, 0), b3, voffB); PG8_STAGE(PG8_SB(1, 1), b3 + hstep, voffB); PG8_STAGE(PG8_SA(1, 0), a3, voffA);
;             PG8_WAIT_V(8); PG8_WAIT_L(0); PG8_BAR; PG8_MMA(1, 0, At, B0); PG8_MMA(1, 1, At, B1); PG8_BAR; PG8_SCHED;
	v_mfma_f32_16x16x32_bf16 v[66:69], v[248:251], v[252:255], v[66:69]
	s_setprio 0
	ds_read_b128 v[180:183], v147 offset:49152
	ds_read_b128 v[184:187], v147 offset:50176
	ds_read_b128 v[188:191], v147 offset:51200
	ds_read_b128 v[192:195], v147 offset:52224
	ds_read_b128 v[196:199], v147 offset:53248
	ds_read_b128 v[200:203], v147 offset:54272
	ds_read_b128 v[204:207], v147 offset:55296
	ds_read_b128 v[208:211], v147 offset:56320
	s_add_u32 s58, s66, 0x80
	s_addc_u32 s59, s67, 0
	s_mov_b32 m0, s88
	s_nop 0
	global_load_lds_dwordx4 v140, s[58:59]
	s_nop 0
	s_mov_b32 m0, s89
	s_nop 0
	global_load_lds_dwordx4 v142, s[58:59]
	s_add_u32 s58, s66, 0x2b0080
	s_addc_u32 s59, s67, 0
	s_mov_b32 m0, s92
	s_nop 0
	global_load_lds_dwordx4 v140, s[58:59]
	s_nop 0
	s_mov_b32 m0, s93
	s_nop 0
	global_load_lds_dwordx4 v142, s[58:59]
	s_nop 0
	s_mov_b32 m0, s90
	s_nop 0
	global_load_lds_dwordx4 v1, s[62:63]
	s_nop 0
	s_mov_b32 m0, s91
	s_nop 0
	global_load_lds_dwordx4 v141, s[62:63]
	s_waitcnt vmcnt(8)
	s_waitcnt lgkmcnt(0)
	s_barrier
	s_setprio 1
	s_waitcnt lgkmcnt(7)
	v_mfma_f32_16x16x32_bf16 v[62:65], v[134:137], v[180:183], v[62:65]
	v_mfma_f32_16x16x32_bf16 v[58:61], v[156:159], v[180:183], v[58:61]
	s_waitcnt lgkmcnt(5)
	v_mfma_f32_16x16x32_bf16 v[46:49], v[134:137], v[188:191], v[46:49]
	v_mfma_f32_16x16x32_bf16 v[42:45], v[156:159], v[188:191], v[42:45]
	s_waitcnt lgkmcnt(3)
	v_mfma_f32_16x16x32_bf16 v[30:33], v[134:137], v[196:199], v[30:33]
	v_mfma_f32_16x16x32_bf16 v[26:29], v[156:159], v[196:199], v[26:29]
	s_waitcnt lgkmcnt(1)
	v_mfma_f32_16x16x32_bf16 v[14:17], v[134:137], v[204:207], v[14:17]
	v_mfma_f32_16x16x32_bf16 v[10:13], v[156:159], v[204:207], v[10:13]
	v_mfma_f32_16x16x32_bf16 v[62:65], v[152:155], v[184:187], v[62:65]
	v_mfma_f32_16x16x32_bf16 v[58:61], v[160:163], v[184:187], v[58:61]
	v_mfma_f32_16x16x32_bf16 v[46:49], v[152:155], v[192:195], v[46:49]
	v_mfma_f32_16x16x32_bf16 v[42:45], v[160:163], v[192:195], v[42:45]
	v_mfma_f32_16x16x32_bf16 v[30:33], v[152:155], v[200:203], v[30:33]
	v_mfma_f32_16x16x32_bf16 v[26:29], v[160:163], v[200:203], v[26:29]
	s_waitcnt lgkmcnt(0)
	v_mfma_f32_16x16x32_bf16 v[14:17], v[152:155], v[208:211], v[14:17]
	v_mfma_f32_16x16x32_bf16 v[10:13], v[160:163], v[208:211], v[10:13]
	s_setprio 0
	s_setprio 1
	v_mfma_f32_16x16x32_bf16 v[54:57], v[164:167], v[180:183], v[54:57]
	v_mfma_f32_16x16x32_bf16 v[50:53], v[172:175], v[180:183], v[50:53]
	v_mfma_f32_16x16x32_bf16 v[38:41], v[164:167], v[188:191], v[38:41]
	v_mfma_f32_16x16x32_bf16 v[34:37], v[172:175], v[188:191], v[34:37]
	v_mfma_f32_16x16x32_bf16 v[22:25], v[164:167], v[196:199], v[22:25]
	v_mfma_f32_16x16x32_bf16 v[18:21], v[172:175], v[196:199], v[18:21]
	v_mfma_f32_16x16x32_bf16 v[6:9], v[164:167], v[204:207], v[6:9]
	v_mfma_f32_16x16x32_bf16 v[2:5], v[172:175], v[204:207], v[2:5]
	v_mfma_f32_16x16x32_bf16 v[54:57], v[168:171], v[184:187], v[54:57]
	v_mfma_f32_16x16x32_bf16 v[50:53], v[176:179], v[184:187], v[50:53]
	v_mfma_f32_16x16x32_bf16 v[38:41], v[168:171], v[192:195], v[38:41]
	v_mov_b32_e32 v248, v176
	v_mov_b32_e32 v249, v177
	v_mfma_f32_16x16x32_bf16 v[34:37], v[176:179], v[192:195], v[34:37]
	v_mov_b32_e32 v250, v178
	v_mov_b32_e32 v251, v179
	v_mfma_f32_16x16x32_bf16 v[22:25], v[168:171], v[200:203], v[22:25]
	v_mov_b32_e32 v252, v208
	v_mov_b32_e32 v253, v209
	v_mfma_f32_16x16x32_bf16 v[18:21], v[176:179], v[200:203], v[18:21]
	v_mov_b32_e32 v254, v210
	v_mov_b32_e32 v255, v211
	v_mfma_f32_16x16x32_bf16 v[6:9], v[168:171], v[208:211], v[6:9]
	s_setprio 2
	s_barrier
	v_mfma_f32_16x16x32_bf16 v[2:5], v[248:251], v[252:255], v[2:5]
	s_setprio 0
	s_add_i32 s57, s57, 2
	s_add_u32 s53, s53, 0x100
	s_addc_u32 s54, s54, 0
	s_add_u32 s55, s55, 0x100
	s_addc_u32 s56, s56, 0
	s_add_u32 s50, s50, 0x100
	s_addc_u32 s51, s51, 0
	s_cmpk_gt_u32 s57, 0xa9
	s_cbranch_scc0 .LBB0_234
	s_and_b64 vcc, exec, s[16:17]
	s_cbranch_vccz .LBB0_237
	s_barrier

; #define PG8_STAGE(bufoff, gbase, voff) do { _Pragma("unroll") for (int _i = 0; _i < 2; ++_i) \
;         asm volatile("s_mov_b32 m0, %2\n\ts_nop 0\n\tglobal_load_lds_dwordx4 %0, %1" :: "v"((voff)[_i]), "s"((const char*)(gbase)), "s"(ldsbase + (unsigned)(bufoff) + ldsw + (unsigned)_i * 8192u) : "memory", "m0"); } while (0)
; #define PG8_LDA(dst, b, h) do { _Pragma("unroll") for (int m = 0; m < 4; ++m) _Pragma("unroll") for (int k = 0; k < 2; ++k) dst[m][k] = *(const PG8_LAS bf16x8*)(lds + PG8_SA(b, h) + aoff + m * 2048 + k * 1024); } while (0)
; #define PG8_LDB(dst, b, h) do { _Pragma("unroll") for (int n = 0; n < 2; ++n) _Pragma("unroll") for (int k = 0; k < 2; ++k) dst[n][k] = *(const PG8_LAS bf16x8*)(lds + PG8_SB(b, h) + boff + n * 2048 + k * 1024); } while (0)
; #define PG8_MMA(ai, bj, At, Bt) do { __builtin_amdgcn_s_setprio(1); _Pragma("unroll") for (int m = 0; m < 4; ++m) _Pragma("unroll") for (int n = 0; n < 2; ++n) _Pragma("unroll") for (int k = 0; k < 2; ++k) \
;         acc[ai][bj][m][n] = __builtin_amdgcn_mfma_f32_16x16x32_bf16(Bt[n][k], At[m][k], acc[ai][bj][m][n], 0, 0, 0); __builtin_amdgcn_s_setprio(0); } while (0)
; #define PG8_WAIT_V(n) asm volatile("s_waitcnt vmcnt(" #n ")" ::: "memory")
; #define PG8_WAIT_L(n) asm volatile("s_waitcnt lgkmcnt(" #n ")" ::: "memory")
; #define PG8_BAR __builtin_amdgcn_s_barrier()
; #define PG8_SCHED __builtin_amdgcn_sched_barrier(0)
; template <class Epi, class Sched, bool ALIGN_EPI = false, bool SP2 = false>
; __device__ __forceinline__ void gemm_phase(PG8_LAS unsigned char* lds, const Gemm g, const Sched& S, const Epi& E) {
;     ...
;             PG8_LDB(B0, 0, 0); PG8_LDB(B1, 0, 1); PG8_SCHED; PG8_LDA(At, 0, 0); PG8_STAGE(PG8_SA(1, 1), a1 + hstep, voffA);
;             PG8_WAIT_V(8); PG8_WAIT_L(0); PG8_BAR; PG8_MMA(0, 0, At, B0); PG8_MMA(0, 1, At, B1); PG8_BAR; PG8_SCHED;
;             PG8_LDA(At, 0, 1); PG8_STAGE(PG8_SB(0, 0), b2, voffB); PG8_STAGE(PG8_SB(0, 1), b2 + hstep, voffB); PG8_STAGE(PG8_SA(0, 0), a2, voffA);
.LBB0_325:
	v_add_u32_e32 v138, 0x10000, v151
	ds_read_b128 v[154:157], v138
	ds_read_b128 v[158:161], v138 offset:1024
	ds_read_b128 v[162:165], v138 offset:2048
	ds_read_b128 v[166:169], v138 offset:3072
	v_add_u32_e32 v138, 0x14000, v151
	s_add_u32 s8, s82, 0x100
	ds_read_b128 v[170:173], v138
	ds_read_b128 v[174:177], v138 offset:1024
	ds_read_b128 v[178:181], v138 offset:2048
	ds_read_b128 v[182:185], v138 offset:3072
	s_addc_u32 s9, s83, 0
	s_and_b64 s[60:61], s[62:63], exec
	s_cselect_b32 s84, s54, s8
	s_cselect_b32 s85, s19, s9
	s_cselect_b32 s63, s17, s57
	s_cselect_b32 s62, s55, s56
	s_add_u32 s66, s84, 0x80
	s_addc_u32 s67, s85, 0
	s_add_u32 s76, s62, 0x80
	s_addc_u32 s77, s63, 0
	ds_read_b128 v[186:189], v152
	ds_read_b128 v[190:193], v152 offset:1024
	ds_read_b128 v[194:197], v152 offset:2048
	ds_read_b128 v[198:201], v152 offset:3072
	ds_read_b128 v[202:205], v152 offset:4096
	ds_read_b128 v[206:209], v152 offset:5120
	ds_read_b128 v[210:213], v152 offset:6144
	ds_read_b128 v[214:217], v152 offset:7168
	s_add_u32 s60, s82, 0x100080
	s_addc_u32 s61, s83, 0
	s_mov_b32 m0, s97
	s_nop 0
	global_load_lds_dwordx4 v141, s[60:61]
	s_nop 0
	s_mov_b32 m0, s70
	s_nop 0
	global_load_lds_dwordx4 v143, s[60:61]
	s_waitcnt vmcnt(8)
	s_waitcnt lgkmcnt(0)
	s_barrier
	s_setprio 1
	s_waitcnt lgkmcnt(7)
	v_mfma_f32_16x16x32_bf16 v[126:129], v[154:157], v[186:189], v[126:129]
	v_mfma_f32_16x16x32_bf16 v[122:125], v[162:165], v[186:189], v[122:125]
	s_waitcnt lgkmcnt(5)
	v_mfma_f32_16x16x32_bf16 v[110:113], v[154:157], v[194:197], v[110:113]
	v_mfma_f32_16x16x32_bf16 v[106:109], v[162:165], v[194:197], v[106:109]
	s_waitcnt lgkmcnt(3)
	v_mfma_f32_16x16x32_bf16 v[94:97], v[154:157], v[202:205], v[94:97]
	v_mfma_f32_16x16x32_bf16 v[90:93], v[162:165], v[202:205], v[90:93]
	s_waitcnt lgkmcnt(1)
	v_mfma_f32_16x16x32_bf16 v[78:81], v[154:157], v[210:213], v[78:81]
	v_mfma_f32_16x16x32_bf16 v[74:77], v[162:165], v[210:213], v[74:77]
	v_mfma_f32_16x16x32_bf16 v[126:129], v[158:161], v[190:193], v[126:129]
	v_mfma_f32_16x16x32_bf16 v[122:125], v[166:169], v[190:193], v[122:125]
	v_mfma_f32_16x16x32_bf16 v[110:113], v[158:161], v[198:201], v[110:113]
	v_mfma_f32_16x16x32_bf16 v[106:109], v[166:169], v[198:201], v[106:109]
	v_mfma_f32_16x16x32_bf16 v[94:97], v[158:161], v[206:209], v[94:97]
	v_mfma_f32_16x16x32_bf16 v[90:93], v[166:169], v[206:209], v[90:93]
	s_waitcnt lgkmcnt(0)
	v_mfma_f32_16x16x32_bf16 v[78:81], v[158:161], v[214:217], v[78:81]
	v_mfma_f32_16x16x32_bf16 v[74:77], v[166:169], v[214:217], v[74:77]
	s_setprio 0
	s_setprio 1
	v_mfma_f32_16x16x32_bf16 v[118:121], v[170:173], v[186:189], v[118:121]
	v_mfma_f32_16x16x32_bf16 v[114:117], v[178:181], v[186:189], v[114:117]
	v_mfma_f32_16x16x32_bf16 v[102:105], v[170:173], v[194:197], v[102:105]
	v_mfma_f32_16x16x32_bf16 v[98:101], v[178:181], v[194:197], v[98:101]
	v_mfma_f32_16x16x32_bf16 v[86:89], v[170:173], v[202:205], v[86:89]
	v_mfma_f32_16x16x32_bf16 v[82:85], v[178:181], v[202:205], v[82:85]
	v_mfma_f32_16x16x32_bf16 v[70:73], v[170:173], v[210:213], v[70:73]
	v_mfma_f32_16x16x32_bf16 v[66:69], v[178:181], v[210:213], v[66:69]
	v_mfma_f32_16x16x32_bf16 v[118:121], v[174:177], v[190:193], v[118:121]
	v_mfma_f32_16x16x32_bf16 v[114:117], v[182:185], v[190:193], v[114:117]
	v_mfma_f32_16x16x32_bf16 v[102:105], v[174:177], v[198:201], v[102:105]
	v_mov_b32_e32 v248, v182
	v_mov_b32_e32 v249, v183
	v_mfma_f32_16x16x32_bf16 v[98:101], v[182:185], v[198:201], v[98:101]
	v_mov_b32_e32 v250, v184
	v_mov_b32_e32 v251, v185
	v_mfma_f32_16x16x32_bf16 v[86:89], v[174:177], v[206:209], v[86:89]
	v_mov_b32_e32 v252, v214
	v_mov_b32_e32 v253, v215
	v_mfma_f32_16x16x32_bf16 v[82:85], v[182:185], v[206:209], v[82:85]
	v_mov_b32_e32 v254, v216
	v_mov_b32_e32 v255, v217
	v_mfma_f32_16x16x32_bf16 v[70:73], v[174:177], v[214:217], v[70:73]
	s_setprio 2
	s_barrier
	v_mfma_f32_16x16x32_bf16 v[66:69], v[248:251], v[252:255], v[66:69]
	s_setprio 0
	ds_read_b128 v[186:189], v152 offset:16384
	ds_read_b128 v[190:193], v152 offset:17408
	ds_read_b128 v[194:197], v152 offset:18432
	ds_read_b128 v[198:201], v152 offset:19456
	ds_read_b128 v[202:205], v152 offset:20480
	ds_read_b128 v[206:209], v152 offset:21504
	ds_read_b128 v[210:213], v152 offset:22528
	ds_read_b128 v[214:217], v152 offset:23552
	s_mov_b32 m0, s68
	s_nop 0
	global_load_lds_dwordx4 v142, s[62:63]
	s_add_u32 s60, s62, 0x100000
	s_mov_b32 m0, s69
	s_nop 0
	global_load_lds_dwordx4 v144, s[62:63]
	s_addc_u32 s61, s63, 0
	s_mov_b32 m0, s81
	s_nop 0
	global_load_lds_dwordx4 v142, s[60:61]
	s_nop 0
	s_mov_b32 m0, s86
	s_nop 0
	global_load_lds_dwordx4 v144, s[60:61]
	s_nop 0
	s_mov_b32 m0, s65
	s_nop 0
	global_load_lds_dwordx4 v141, s[84:85]
	s_nop 0
	s_mov_b32 m0, s87
	s_nop 0
	global_load_lds_dwordx4 v143, s[84:85]
	s_waitcnt vmcnt(8)
	s_waitcnt lgkmcnt(0)
	s_barrier
; #define PG8_STAGE(bufoff, gbase, voff) do { _Pragma("unroll") for (int _i = 0; _i < 2; ++_i) \
;         asm volatile("s_mov_b32 m0, %2\n\ts_nop 0\n\tglobal_load_lds_dwordx4 %0, %1" :: "v"((voff)[_i]), "s"((const char*)(gbase)), "s"(ldsbase + (unsigned)(bufoff) + ldsw + (unsigned)_i * 8192u) : "memory", "m0"); } while (0)
; #define PG8_LDA(dst, b, h) do { _Pragma("unroll") for (int m = 0; m < 4; ++m) _Pragma("unroll") for (int k = 0; k < 2; ++k) dst[m][k] = *(const PG8_LAS bf16x8*)(lds + PG8_SA(b, h) + aoff + m * 2048 + k * 1024); } while (0)
; #define PG8_LDB(dst, b, h) do { _Pragma("unroll") for (int n = 0; n < 2; ++n) _Pragma("unroll") for (int k = 0; k < 2; ++k) dst[n][k] = *(const PG8_LAS bf16x8*)(lds + PG8_SB(b, h) + boff + n * 2048 + k * 1024); } while (0)
; #define PG8_MMA(ai, bj, At, Bt) do { __builtin_amdgcn_s_setprio(1); _Pragma("unroll") for (int m = 0; m < 4; ++m) _Pragma("unroll") for (int n = 0; n < 2; ++n) _Pragma("unroll") for (int k = 0; k < 2; ++k) \
;         acc[ai][bj][m][n] = __builtin_amdgcn_mfma_f32_16x16x32_bf16(Bt[n][k], At[m][k], acc[ai][bj][m][n], 0, 0, 0); __builtin_amdgcn_s_setprio(0); } while (0)
; #define PG8_WAIT_V(n) asm volatile("s_waitcnt vmcnt(" #n ")" ::: "memory")
; #define PG8_WAIT_L(n) asm volatile("s_waitcnt lgkmcnt(" #n ")" ::: "memory")
; #define PG8_BAR __builtin_amdgcn_s_barrier()
; #define PG8_SCHED __builtin_amdgcn_sched_barrier(0)
; template <class Epi, class Sched, bool ALIGN_EPI = false, bool SP2 = false>
; __device__ __forceinline__ void gemm_phase(PG8_LAS unsigned char* lds, const Gemm g, const Sched& S, const Epi& E) {
;     ...
;             PG8_WAIT_V(8); PG8_WAIT_L(0); PG8_BAR; PG8_MMA(0, 0, At, B0); PG8_MMA(0, 1, At, B1); PG8_BAR; PG8_SCHED;
;             PG8_LDA(At, 0, 1); PG8_STAGE(PG8_SB(0, 0), b2, voffB); PG8_STAGE(PG8_SB(0, 1), b2 + hstep, voffB); PG8_STAGE(PG8_SA(0, 0), a2, voffA);
;             PG8_WAIT_V(8); PG8_WAIT_L(0); PG8_BAR; PG8_MMA(1, 0, At, B0); PG8_MMA(1, 1, At, B1); PG8_BAR; PG8_SCHED;
;             PG8_LDB(B0, 1, 0); PG8_LDB(B1, 1, 1); PG8_SCHED; PG8_LDA(At, 1, 0); PG8_STAGE(PG8_SA(0, 1), a2 + hstep, voffA);
;             PG8_WAIT_V(8); PG8_WAIT_L(0); PG8_BAR; PG8_MMA(0, 0, At, B0); PG8_MMA(0, 1, At, B1); PG8_BAR; PG8_SCHED;
;             PG8_LDA(At, 1, 1); PG8_STAGE(PG8_SB(1, 0), b3, voffB); PG8_STAGE(PG8_SB(1, 1), b3 + hstep, voffB); PG8_STAGE(PG8_SA(1, 0), a3, voffA);
	s_setprio 1
	s_waitcnt lgkmcnt(7)
	v_mfma_f32_16x16x32_bf16 v[62:65], v[154:157], v[186:189], v[62:65]
	v_mfma_f32_16x16x32_bf16 v[58:61], v[162:165], v[186:189], v[58:61]
	s_waitcnt lgkmcnt(5)
	v_mfma_f32_16x16x32_bf16 v[46:49], v[154:157], v[194:197], v[46:49]
	v_mfma_f32_16x16x32_bf16 v[42:45], v[162:165], v[194:197], v[42:45]
	s_waitcnt lgkmcnt(3)
	v_mfma_f32_16x16x32_bf16 v[30:33], v[154:157], v[202:205], v[30:33]
	v_mfma_f32_16x16x32_bf16 v[26:29], v[162:165], v[202:205], v[26:29]
	s_waitcnt lgkmcnt(1)
	v_mfma_f32_16x16x32_bf16 v[14:17], v[154:157], v[210:213], v[14:17]
	v_mfma_f32_16x16x32_bf16 v[10:13], v[162:165], v[210:213], v[10:13]
	v_mfma_f32_16x16x32_bf16 v[62:65], v[158:161], v[190:193], v[62:65]
	v_mfma_f32_16x16x32_bf16 v[58:61], v[166:169], v[190:193], v[58:61]
	v_mfma_f32_16x16x32_bf16 v[46:49], v[158:161], v[198:201], v[46:49]
	v_mfma_f32_16x16x32_bf16 v[42:45], v[166:169], v[198:201], v[42:45]
	v_mfma_f32_16x16x32_bf16 v[30:33], v[158:161], v[206:209], v[30:33]
	v_mfma_f32_16x16x32_bf16 v[26:29], v[166:169], v[206:209], v[26:29]
	s_waitcnt lgkmcnt(0)
	v_mfma_f32_16x16x32_bf16 v[14:17], v[158:161], v[214:217], v[14:17]
	v_mfma_f32_16x16x32_bf16 v[10:13], v[166:169], v[214:217], v[10:13]
	s_setprio 0
	s_setprio 1
	v_mfma_f32_16x16x32_bf16 v[54:57], v[170:173], v[186:189], v[54:57]
	v_mfma_f32_16x16x32_bf16 v[50:53], v[178:181], v[186:189], v[50:53]
	v_mfma_f32_16x16x32_bf16 v[38:41], v[170:173], v[194:197], v[38:41]
	v_mfma_f32_16x16x32_bf16 v[34:37], v[178:181], v[194:197], v[34:37]
	v_mfma_f32_16x16x32_bf16 v[22:25], v[170:173], v[202:205], v[22:25]
	v_mfma_f32_16x16x32_bf16 v[18:21], v[178:181], v[202:205], v[18:21]
	v_mfma_f32_16x16x32_bf16 v[6:9], v[170:173], v[210:213], v[6:9]
	v_mfma_f32_16x16x32_bf16 v[2:5], v[178:181], v[210:213], v[2:5]
	v_mfma_f32_16x16x32_bf16 v[54:57], v[174:177], v[190:193], v[54:57]
	v_mfma_f32_16x16x32_bf16 v[50:53], v[182:185], v[190:193], v[50:53]
	v_mfma_f32_16x16x32_bf16 v[38:41], v[174:177], v[198:201], v[38:41]
	v_mov_b32_e32 v248, v182
	v_mov_b32_e32 v249, v183
	v_mfma_f32_16x16x32_bf16 v[34:37], v[182:185], v[198:201], v[34:37]
	v_mov_b32_e32 v250, v184
	v_mov_b32_e32 v251, v185
	v_mfma_f32_16x16x32_bf16 v[22:25], v[174:177], v[206:209], v[22:25]
	v_mov_b32_e32 v252, v214
	v_mov_b32_e32 v253, v215
	v_mfma_f32_16x16x32_bf16 v[18:21], v[182:185], v[206:209], v[18:21]
	v_mov_b32_e32 v254, v216
	v_mov_b32_e32 v255, v217
	v_mfma_f32_16x16x32_bf16 v[6:9], v[174:177], v[214:217], v[6:9]
	s_setprio 2
	s_barrier
	v_mfma_f32_16x16x32_bf16 v[2:5], v[248:251], v[252:255], v[2:5]
	s_setprio 0
	v_add_u32_e32 v138, 0x18000, v151
	ds_read_b128 v[154:157], v138
	ds_read_b128 v[158:161], v138 offset:1024
	ds_read_b128 v[162:165], v138 offset:2048
	ds_read_b128 v[166:169], v138 offset:3072
	v_add_u32_e32 v138, 0x1c000, v151
	ds_read_b128 v[170:173], v138
	ds_read_b128 v[174:177], v138 offset:1024
	ds_read_b128 v[178:181], v138 offset:2048
	ds_read_b128 v[182:185], v138 offset:3072
	ds_read_b128 v[186:189], v152 offset:32768
	ds_read_b128 v[190:193], v152 offset:33792
	ds_read_b128 v[194:197], v152 offset:34816
	ds_read_b128 v[198:201], v152 offset:35840
	ds_read_b128 v[202:205], v152 offset:36864
	ds_read_b128 v[206:209], v152 offset:37888
	ds_read_b128 v[210:213], v152 offset:38912
	ds_read_b128 v[214:217], v152 offset:39936
	s_add_u32 s60, s84, 0x100000
	s_addc_u32 s61, s85, 0
	s_mov_b32 m0, s88
	s_nop 0
	global_load_lds_dwordx4 v141, s[60:61]
	s_nop 0
	s_mov_b32 m0, s89
	s_nop 0
	global_load_lds_dwordx4 v143, s[60:61]
	s_waitcnt vmcnt(8)
	s_waitcnt lgkmcnt(0)
	s_barrier
	s_setprio 1
	s_waitcnt lgkmcnt(7)
	v_mfma_f32_16x16x32_bf16 v[126:129], v[154:157], v[186:189], v[126:129]
	v_mfma_f32_16x16x32_bf16 v[122:125], v[162:165], v[186:189], v[122:125]
	s_waitcnt lgkmcnt(5)
	v_mfma_f32_16x16x32_bf16 v[110:113], v[154:157], v[194:197], v[110:113]
	v_mfma_f32_16x16x32_bf16 v[106:109], v[162:165], v[194:197], v[106:109]
	s_waitcnt lgkmcnt(3)
	v_mfma_f32_16x16x32_bf16 v[94:97], v[154:157], v[202:205], v[94:97]
	v_mfma_f32_16x16x32_bf16 v[90:93], v[162:165], v[202:205], v[90:93]
	s_waitcnt lgkmcnt(1)
	v_mfma_f32_16x16x32_bf16 v[78:81], v[154:157], v[210:213], v[78:81]
	v_mfma_f32_16x16x32_bf16 v[74:77], v[162:165], v[210:213], v[74:77]
	v_mfma_f32_16x16x32_bf16 v[126:129], v[158:161], v[190:193], v[126:129]
	v_mfma_f32_16x16x32_bf16 v[122:125], v[166:169], v[190:193], v[122:125]
	v_mfma_f32_16x16x32_bf16 v[110:113], v[158:161], v[198:201], v[110:113]
	v_mfma_f32_16x16x32_bf16 v[106:109], v[166:169], v[198:201], v[106:109]
	v_mfma_f32_16x16x32_bf16 v[94:97], v[158:161], v[206:209], v[94:97]
	v_mfma_f32_16x16x32_bf16 v[90:93], v[166:169], v[206:209], v[90:93]
	s_waitcnt lgkmcnt(0)
	v_mfma_f32_16x16x32_bf16 v[78:81], v[158:161], v[214:217], v[78:81]
	v_mfma_f32_16x16x32_bf16 v[74:77], v[166:169], v[214:217], v[74:77]
	s_setprio 0
	s_setprio 1
	v_mfma_f32_16x16x32_bf16 v[118:121], v[170:173], v[186:189], v[118:121]
	v_mfma_f32_16x16x32_bf16 v[114:117], v[178:181], v[186:189], v[114:117]
	v_mfma_f32_16x16x32_bf16 v[102:105], v[170:173], v[194:197], v[102:105]
	v_mfma_f32_16x16x32_bf16 v[98:101], v[178:181], v[194:197], v[98:101]
	v_mfma_f32_16x16x32_bf16 v[86:89], v[170:173], v[202:205], v[86:89]
	v_mfma_f32_16x16x32_bf16 v[82:85], v[178:181], v[202:205], v[82:85]
	v_mfma_f32_16x16x32_bf16 v[70:73], v[170:173], v[210:213], v[70:73]
	v_mfma_f32_16x16x32_bf16 v[66:69], v[178:181], v[210:213], v[66:69]
	v_mfma_f32_16x16x32_bf16 v[118:121], v[174:177], v[190:193], v[118:121]
	v_mfma_f32_16x16x32_bf16 v[114:117], v[182:185], v[190:193], v[114:117]
	v_mfma_f32_16x16x32_bf16 v[102:105], v[174:177], v[198:201], v[102:105]
	v_mov_b32_e32 v248, v182
	v_mov_b32_e32 v249, v183
	v_mfma_f32_16x16x32_bf16 v[98:101], v[182:185], v[198:201], v[98:101]
	v_mov_b32_e32 v250, v184
	v_mov_b32_e32 v251, v185
	v_mfma_f32_16x16x32_bf16 v[86:89], v[174:177], v[206:209], v[86:89]
	v_mov_b32_e32 v252, v214
	v_mov_b32_e32 v253, v215
	v_mfma_f32_16x16x32_bf16 v[82:85], v[182:185], v[206:209], v[82:85]
	v_mov_b32_e32 v254, v216
	v_mov_b32_e32 v255, v217
	v_mfma_f32_16x16x32_bf16 v[70:73], v[174:177], v[214:217], v[70:73]
	s_setprio 2
	s_barrier
; #define PG8_STAGE(bufoff, gbase, voff) do { _Pragma("unroll") for (int _i = 0; _i < 2; ++_i) \
;         asm volatile("s_mov_b32 m0, %2\n\ts_nop 0\n\tglobal_load_lds_dwordx4 %0, %1" :: "v"((voff)[_i]), "s"((const char*)(gbase)), "s"(ldsbase + (unsigned)(bufoff) + ldsw + (unsigned)_i * 8192u) : "memory", "m0"); } while (0)
; #define PG8_LDA(dst, b, h) do { _Pragma("unroll") for (int m = 0; m < 4; ++m) _Pragma("unroll") for (int k = 0; k < 2; ++k) dst[m][k] = *(const PG8_LAS bf16x8*)(lds + PG8_SA(b, h) + aoff + m * 2048 + k * 1024); } while (0)
; #define PG8_MMA(ai, bj, At, Bt) do { __builtin_amdgcn_s_setprio(1); _Pragma("unroll") for (int m = 0; m < 4; ++m) _Pragma("unroll") for (int n = 0; n < 2; ++n) _Pragma("unroll") for (int k = 0; k < 2; ++k) \
;         acc[ai][bj][m][n] = __builtin_amdgcn_mfma_f32_16x16x32_bf16(Bt[n][k], At[m][k], acc[ai][bj][m][n], 0, 0, 0); __builtin_amdgcn_s_setprio(0); } while (0)
; #define PG8_WAIT_V(n) asm volatile("s_waitcnt vmcnt(" #n ")" ::: "memory")
; #define PG8_WAIT_L(n) asm volatile("s_waitcnt lgkmcnt(" #n ")" ::: "memory")
; #define PG8_BAR __builtin_amdgcn_s_barrier()
; #define PG8_SCHED __builtin_amdgcn_sched_barrier(0)
; template <class Epi, class Sched, bool ALIGN_EPI = false, bool SP2 = false>
; __device__ __forceinline__ void gemm_phase(PG8_LAS unsigned char* lds, const Gemm g, const Sched& S, const Epi& E) {
;     ...
;             PG8_WAIT_V(8); PG8_WAIT_L(0); PG8_BAR; PG8_MMA(0, 0, At, B0); PG8_MMA(0, 1, At, B1); PG8_BAR; PG8_SCHED;
;             PG8_LDA(At, 1, 1); PG8_STAGE(PG8_SB(1, 0), b3, voffB); PG8_STAGE(PG8_SB(1, 1), b3 + hstep, voffB); PG8_STAGE(PG8_SA(1, 0), a3, voffA);
;             PG8_WAIT_V(8); PG8_WAIT_L(0); PG8_BAR; PG8_MMA(1, 0, At, B0); PG8_MMA(1, 1, At, B1); PG8_BAR; PG8_SCHED;
	v_mfma_f32_16x16x32_bf16 v[66:69], v[248:251], v[252:255], v[66:69]
	s_setprio 0
	ds_read_b128 v[186:189], v152 offset:49152
	ds_read_b128 v[190:193], v152 offset:50176
	ds_read_b128 v[194:197], v152 offset:51200
	ds_read_b128 v[198:201], v152 offset:52224
	ds_read_b128 v[202:205], v152 offset:53248
	ds_read_b128 v[206:209], v152 offset:54272
	ds_read_b128 v[210:213], v152 offset:55296
	ds_read_b128 v[214:217], v152 offset:56320
	s_mov_b32 m0, s90
	s_nop 0
	global_load_lds_dwordx4 v142, s[76:77]
	s_add_u32 s60, s62, 0x100080
	s_mov_b32 m0, s91
	s_nop 0
	global_load_lds_dwordx4 v144, s[76:77]
	s_addc_u32 s61, s63, 0
	s_mov_b32 m0, s95
	s_nop 0
	global_load_lds_dwordx4 v142, s[60:61]
	s_nop 0
	s_mov_b32 m0, s96
	s_nop 0
	global_load_lds_dwordx4 v144, s[60:61]
	s_nop 0
	s_mov_b32 m0, s92
	s_nop 0
	global_load_lds_dwordx4 v141, s[66:67]
	s_nop 0
	s_mov_b32 m0, s94
	s_nop 0
	global_load_lds_dwordx4 v143, s[66:67]
	s_waitcnt vmcnt(8)
	s_waitcnt lgkmcnt(0)
	s_barrier
	s_setprio 1
	s_waitcnt lgkmcnt(7)
	v_mfma_f32_16x16x32_bf16 v[62:65], v[154:157], v[186:189], v[62:65]
	v_mfma_f32_16x16x32_bf16 v[58:61], v[162:165], v[186:189], v[58:61]
	s_waitcnt lgkmcnt(5)
	v_mfma_f32_16x16x32_bf16 v[46:49], v[154:157], v[194:197], v[46:49]
	v_mfma_f32_16x16x32_bf16 v[42:45], v[162:165], v[194:197], v[42:45]
	s_waitcnt lgkmcnt(3)
	v_mfma_f32_16x16x32_bf16 v[30:33], v[154:157], v[202:205], v[30:33]
	v_mfma_f32_16x16x32_bf16 v[26:29], v[162:165], v[202:205], v[26:29]
	s_waitcnt lgkmcnt(1)
	v_mfma_f32_16x16x32_bf16 v[14:17], v[154:157], v[210:213], v[14:17]
	v_mfma_f32_16x16x32_bf16 v[10:13], v[162:165], v[210:213], v[10:13]
	v_mfma_f32_16x16x32_bf16 v[62:65], v[158:161], v[190:193], v[62:65]
	v_mfma_f32_16x16x32_bf16 v[58:61], v[166:169], v[190:193], v[58:61]
	v_mfma_f32_16x16x32_bf16 v[46:49], v[158:161], v[198:201], v[46:49]
	v_mfma_f32_16x16x32_bf16 v[42:45], v[166:169], v[198:201], v[42:45]
	v_mfma_f32_16x16x32_bf16 v[30:33], v[158:161], v[206:209], v[30:33]
	v_mfma_f32_16x16x32_bf16 v[26:29], v[166:169], v[206:209], v[26:29]
	s_waitcnt lgkmcnt(0)
	v_mfma_f32_16x16x32_bf16 v[14:17], v[158:161], v[214:217], v[14:17]
	v_mfma_f32_16x16x32_bf16 v[10:13], v[166:169], v[214:217], v[10:13]
	s_setprio 0
	s_setprio 1
	v_mfma_f32_16x16x32_bf16 v[54:57], v[170:173], v[186:189], v[54:57]
	v_mfma_f32_16x16x32_bf16 v[50:53], v[178:181], v[186:189], v[50:53]
	v_mfma_f32_16x16x32_bf16 v[38:41], v[170:173], v[194:197], v[38:41]
	v_mfma_f32_16x16x32_bf16 v[34:37], v[178:181], v[194:197], v[34:37]
	v_mfma_f32_16x16x32_bf16 v[22:25], v[170:173], v[202:205], v[22:25]
	v_mfma_f32_16x16x32_bf16 v[18:21], v[178:181], v[202:205], v[18:21]
	v_mfma_f32_16x16x32_bf16 v[6:9], v[170:173], v[210:213], v[6:9]
	v_mfma_f32_16x16x32_bf16 v[2:5], v[178:181], v[210:213], v[2:5]
	v_mfma_f32_16x16x32_bf16 v[54:57], v[174:177], v[190:193], v[54:57]
	v_mfma_f32_16x16x32_bf16 v[50:53], v[182:185], v[190:193], v[50:53]
	v_mfma_f32_16x16x32_bf16 v[38:41], v[174:177], v[198:201], v[38:41]
	v_mov_b32_e32 v248, v182
	v_mov_b32_e32 v249, v183
	v_mfma_f32_16x16x32_bf16 v[34:37], v[182:185], v[198:201], v[34:37]
	v_mov_b32_e32 v250, v184
	v_mov_b32_e32 v251, v185
	v_mfma_f32_16x16x32_bf16 v[22:25], v[174:177], v[206:209], v[22:25]
	v_mov_b32_e32 v252, v214
	v_mov_b32_e32 v253, v215
	v_mfma_f32_16x16x32_bf16 v[18:21], v[182:185], v[206:209], v[18:21]
	v_mov_b32_e32 v254, v216
	v_mov_b32_e32 v255, v217
	v_mfma_f32_16x16x32_bf16 v[6:9], v[174:177], v[214:217], v[6:9]
	s_setprio 2
	s_barrier
	v_mfma_f32_16x16x32_bf16 v[2:5], v[248:251], v[252:255], v[2:5]
	s_setprio 0
	s_add_i32 s58, s58, 2
	s_add_u32 s56, s56, 0x100
	s_addc_u32 s57, s57, 0
	s_cmp_gt_u32 s58, 61
	s_cbranch_scc1 .LBB0_316
	s_mov_b64 s[82:83], s[8:9]
	s_branch .LBB0_320

; #define PG8_STAGE(bufoff, gbase, voff) do { _Pragma("unroll") for (int _i = 0; _i < 2; ++_i) \
;         asm volatile("s_mov_b32 m0, %2\n\ts_nop 0\n\tglobal_load_lds_dwordx4 %0, %1" :: "v"((voff)[_i]), "s"((const char*)(gbase)), "s"(ldsbase + (unsigned)(bufoff) + ldsw + (unsigned)_i * 8192u) : "memory", "m0"); } while (0)
; #define PG8_LDA(dst, b, h) do { _Pragma("unroll") for (int m = 0; m < 4; ++m) _Pragma("unroll") for (int k = 0; k < 2; ++k) dst[m][k] = *(const PG8_LAS bf16x8*)(lds + PG8_SA(b, h) + aoff + m * 2048 + k * 1024); } while (0)
; #define PG8_LDB(dst, b, h) do { _Pragma("unroll") for (int n = 0; n < 2; ++n) _Pragma("unroll") for (int k = 0; k < 2; ++k) dst[n][k] = *(const PG8_LAS bf16x8*)(lds + PG8_SB(b, h) + boff + n * 2048 + k * 1024); } while (0)
; #define PG8_MMA(ai, bj, At, Bt) do { __builtin_amdgcn_s_setprio(1); _Pragma("unroll") for (int m = 0; m < 4; ++m) _Pragma("unroll") for (int n = 0; n < 2; ++n) _Pragma("unroll") for (int k = 0; k < 2; ++k) \
;         acc[ai][bj][m][n] = __builtin_amdgcn_mfma_f32_16x16x32_bf16(Bt[n][k], At[m][k], acc[ai][bj][m][n], 0, 0, 0); __builtin_amdgcn_s_setprio(0); } while (0)
; #define PG8_WAIT_V(n) asm volatile("s_waitcnt vmcnt(" #n ")" ::: "memory")
; #define PG8_WAIT_L(n) asm volatile("s_waitcnt lgkmcnt(" #n ")" ::: "memory")
; #define PG8_BAR __builtin_amdgcn_s_barrier()
; #define PG8_SCHED __builtin_amdgcn_sched_barrier(0)
; template <class Epi, class Sched, bool ALIGN_EPI = false, bool SP2 = false>
; __device__ __forceinline__ void gemm_phase(PG8_LAS unsigned char* lds, const Gemm g, const Sched& S, const Epi& E) {
;     ...
;             PG8_LDB(B0, 0, 0); PG8_LDB(B1, 0, 1); PG8_SCHED; PG8_LDA(At, 0, 0); PG8_STAGE(PG8_SA(1, 1), a1 + hstep, voffA);
;             PG8_WAIT_V(8); PG8_WAIT_L(0); PG8_BAR; PG8_MMA(0, 0, At, B0); PG8_MMA(0, 1, At, B1); PG8_BAR; PG8_SCHED;
;             PG8_LDA(At, 0, 1); PG8_STAGE(PG8_SB(0, 0), b2, voffB); PG8_STAGE(PG8_SB(0, 1), b2 + hstep, voffB); PG8_STAGE(PG8_SA(0, 0), a2, voffA);
.LBB0_620:
	v_add_u32_e32 v3, 0x10000, v199
	ds_read_b128 v[134:137], v3
	ds_read_b128 v[138:141], v3 offset:1024
	ds_read_b128 v[142:145], v3 offset:2048
	ds_read_b128 v[146:149], v3 offset:3072
	v_add_u32_e32 v3, 0x14000, v199
	s_add_u32 s44, s42, 0x100
	ds_read_b128 v[158:161], v3
	ds_read_b128 v[162:165], v3 offset:1024
	ds_read_b128 v[166:169], v3 offset:2048
	ds_read_b128 v[170:173], v3 offset:3072
	s_addc_u32 s45, s43, 0
	s_cmp_eq_u32 s92, 60
	s_cselect_b32 s56, s88, s44
	s_cselect_b32 s57, s23, s45
	s_cselect_b32 s47, s19, s91
	s_cselect_b32 s46, s89, s90
	s_add_u32 s50, s56, 0x80
	s_addc_u32 s51, s57, 0
	s_add_u32 s54, s46, 0x80
	s_addc_u32 s55, s47, 0
	ds_read_b128 v[174:177], v200
	ds_read_b128 v[178:181], v200 offset:1024
	ds_read_b128 v[182:185], v200 offset:2048
	ds_read_b128 v[186:189], v200 offset:3072
	ds_read_b128 v[190:193], v200 offset:4096
	ds_read_b128 v[202:205], v200 offset:5120
	ds_read_b128 v[206:209], v200 offset:6144
	ds_read_b128 v[210:213], v200 offset:7168
	s_add_u32 s42, s42, 0x100080
	s_addc_u32 s43, s43, 0
	s_mov_b32 m0, s85
	s_nop 0
	global_load_lds_dwordx4 v1, s[42:43]
	s_nop 0
	s_mov_b32 m0, s86
	s_nop 0
	global_load_lds_dwordx4 v195, s[42:43]
	s_waitcnt vmcnt(8)
	s_waitcnt lgkmcnt(0)
	s_barrier
	s_setprio 1
	s_waitcnt lgkmcnt(7)
	v_mfma_f32_16x16x32_bf16 v[130:133], v[134:137], v[174:177], v[130:133]
	v_mfma_f32_16x16x32_bf16 v[126:129], v[142:145], v[174:177], v[126:129]
	s_waitcnt lgkmcnt(5)
	v_mfma_f32_16x16x32_bf16 v[122:125], v[134:137], v[182:185], v[122:125]
	v_mfma_f32_16x16x32_bf16 v[118:121], v[142:145], v[182:185], v[118:121]
	s_waitcnt lgkmcnt(3)
	v_mfma_f32_16x16x32_bf16 v[114:117], v[134:137], v[190:193], v[114:117]
	v_mfma_f32_16x16x32_bf16 v[110:113], v[142:145], v[190:193], v[110:113]
	s_waitcnt lgkmcnt(1)
	v_mfma_f32_16x16x32_bf16 v[106:109], v[134:137], v[206:209], v[106:109]
	v_mfma_f32_16x16x32_bf16 v[102:105], v[142:145], v[206:209], v[102:105]
	v_mfma_f32_16x16x32_bf16 v[130:133], v[138:141], v[178:181], v[130:133]
	v_mfma_f32_16x16x32_bf16 v[126:129], v[146:149], v[178:181], v[126:129]
	v_mfma_f32_16x16x32_bf16 v[122:125], v[138:141], v[186:189], v[122:125]
	v_mfma_f32_16x16x32_bf16 v[118:121], v[146:149], v[186:189], v[118:121]
	v_mfma_f32_16x16x32_bf16 v[114:117], v[138:141], v[202:205], v[114:117]
	v_mfma_f32_16x16x32_bf16 v[110:113], v[146:149], v[202:205], v[110:113]
	s_waitcnt lgkmcnt(0)
	v_mfma_f32_16x16x32_bf16 v[106:109], v[138:141], v[210:213], v[106:109]
	v_mfma_f32_16x16x32_bf16 v[102:105], v[146:149], v[210:213], v[102:105]
	s_setprio 0
	s_setprio 1
	v_mfma_f32_16x16x32_bf16 v[66:69], v[158:161], v[174:177], v[66:69]
	v_mfma_f32_16x16x32_bf16 v[62:65], v[166:169], v[174:177], v[62:65]
	v_mfma_f32_16x16x32_bf16 v[58:61], v[158:161], v[182:185], v[58:61]
	v_mfma_f32_16x16x32_bf16 v[54:57], v[166:169], v[182:185], v[54:57]
	v_mfma_f32_16x16x32_bf16 v[50:53], v[158:161], v[190:193], v[50:53]
	v_mfma_f32_16x16x32_bf16 v[46:49], v[166:169], v[190:193], v[46:49]
	v_mfma_f32_16x16x32_bf16 v[42:45], v[158:161], v[206:209], v[42:45]
	v_mfma_f32_16x16x32_bf16 v[38:41], v[166:169], v[206:209], v[38:41]
	v_mfma_f32_16x16x32_bf16 v[66:69], v[162:165], v[178:181], v[66:69]
	v_mfma_f32_16x16x32_bf16 v[62:65], v[170:173], v[178:181], v[62:65]
	v_mfma_f32_16x16x32_bf16 v[58:61], v[162:165], v[186:189], v[58:61]
	v_mov_b32_e32 v248, v170
	v_mov_b32_e32 v249, v171
	v_mfma_f32_16x16x32_bf16 v[54:57], v[170:173], v[186:189], v[54:57]
	v_mov_b32_e32 v250, v172
	v_mov_b32_e32 v251, v173
	v_mfma_f32_16x16x32_bf16 v[50:53], v[162:165], v[202:205], v[50:53]
	v_mov_b32_e32 v252, v210
	v_mov_b32_e32 v253, v211
	v_mfma_f32_16x16x32_bf16 v[46:49], v[170:173], v[202:205], v[46:49]
	v_mov_b32_e32 v254, v212
	v_mov_b32_e32 v255, v213
	v_mfma_f32_16x16x32_bf16 v[42:45], v[162:165], v[210:213], v[42:45]
	s_setprio 2
	s_barrier
	v_mfma_f32_16x16x32_bf16 v[38:41], v[248:251], v[252:255], v[38:41]
	s_setprio 0
	ds_read_b128 v[174:177], v200 offset:16384
	ds_read_b128 v[178:181], v200 offset:17408
	ds_read_b128 v[182:185], v200 offset:18432
	ds_read_b128 v[186:189], v200 offset:19456
	ds_read_b128 v[190:193], v200 offset:20480
	ds_read_b128 v[202:205], v200 offset:21504
	ds_read_b128 v[206:209], v200 offset:22528
	ds_read_b128 v[210:213], v200 offset:23552
	s_mov_b32 m0, s63
	s_nop 0
	global_load_lds_dwordx4 v194, s[46:47]
	s_add_u32 s42, s46, 0x100000
	s_mov_b32 m0, s64
	s_nop 0
	global_load_lds_dwordx4 v196, s[46:47]
	s_addc_u32 s43, s47, 0
	s_mov_b32 m0, s65
	s_nop 0
	global_load_lds_dwordx4 v194, s[42:43]
	s_nop 0
	s_mov_b32 m0, s66
	s_nop 0
	global_load_lds_dwordx4 v196, s[42:43]
	s_nop 0
	s_mov_b32 m0, s62
	s_nop 0
	global_load_lds_dwordx4 v1, s[56:57]
	s_nop 0
	s_mov_b32 m0, s67
	s_nop 0
	global_load_lds_dwordx4 v195, s[56:57]
	s_waitcnt vmcnt(8)
	s_waitcnt lgkmcnt(0)
	s_barrier
; #define PG8_STAGE(bufoff, gbase, voff) do { _Pragma("unroll") for (int _i = 0; _i < 2; ++_i) \
;         asm volatile("s_mov_b32 m0, %2\n\ts_nop 0\n\tglobal_load_lds_dwordx4 %0, %1" :: "v"((voff)[_i]), "s"((const char*)(gbase)), "s"(ldsbase + (unsigned)(bufoff) + ldsw + (unsigned)_i * 8192u) : "memory", "m0"); } while (0)
; #define PG8_LDA(dst, b, h) do { _Pragma("unroll") for (int m = 0; m < 4; ++m) _Pragma("unroll") for (int k = 0; k < 2; ++k) dst[m][k] = *(const PG8_LAS bf16x8*)(lds + PG8_SA(b, h) + aoff + m * 2048 + k * 1024); } while (0)
; #define PG8_LDB(dst, b, h) do { _Pragma("unroll") for (int n = 0; n < 2; ++n) _Pragma("unroll") for (int k = 0; k < 2; ++k) dst[n][k] = *(const PG8_LAS bf16x8*)(lds + PG8_SB(b, h) + boff + n * 2048 + k * 1024); } while (0)
; #define PG8_MMA(ai, bj, At, Bt) do { __builtin_amdgcn_s_setprio(1); _Pragma("unroll") for (int m = 0; m < 4; ++m) _Pragma("unroll") for (int n = 0; n < 2; ++n) _Pragma("unroll") for (int k = 0; k < 2; ++k) \
;         acc[ai][bj][m][n] = __builtin_amdgcn_mfma_f32_16x16x32_bf16(Bt[n][k], At[m][k], acc[ai][bj][m][n], 0, 0, 0); __builtin_amdgcn_s_setprio(0); } while (0)
; #define PG8_WAIT_V(n) asm volatile("s_waitcnt vmcnt(" #n ")" ::: "memory")
; #define PG8_WAIT_L(n) asm volatile("s_waitcnt lgkmcnt(" #n ")" ::: "memory")
; #define PG8_BAR __builtin_amdgcn_s_barrier()
; #define PG8_SCHED __builtin_amdgcn_sched_barrier(0)
; template <class Epi, class Sched, bool ALIGN_EPI = false, bool SP2 = false>
; __device__ __forceinline__ void gemm_phase(PG8_LAS unsigned char* lds, const Gemm g, const Sched& S, const Epi& E) {
;     ...
;             PG8_WAIT_V(8); PG8_WAIT_L(0); PG8_BAR; PG8_MMA(0, 0, At, B0); PG8_MMA(0, 1, At, B1); PG8_BAR; PG8_SCHED;
;             PG8_LDA(At, 0, 1); PG8_STAGE(PG8_SB(0, 0), b2, voffB); PG8_STAGE(PG8_SB(0, 1), b2 + hstep, voffB); PG8_STAGE(PG8_SA(0, 0), a2, voffA);
;             PG8_WAIT_V(8); PG8_WAIT_L(0); PG8_BAR; PG8_MMA(1, 0, At, B0); PG8_MMA(1, 1, At, B1); PG8_BAR; PG8_SCHED;
;             PG8_LDB(B0, 1, 0); PG8_LDB(B1, 1, 1); PG8_SCHED; PG8_LDA(At, 1, 0); PG8_STAGE(PG8_SA(0, 1), a2 + hstep, voffA);
;             PG8_WAIT_V(8); PG8_WAIT_L(0); PG8_BAR; PG8_MMA(0, 0, At, B0); PG8_MMA(0, 1, At, B1); PG8_BAR; PG8_SCHED;
;             PG8_LDA(At, 1, 1); PG8_STAGE(PG8_SB(1, 0), b3, voffB); PG8_STAGE(PG8_SB(1, 1), b3 + hstep, voffB); PG8_STAGE(PG8_SA(1, 0), a3, voffA);
	s_setprio 1
	s_waitcnt lgkmcnt(7)
	v_mfma_f32_16x16x32_bf16 v[98:101], v[134:137], v[174:177], v[98:101]
	v_mfma_f32_16x16x32_bf16 v[94:97], v[142:145], v[174:177], v[94:97]
	s_waitcnt lgkmcnt(5)
	v_mfma_f32_16x16x32_bf16 v[90:93], v[134:137], v[182:185], v[90:93]
	v_mfma_f32_16x16x32_bf16 v[86:89], v[142:145], v[182:185], v[86:89]
	s_waitcnt lgkmcnt(3)
	v_mfma_f32_16x16x32_bf16 v[82:85], v[134:137], v[190:193], v[82:85]
	v_mfma_f32_16x16x32_bf16 v[78:81], v[142:145], v[190:193], v[78:81]
	s_waitcnt lgkmcnt(1)
	v_mfma_f32_16x16x32_bf16 v[74:77], v[134:137], v[206:209], v[74:77]
	v_mfma_f32_16x16x32_bf16 v[70:73], v[142:145], v[206:209], v[70:73]
	v_mfma_f32_16x16x32_bf16 v[98:101], v[138:141], v[178:181], v[98:101]
	v_mfma_f32_16x16x32_bf16 v[94:97], v[146:149], v[178:181], v[94:97]
	v_mfma_f32_16x16x32_bf16 v[90:93], v[138:141], v[186:189], v[90:93]
	v_mfma_f32_16x16x32_bf16 v[86:89], v[146:149], v[186:189], v[86:89]
	v_mfma_f32_16x16x32_bf16 v[82:85], v[138:141], v[202:205], v[82:85]
	v_mfma_f32_16x16x32_bf16 v[78:81], v[146:149], v[202:205], v[78:81]
	s_waitcnt lgkmcnt(0)
	v_mfma_f32_16x16x32_bf16 v[74:77], v[138:141], v[210:213], v[74:77]
	v_mfma_f32_16x16x32_bf16 v[70:73], v[146:149], v[210:213], v[70:73]
	s_setprio 0
	s_setprio 1
	v_mfma_f32_16x16x32_bf16 v[34:37], v[158:161], v[174:177], v[34:37]
	v_mfma_f32_16x16x32_bf16 v[30:33], v[166:169], v[174:177], v[30:33]
	v_mfma_f32_16x16x32_bf16 v[26:29], v[158:161], v[182:185], v[26:29]
	v_mfma_f32_16x16x32_bf16 v[22:25], v[166:169], v[182:185], v[22:25]
	v_mfma_f32_16x16x32_bf16 v[18:21], v[158:161], v[190:193], v[18:21]
	v_mfma_f32_16x16x32_bf16 v[14:17], v[166:169], v[190:193], v[14:17]
	v_mfma_f32_16x16x32_bf16 v[10:13], v[158:161], v[206:209], v[10:13]
	v_mfma_f32_16x16x32_bf16 v[4:7], v[166:169], v[206:209], v[6:9]
	v_mfma_f32_16x16x32_bf16 v[34:37], v[162:165], v[178:181], v[34:37]
	v_mfma_f32_16x16x32_bf16 v[30:33], v[170:173], v[178:181], v[30:33]
	v_mfma_f32_16x16x32_bf16 v[26:29], v[162:165], v[186:189], v[26:29]
	v_mov_b32_e32 v248, v170
	v_mov_b32_e32 v249, v171
	v_mfma_f32_16x16x32_bf16 v[22:25], v[170:173], v[186:189], v[22:25]
	v_mov_b32_e32 v250, v172
	v_mov_b32_e32 v251, v173
	v_mfma_f32_16x16x32_bf16 v[18:21], v[162:165], v[202:205], v[18:21]
	v_mov_b32_e32 v252, v210
	v_mov_b32_e32 v253, v211
	v_mfma_f32_16x16x32_bf16 v[14:17], v[170:173], v[202:205], v[14:17]
	v_mov_b32_e32 v254, v212
	v_mov_b32_e32 v255, v213
	v_mfma_f32_16x16x32_bf16 v[10:13], v[162:165], v[210:213], v[10:13]
	s_setprio 2
	s_barrier
	v_mfma_f32_16x16x32_bf16 v[4:7], v[248:251], v[252:255], v[4:7]
	s_setprio 0
	v_add_u32_e32 v3, 0x18000, v199
	ds_read_b128 v[134:137], v3
	ds_read_b128 v[138:141], v3 offset:1024
	ds_read_b128 v[142:145], v3 offset:2048
	ds_read_b128 v[146:149], v3 offset:3072
	v_add_u32_e32 v3, 0x1c000, v199
	ds_read_b128 v[158:161], v3
	ds_read_b128 v[162:165], v3 offset:1024
	ds_read_b128 v[166:169], v3 offset:2048
	ds_read_b128 v[170:173], v3 offset:3072
	ds_read_b128 v[174:177], v200 offset:32768
	ds_read_b128 v[178:181], v200 offset:33792
	ds_read_b128 v[182:185], v200 offset:34816
	ds_read_b128 v[186:189], v200 offset:35840
	ds_read_b128 v[190:193], v200 offset:36864
	ds_read_b128 v[202:205], v200 offset:37888
	ds_read_b128 v[206:209], v200 offset:38912
	ds_read_b128 v[210:213], v200 offset:39936
	s_add_u32 s42, s56, 0x100000
	s_addc_u32 s43, s57, 0
	s_mov_b32 m0, s76
	s_nop 0
	global_load_lds_dwordx4 v1, s[42:43]
	s_nop 0
	s_mov_b32 m0, s77
	s_nop 0
	global_load_lds_dwordx4 v195, s[42:43]
	s_waitcnt vmcnt(8)
	s_waitcnt lgkmcnt(0)
	s_barrier
	s_setprio 1
	s_waitcnt lgkmcnt(7)
	v_mfma_f32_16x16x32_bf16 v[130:133], v[134:137], v[174:177], v[130:133]
	v_mfma_f32_16x16x32_bf16 v[126:129], v[142:145], v[174:177], v[126:129]
	s_waitcnt lgkmcnt(5)
	v_mfma_f32_16x16x32_bf16 v[122:125], v[134:137], v[182:185], v[122:125]
	v_mfma_f32_16x16x32_bf16 v[118:121], v[142:145], v[182:185], v[118:121]
	s_waitcnt lgkmcnt(3)
	v_mfma_f32_16x16x32_bf16 v[114:117], v[134:137], v[190:193], v[114:117]
	v_mfma_f32_16x16x32_bf16 v[110:113], v[142:145], v[190:193], v[110:113]
	s_waitcnt lgkmcnt(1)
	v_mfma_f32_16x16x32_bf16 v[106:109], v[134:137], v[206:209], v[106:109]
	v_mfma_f32_16x16x32_bf16 v[102:105], v[142:145], v[206:209], v[102:105]
	v_mfma_f32_16x16x32_bf16 v[130:133], v[138:141], v[178:181], v[130:133]
	v_mfma_f32_16x16x32_bf16 v[126:129], v[146:149], v[178:181], v[126:129]
	v_mfma_f32_16x16x32_bf16 v[122:125], v[138:141], v[186:189], v[122:125]
	v_mfma_f32_16x16x32_bf16 v[118:121], v[146:149], v[186:189], v[118:121]
	v_mfma_f32_16x16x32_bf16 v[114:117], v[138:141], v[202:205], v[114:117]
	v_mfma_f32_16x16x32_bf16 v[110:113], v[146:149], v[202:205], v[110:113]
	s_waitcnt lgkmcnt(0)
	v_mfma_f32_16x16x32_bf16 v[106:109], v[138:141], v[210:213], v[106:109]
	v_mfma_f32_16x16x32_bf16 v[102:105], v[146:149], v[210:213], v[102:105]
	s_setprio 0
	s_setprio 1
	v_mfma_f32_16x16x32_bf16 v[66:69], v[158:161], v[174:177], v[66:69]
	v_mfma_f32_16x16x32_bf16 v[62:65], v[166:169], v[174:177], v[62:65]
	v_mfma_f32_16x16x32_bf16 v[58:61], v[158:161], v[182:185], v[58:61]
	v_mfma_f32_16x16x32_bf16 v[54:57], v[166:169], v[182:185], v[54:57]
	v_mfma_f32_16x16x32_bf16 v[50:53], v[158:161], v[190:193], v[50:53]
	v_mfma_f32_16x16x32_bf16 v[46:49], v[166:169], v[190:193], v[46:49]
	v_mfma_f32_16x16x32_bf16 v[42:45], v[158:161], v[206:209], v[42:45]
	v_mfma_f32_16x16x32_bf16 v[38:41], v[166:169], v[206:209], v[38:41]
	v_mfma_f32_16x16x32_bf16 v[66:69], v[162:165], v[178:181], v[66:69]
	v_mfma_f32_16x16x32_bf16 v[62:65], v[170:173], v[178:181], v[62:65]
	v_mfma_f32_16x16x32_bf16 v[58:61], v[162:165], v[186:189], v[58:61]
	v_mov_b32_e32 v248, v170
	v_mov_b32_e32 v249, v171
	v_mfma_f32_16x16x32_bf16 v[54:57], v[170:173], v[186:189], v[54:57]
	v_mov_b32_e32 v250, v172
	v_mov_b32_e32 v251, v173
	v_mfma_f32_16x16x32_bf16 v[50:53], v[162:165], v[202:205], v[50:53]
	v_mov_b32_e32 v252, v210
	v_mov_b32_e32 v253, v211
	v_mfma_f32_16x16x32_bf16 v[46:49], v[170:173], v[202:205], v[46:49]
	v_mov_b32_e32 v254, v212
	v_mov_b32_e32 v255, v213
	v_mfma_f32_16x16x32_bf16 v[42:45], v[162:165], v[210:213], v[42:45]
	s_setprio 2
	s_barrier
; #define PG8_STAGE(bufoff, gbase, voff) do { _Pragma("unroll") for (int _i = 0; _i < 2; ++_i) \
;         asm volatile("s_mov_b32 m0, %2\n\ts_nop 0\n\tglobal_load_lds_dwordx4 %0, %1" :: "v"((voff)[_i]), "s"((const char*)(gbase)), "s"(ldsbase + (unsigned)(bufoff) + ldsw + (unsigned)_i * 8192u) : "memory", "m0"); } while (0)
; #define PG8_LDA(dst, b, h) do { _Pragma("unroll") for (int m = 0; m < 4; ++m) _Pragma("unroll") for (int k = 0; k < 2; ++k) dst[m][k] = *(const PG8_LAS bf16x8*)(lds + PG8_SA(b, h) + aoff + m * 2048 + k * 1024); } while (0)
; #define PG8_MMA(ai, bj, At, Bt) do { __builtin_amdgcn_s_setprio(1); _Pragma("unroll") for (int m = 0; m < 4; ++m) _Pragma("unroll") for (int n = 0; n < 2; ++n) _Pragma("unroll") for (int k = 0; k < 2; ++k) \
;         acc[ai][bj][m][n] = __builtin_amdgcn_mfma_f32_16x16x32_bf16(Bt[n][k], At[m][k], acc[ai][bj][m][n], 0, 0, 0); __builtin_amdgcn_s_setprio(0); } while (0)
; #define PG8_WAIT_V(n) asm volatile("s_waitcnt vmcnt(" #n ")" ::: "memory")
; #define PG8_WAIT_L(n) asm volatile("s_waitcnt lgkmcnt(" #n ")" ::: "memory")
; #define PG8_BAR __builtin_amdgcn_s_barrier()
; #define PG8_SCHED __builtin_amdgcn_sched_barrier(0)
; template <class Epi, class Sched, bool ALIGN_EPI = false, bool SP2 = false>
; __device__ __forceinline__ void gemm_phase(PG8_LAS unsigned char* lds, const Gemm g, const Sched& S, const Epi& E) {
;     ...
;             if constexpr (epi_has_mid<Epi>::value) { if (t == Epi::MID_T) E.mid(acc, cur, wr, wc, fr, fq); }
;     ...
;             PG8_WAIT_V(8); PG8_WAIT_L(0); PG8_BAR; PG8_MMA(0, 0, At, B0); PG8_MMA(0, 1, At, B1); PG8_BAR; PG8_SCHED;
;             PG8_LDA(At, 1, 1); PG8_STAGE(PG8_SB(1, 0), b3, voffB); PG8_STAGE(PG8_SB(1, 1), b3 + hstep, voffB); PG8_STAGE(PG8_SA(1, 0), a3, voffA);
;             PG8_WAIT_V(8); PG8_WAIT_L(0); PG8_BAR; PG8_MMA(1, 0, At, B0); PG8_MMA(1, 1, At, B1); PG8_BAR; PG8_SCHED;
	v_mfma_f32_16x16x32_bf16 v[38:41], v[248:251], v[252:255], v[38:41]
	s_setprio 0
	ds_read_b128 v[174:177], v200 offset:49152
	ds_read_b128 v[178:181], v200 offset:50176
	ds_read_b128 v[182:185], v200 offset:51200
	ds_read_b128 v[186:189], v200 offset:52224
	ds_read_b128 v[190:193], v200 offset:53248
	ds_read_b128 v[202:205], v200 offset:54272
	ds_read_b128 v[206:209], v200 offset:55296
	ds_read_b128 v[210:213], v200 offset:56320
	s_mov_b32 m0, s78
	s_nop 0
	global_load_lds_dwordx4 v194, s[54:55]
	s_add_u32 s42, s46, 0x100080
	s_mov_b32 m0, s79
	s_nop 0
	global_load_lds_dwordx4 v196, s[54:55]
	s_addc_u32 s43, s47, 0
	s_mov_b32 m0, s83
	s_nop 0
	global_load_lds_dwordx4 v194, s[42:43]
	s_nop 0
	s_mov_b32 m0, s84
	s_nop 0
	global_load_lds_dwordx4 v196, s[42:43]
	s_nop 0
	s_mov_b32 m0, s80
	s_nop 0
	global_load_lds_dwordx4 v1, s[50:51]
	s_nop 0
	s_mov_b32 m0, s82
	s_nop 0
	global_load_lds_dwordx4 v195, s[50:51]
	s_waitcnt vmcnt(8)
	s_waitcnt lgkmcnt(0)
	s_barrier
	s_setprio 1
	s_waitcnt lgkmcnt(7)
	v_mfma_f32_16x16x32_bf16 v[98:101], v[134:137], v[174:177], v[98:101]
	v_mfma_f32_16x16x32_bf16 v[94:97], v[142:145], v[174:177], v[94:97]
	s_waitcnt lgkmcnt(5)
	v_mfma_f32_16x16x32_bf16 v[90:93], v[134:137], v[182:185], v[90:93]
	v_mfma_f32_16x16x32_bf16 v[86:89], v[142:145], v[182:185], v[86:89]
	s_waitcnt lgkmcnt(3)
	v_mfma_f32_16x16x32_bf16 v[82:85], v[134:137], v[190:193], v[82:85]
	v_mfma_f32_16x16x32_bf16 v[78:81], v[142:145], v[190:193], v[78:81]
	s_waitcnt lgkmcnt(1)
	v_mfma_f32_16x16x32_bf16 v[74:77], v[134:137], v[206:209], v[74:77]
	v_mfma_f32_16x16x32_bf16 v[70:73], v[142:145], v[206:209], v[70:73]
	v_mfma_f32_16x16x32_bf16 v[98:101], v[138:141], v[178:181], v[98:101]
	v_mfma_f32_16x16x32_bf16 v[94:97], v[146:149], v[178:181], v[94:97]
	v_mfma_f32_16x16x32_bf16 v[90:93], v[138:141], v[186:189], v[90:93]
	v_mfma_f32_16x16x32_bf16 v[86:89], v[146:149], v[186:189], v[86:89]
	v_mfma_f32_16x16x32_bf16 v[82:85], v[138:141], v[202:205], v[82:85]
	v_mfma_f32_16x16x32_bf16 v[78:81], v[146:149], v[202:205], v[78:81]
	s_waitcnt lgkmcnt(0)
	v_mfma_f32_16x16x32_bf16 v[74:77], v[138:141], v[210:213], v[74:77]
	v_mfma_f32_16x16x32_bf16 v[70:73], v[146:149], v[210:213], v[70:73]
	s_setprio 0
	s_setprio 1
	v_mfma_f32_16x16x32_bf16 v[34:37], v[158:161], v[174:177], v[34:37]
	v_mfma_f32_16x16x32_bf16 v[30:33], v[166:169], v[174:177], v[30:33]
	v_mfma_f32_16x16x32_bf16 v[26:29], v[158:161], v[182:185], v[26:29]
	v_mfma_f32_16x16x32_bf16 v[22:25], v[166:169], v[182:185], v[22:25]
	v_mfma_f32_16x16x32_bf16 v[18:21], v[158:161], v[190:193], v[18:21]
	v_mfma_f32_16x16x32_bf16 v[14:17], v[166:169], v[190:193], v[14:17]
	v_mfma_f32_16x16x32_bf16 v[8:11], v[158:161], v[206:209], v[10:13]
	v_mfma_f32_16x16x32_bf16 v[4:7], v[166:169], v[206:209], v[4:7]
	v_mfma_f32_16x16x32_bf16 v[34:37], v[162:165], v[178:181], v[34:37]
	v_mfma_f32_16x16x32_bf16 v[30:33], v[170:173], v[178:181], v[30:33]
	v_mfma_f32_16x16x32_bf16 v[26:29], v[162:165], v[186:189], v[26:29]
	v_mov_b32_e32 v248, v170
	v_mov_b32_e32 v249, v171
	v_mfma_f32_16x16x32_bf16 v[22:25], v[170:173], v[186:189], v[22:25]
	v_mov_b32_e32 v250, v172
	v_mov_b32_e32 v251, v173
	v_mfma_f32_16x16x32_bf16 v[18:21], v[162:165], v[202:205], v[18:21]
	v_mov_b32_e32 v252, v210
	v_mov_b32_e32 v253, v211
	v_mfma_f32_16x16x32_bf16 v[14:17], v[170:173], v[202:205], v[14:17]
	v_mov_b32_e32 v254, v212
	v_mov_b32_e32 v255, v213
	v_mfma_f32_16x16x32_bf16 v[10:13], v[162:165], v[210:213], v[8:11]
	s_setprio 2
	s_barrier
	v_mfma_f32_16x16x32_bf16 v[6:9], v[248:251], v[252:255], v[4:7]
	s_setprio 0
	s_add_i32 s92, s92, 2
	s_add_u32 s90, s90, 0x100
	s_addc_u32 s91, s91, 0
	s_cmp_gt_u32 s92, 61
	s_cbranch_scc1 .LBB0_622
	s_mov_b64 s[42:43], s[44:45]
	s_cmp_lg_u32 s92, 30
	s_cbranch_scc0 .LBB0_619
	s_branch .LBB0_620

; #define PG8_STAGE(bufoff, gbase, voff) do { _Pragma("unroll") for (int _i = 0; _i < 2; ++_i) \
;         asm volatile("s_mov_b32 m0, %2\n\ts_nop 0\n\tglobal_load_lds_dwordx4 %0, %1" :: "v"((voff)[_i]), "s"((const char*)(gbase)), "s"(ldsbase + (unsigned)(bufoff) + ldsw + (unsigned)_i * 8192u) : "memory", "m0"); } while (0)
; #define PG8_LDA(dst, b, h) do { _Pragma("unroll") for (int m = 0; m < 4; ++m) _Pragma("unroll") for (int k = 0; k < 2; ++k) dst[m][k] = *(const PG8_LAS bf16x8*)(lds + PG8_SA(b, h) + aoff + m * 2048 + k * 1024); } while (0)
; #define PG8_LDB(dst, b, h) do { _Pragma("unroll") for (int n = 0; n < 2; ++n) _Pragma("unroll") for (int k = 0; k < 2; ++k) dst[n][k] = *(const PG8_LAS bf16x8*)(lds + PG8_SB(b, h) + boff + n * 2048 + k * 1024); } while (0)
; #define PG8_MMA(ai, bj, At, Bt) do { __builtin_amdgcn_s_setprio(1); _Pragma("unroll") for (int m = 0; m < 4; ++m) _Pragma("unroll") for (int n = 0; n < 2; ++n) _Pragma("unroll") for (int k = 0; k < 2; ++k) \
;         acc[ai][bj][m][n] = __builtin_amdgcn_mfma_f32_16x16x32_bf16(Bt[n][k], At[m][k], acc[ai][bj][m][n], 0, 0, 0); __builtin_amdgcn_s_setprio(0); } while (0)
; #define PG8_WAIT_V(n) asm volatile("s_waitcnt vmcnt(" #n ")" ::: "memory")
; #define PG8_WAIT_L(n) asm volatile("s_waitcnt lgkmcnt(" #n ")" ::: "memory")
; #define PG8_BAR __builtin_amdgcn_s_barrier()
; #define PG8_SCHED __builtin_amdgcn_sched_barrier(0)
; template <class Epi, class Sched, bool ALIGN_EPI = false, bool SP2 = false>
; __device__ __forceinline__ void gemm_phase(PG8_LAS unsigned char* lds, const Gemm g, const Sched& S, const Epi& E) {
;     ...
;             PG8_LDB(B0, 0, 0); PG8_LDB(B1, 0, 1); PG8_SCHED; PG8_LDA(At, 0, 0); PG8_STAGE(PG8_SA(1, 1), a1 + hstep, voffA);
;             PG8_WAIT_V(8); PG8_WAIT_L(0); PG8_BAR; PG8_MMA(0, 0, At, B0); PG8_MMA(0, 1, At, B1); PG8_BAR; PG8_SCHED;
;             PG8_LDA(At, 0, 1); PG8_STAGE(PG8_SB(0, 0), b2, voffB); PG8_STAGE(PG8_SB(0, 1), b2 + hstep, voffB); PG8_STAGE(PG8_SA(0, 0), a2, voffA);
.LBB0_698:
	ds_read_b128 v[134:137], v145
	ds_read_b128 v[152:155], v145 offset:1024
	ds_read_b128 v[156:159], v145 offset:2048
	ds_read_b128 v[160:163], v145 offset:3072
	ds_read_b128 v[164:167], v146
	ds_read_b128 v[168:171], v146 offset:1024
	ds_read_b128 v[172:175], v146 offset:2048
	ds_read_b128 v[176:179], v146 offset:3072
	s_cmp_eq_u32 s69, 60
	s_cselect_b32 s48, s41, s53
	s_cselect_b32 s49, s19, s58
	s_cselect_b32 s46, s52, s59
	s_cselect_b32 s47, s17, s68
	s_add_u32 s44, s48, 0x80
	s_addc_u32 s45, s49, 0
	ds_read_b128 v[180:183], v147
	ds_read_b128 v[184:187], v147 offset:1024
	ds_read_b128 v[188:191], v147 offset:2048
	ds_read_b128 v[192:195], v147 offset:3072
	ds_read_b128 v[196:199], v147 offset:4096
	ds_read_b128 v[200:203], v147 offset:5120
	ds_read_b128 v[204:207], v147 offset:6144
	ds_read_b128 v[208:211], v147 offset:7168
	s_mov_b32 m0, s67
	s_nop 0
	global_load_lds_dwordx4 v1, s[42:43]
	s_nop 0
	s_mov_b32 m0, s74
	s_nop 0
	global_load_lds_dwordx4 v141, s[42:43]
	s_waitcnt vmcnt(8)
	s_waitcnt lgkmcnt(0)
	s_barrier
	s_setprio 1
	s_waitcnt lgkmcnt(7)
	v_mfma_f32_16x16x32_bf16 v[126:129], v[134:137], v[180:183], v[126:129]
	v_mfma_f32_16x16x32_bf16 v[122:125], v[156:159], v[180:183], v[122:125]
	s_waitcnt lgkmcnt(5)
	v_mfma_f32_16x16x32_bf16 v[110:113], v[134:137], v[188:191], v[110:113]
	v_mfma_f32_16x16x32_bf16 v[106:109], v[156:159], v[188:191], v[106:109]
	s_waitcnt lgkmcnt(3)
	v_mfma_f32_16x16x32_bf16 v[94:97], v[134:137], v[196:199], v[94:97]
	v_mfma_f32_16x16x32_bf16 v[90:93], v[156:159], v[196:199], v[90:93]
	s_waitcnt lgkmcnt(1)
	v_mfma_f32_16x16x32_bf16 v[78:81], v[134:137], v[204:207], v[78:81]
	v_mfma_f32_16x16x32_bf16 v[74:77], v[156:159], v[204:207], v[74:77]
	v_mfma_f32_16x16x32_bf16 v[126:129], v[152:155], v[184:187], v[126:129]
	v_mfma_f32_16x16x32_bf16 v[122:125], v[160:163], v[184:187], v[122:125]
	v_mfma_f32_16x16x32_bf16 v[110:113], v[152:155], v[192:195], v[110:113]
	v_mfma_f32_16x16x32_bf16 v[106:109], v[160:163], v[192:195], v[106:109]
	v_mfma_f32_16x16x32_bf16 v[94:97], v[152:155], v[200:203], v[94:97]
	v_mfma_f32_16x16x32_bf16 v[90:93], v[160:163], v[200:203], v[90:93]
	s_waitcnt lgkmcnt(0)
	v_mfma_f32_16x16x32_bf16 v[78:81], v[152:155], v[208:211], v[78:81]
	v_mfma_f32_16x16x32_bf16 v[74:77], v[160:163], v[208:211], v[74:77]
	s_setprio 0
	s_setprio 1
	v_mfma_f32_16x16x32_bf16 v[118:121], v[164:167], v[180:183], v[118:121]
	v_mfma_f32_16x16x32_bf16 v[114:117], v[172:175], v[180:183], v[114:117]
	v_mfma_f32_16x16x32_bf16 v[102:105], v[164:167], v[188:191], v[102:105]
	v_mfma_f32_16x16x32_bf16 v[98:101], v[172:175], v[188:191], v[98:101]
	v_mfma_f32_16x16x32_bf16 v[86:89], v[164:167], v[196:199], v[86:89]
	v_mfma_f32_16x16x32_bf16 v[82:85], v[172:175], v[196:199], v[82:85]
	v_mfma_f32_16x16x32_bf16 v[70:73], v[164:167], v[204:207], v[70:73]
	v_mfma_f32_16x16x32_bf16 v[66:69], v[172:175], v[204:207], v[66:69]
	v_mfma_f32_16x16x32_bf16 v[118:121], v[168:171], v[184:187], v[118:121]
	v_mfma_f32_16x16x32_bf16 v[114:117], v[176:179], v[184:187], v[114:117]
	v_mfma_f32_16x16x32_bf16 v[102:105], v[168:171], v[192:195], v[102:105]
	v_mov_b32_e32 v248, v176
	v_mov_b32_e32 v249, v177
	v_mfma_f32_16x16x32_bf16 v[98:101], v[176:179], v[192:195], v[98:101]
	v_mov_b32_e32 v250, v178
	v_mov_b32_e32 v251, v179
	v_mfma_f32_16x16x32_bf16 v[86:89], v[168:171], v[200:203], v[86:89]
	v_mov_b32_e32 v252, v208
	v_mov_b32_e32 v253, v209
	v_mfma_f32_16x16x32_bf16 v[82:85], v[176:179], v[200:203], v[82:85]
	v_mov_b32_e32 v254, v210
	v_mov_b32_e32 v255, v211
	v_mfma_f32_16x16x32_bf16 v[70:73], v[168:171], v[208:211], v[70:73]
	s_setprio 2
	s_barrier
	v_mfma_f32_16x16x32_bf16 v[66:69], v[248:251], v[252:255], v[66:69]
	s_setprio 0
	ds_read_b128 v[180:183], v147 offset:16384
	ds_read_b128 v[184:187], v147 offset:17408
	ds_read_b128 v[188:191], v147 offset:18432
	ds_read_b128 v[192:195], v147 offset:19456
	ds_read_b128 v[196:199], v147 offset:20480
	ds_read_b128 v[200:203], v147 offset:21504
	ds_read_b128 v[204:207], v147 offset:22528
	ds_read_b128 v[208:211], v147 offset:23552
	s_mov_b32 m0, s35
	s_nop 0
	global_load_lds_dwordx4 v140, s[46:47]
	s_add_u32 s70, s46, 0x100000
	s_mov_b32 m0, s50
	s_nop 0
	global_load_lds_dwordx4 v142, s[46:47]
	s_addc_u32 s71, s47, 0
	s_mov_b32 m0, s51
	s_nop 0
	global_load_lds_dwordx4 v140, s[70:71]
	s_nop 0
	s_mov_b32 m0, s54
	s_nop 0
	global_load_lds_dwordx4 v142, s[70:71]
	s_nop 0
	s_mov_b32 m0, s3
	s_nop 0
	global_load_lds_dwordx4 v1, s[48:49]
	s_nop 0
	s_mov_b32 m0, s55
	s_nop 0
	global_load_lds_dwordx4 v141, s[48:49]
	s_waitcnt vmcnt(8)
	s_waitcnt lgkmcnt(0)
	s_barrier
; #define PG8_STAGE(bufoff, gbase, voff) do { _Pragma("unroll") for (int _i = 0; _i < 2; ++_i) \
;         asm volatile("s_mov_b32 m0, %2\n\ts_nop 0\n\tglobal_load_lds_dwordx4 %0, %1" :: "v"((voff)[_i]), "s"((const char*)(gbase)), "s"(ldsbase + (unsigned)(bufoff) + ldsw + (unsigned)_i * 8192u) : "memory", "m0"); } while (0)
; #define PG8_LDA(dst, b, h) do { _Pragma("unroll") for (int m = 0; m < 4; ++m) _Pragma("unroll") for (int k = 0; k < 2; ++k) dst[m][k] = *(const PG8_LAS bf16x8*)(lds + PG8_SA(b, h) + aoff + m * 2048 + k * 1024); } while (0)
; #define PG8_LDB(dst, b, h) do { _Pragma("unroll") for (int n = 0; n < 2; ++n) _Pragma("unroll") for (int k = 0; k < 2; ++k) dst[n][k] = *(const PG8_LAS bf16x8*)(lds + PG8_SB(b, h) + boff + n * 2048 + k * 1024); } while (0)
; #define PG8_MMA(ai, bj, At, Bt) do { __builtin_amdgcn_s_setprio(1); _Pragma("unroll") for (int m = 0; m < 4; ++m) _Pragma("unroll") for (int n = 0; n < 2; ++n) _Pragma("unroll") for (int k = 0; k < 2; ++k) \
;         acc[ai][bj][m][n] = __builtin_amdgcn_mfma_f32_16x16x32_bf16(Bt[n][k], At[m][k], acc[ai][bj][m][n], 0, 0, 0); __builtin_amdgcn_s_setprio(0); } while (0)
; #define PG8_WAIT_V(n) asm volatile("s_waitcnt vmcnt(" #n ")" ::: "memory")
; #define PG8_WAIT_L(n) asm volatile("s_waitcnt lgkmcnt(" #n ")" ::: "memory")
; #define PG8_BAR __builtin_amdgcn_s_barrier()
; #define PG8_SCHED __builtin_amdgcn_sched_barrier(0)
; template <class Epi, class Sched, bool ALIGN_EPI = false, bool SP2 = false>
; __device__ __forceinline__ void gemm_phase(PG8_LAS unsigned char* lds, const Gemm g, const Sched& S, const Epi& E) {
;     ...
;             PG8_WAIT_V(8); PG8_WAIT_L(0); PG8_BAR; PG8_MMA(0, 0, At, B0); PG8_MMA(0, 1, At, B1); PG8_BAR; PG8_SCHED;
;             PG8_LDA(At, 0, 1); PG8_STAGE(PG8_SB(0, 0), b2, voffB); PG8_STAGE(PG8_SB(0, 1), b2 + hstep, voffB); PG8_STAGE(PG8_SA(0, 0), a2, voffA);
;             PG8_WAIT_V(8); PG8_WAIT_L(0); PG8_BAR; PG8_MMA(1, 0, At, B0); PG8_MMA(1, 1, At, B1); PG8_BAR; PG8_SCHED;
;             PG8_LDB(B0, 1, 0); PG8_LDB(B1, 1, 1); PG8_SCHED; PG8_LDA(At, 1, 0); PG8_STAGE(PG8_SA(0, 1), a2 + hstep, voffA);
;             PG8_WAIT_V(8); PG8_WAIT_L(0); PG8_BAR; PG8_MMA(0, 0, At, B0); PG8_MMA(0, 1, At, B1); PG8_BAR; PG8_SCHED;
;             PG8_LDA(At, 1, 1); PG8_STAGE(PG8_SB(1, 0), b3, voffB); PG8_STAGE(PG8_SB(1, 1), b3 + hstep, voffB); PG8_STAGE(PG8_SA(1, 0), a3, voffA);
	s_setprio 1
	s_waitcnt lgkmcnt(7)
	v_mfma_f32_16x16x32_bf16 v[62:65], v[134:137], v[180:183], v[62:65]
	v_mfma_f32_16x16x32_bf16 v[58:61], v[156:159], v[180:183], v[58:61]
	s_waitcnt lgkmcnt(5)
	v_mfma_f32_16x16x32_bf16 v[46:49], v[134:137], v[188:191], v[46:49]
	v_mfma_f32_16x16x32_bf16 v[42:45], v[156:159], v[188:191], v[42:45]
	s_waitcnt lgkmcnt(3)
	v_mfma_f32_16x16x32_bf16 v[30:33], v[134:137], v[196:199], v[30:33]
	v_mfma_f32_16x16x32_bf16 v[26:29], v[156:159], v[196:199], v[26:29]
	s_waitcnt lgkmcnt(1)
	v_mfma_f32_16x16x32_bf16 v[14:17], v[134:137], v[204:207], v[14:17]
	v_mfma_f32_16x16x32_bf16 v[10:13], v[156:159], v[204:207], v[10:13]
	v_mfma_f32_16x16x32_bf16 v[62:65], v[152:155], v[184:187], v[62:65]
	v_mfma_f32_16x16x32_bf16 v[58:61], v[160:163], v[184:187], v[58:61]
	v_mfma_f32_16x16x32_bf16 v[46:49], v[152:155], v[192:195], v[46:49]
	v_mfma_f32_16x16x32_bf16 v[42:45], v[160:163], v[192:195], v[42:45]
	v_mfma_f32_16x16x32_bf16 v[30:33], v[152:155], v[200:203], v[30:33]
	v_mfma_f32_16x16x32_bf16 v[26:29], v[160:163], v[200:203], v[26:29]
	s_waitcnt lgkmcnt(0)
	v_mfma_f32_16x16x32_bf16 v[14:17], v[152:155], v[208:211], v[14:17]
	v_mfma_f32_16x16x32_bf16 v[10:13], v[160:163], v[208:211], v[10:13]
	s_setprio 0
	s_setprio 1
	v_mfma_f32_16x16x32_bf16 v[54:57], v[164:167], v[180:183], v[54:57]
	v_mfma_f32_16x16x32_bf16 v[50:53], v[172:175], v[180:183], v[50:53]
	v_mfma_f32_16x16x32_bf16 v[38:41], v[164:167], v[188:191], v[38:41]
	v_mfma_f32_16x16x32_bf16 v[34:37], v[172:175], v[188:191], v[34:37]
	v_mfma_f32_16x16x32_bf16 v[22:25], v[164:167], v[196:199], v[22:25]
	v_mfma_f32_16x16x32_bf16 v[18:21], v[172:175], v[196:199], v[18:21]
	v_mfma_f32_16x16x32_bf16 v[6:9], v[164:167], v[204:207], v[6:9]
	v_mfma_f32_16x16x32_bf16 v[2:5], v[172:175], v[204:207], v[2:5]
	v_mfma_f32_16x16x32_bf16 v[54:57], v[168:171], v[184:187], v[54:57]
	v_mfma_f32_16x16x32_bf16 v[50:53], v[176:179], v[184:187], v[50:53]
	v_mfma_f32_16x16x32_bf16 v[38:41], v[168:171], v[192:195], v[38:41]
	v_mov_b32_e32 v248, v176
	v_mov_b32_e32 v249, v177
	v_mfma_f32_16x16x32_bf16 v[34:37], v[176:179], v[192:195], v[34:37]
	v_mov_b32_e32 v250, v178
	v_mov_b32_e32 v251, v179
	v_mfma_f32_16x16x32_bf16 v[22:25], v[168:171], v[200:203], v[22:25]
	v_mov_b32_e32 v252, v208
	v_mov_b32_e32 v253, v209
	v_mfma_f32_16x16x32_bf16 v[18:21], v[176:179], v[200:203], v[18:21]
	v_mov_b32_e32 v254, v210
	v_mov_b32_e32 v255, v211
	v_mfma_f32_16x16x32_bf16 v[6:9], v[168:171], v[208:211], v[6:9]
	s_setprio 2
	s_barrier
	v_mfma_f32_16x16x32_bf16 v[2:5], v[248:251], v[252:255], v[2:5]
	s_setprio 0
	ds_read_b128 v[134:137], v148
	ds_read_b128 v[152:155], v148 offset:1024
	ds_read_b128 v[156:159], v148 offset:2048
	ds_read_b128 v[160:163], v148 offset:3072
	ds_read_b128 v[164:167], v149
	ds_read_b128 v[168:171], v149 offset:1024
	ds_read_b128 v[172:175], v149 offset:2048
	ds_read_b128 v[176:179], v149 offset:3072
	ds_read_b128 v[180:183], v147 offset:32768
	ds_read_b128 v[184:187], v147 offset:33792
	ds_read_b128 v[188:191], v147 offset:34816
	ds_read_b128 v[192:195], v147 offset:35840
	ds_read_b128 v[196:199], v147 offset:36864
	ds_read_b128 v[200:203], v147 offset:37888
	ds_read_b128 v[204:207], v147 offset:38912
	ds_read_b128 v[208:211], v147 offset:39936
	s_add_u32 s48, s48, 0x100000
	s_addc_u32 s49, s49, 0
	s_mov_b32 m0, s56
	s_nop 0
	global_load_lds_dwordx4 v1, s[48:49]
	s_nop 0
	s_mov_b32 m0, s57
	s_nop 0
	global_load_lds_dwordx4 v141, s[48:49]
	s_waitcnt vmcnt(8)
	s_waitcnt lgkmcnt(0)
	s_barrier
	s_setprio 1
	s_waitcnt lgkmcnt(7)
	v_mfma_f32_16x16x32_bf16 v[126:129], v[134:137], v[180:183], v[126:129]
	v_mfma_f32_16x16x32_bf16 v[122:125], v[156:159], v[180:183], v[122:125]
	s_waitcnt lgkmcnt(5)
	v_mfma_f32_16x16x32_bf16 v[110:113], v[134:137], v[188:191], v[110:113]
	v_mfma_f32_16x16x32_bf16 v[106:109], v[156:159], v[188:191], v[106:109]
	s_waitcnt lgkmcnt(3)
	v_mfma_f32_16x16x32_bf16 v[94:97], v[134:137], v[196:199], v[94:97]
	v_mfma_f32_16x16x32_bf16 v[90:93], v[156:159], v[196:199], v[90:93]
	s_waitcnt lgkmcnt(1)
	v_mfma_f32_16x16x32_bf16 v[78:81], v[134:137], v[204:207], v[78:81]
	v_mfma_f32_16x16x32_bf16 v[74:77], v[156:159], v[204:207], v[74:77]
	v_mfma_f32_16x16x32_bf16 v[126:129], v[152:155], v[184:187], v[126:129]
	v_mfma_f32_16x16x32_bf16 v[122:125], v[160:163], v[184:187], v[122:125]
	v_mfma_f32_16x16x32_bf16 v[110:113], v[152:155], v[192:195], v[110:113]
	v_mfma_f32_16x16x32_bf16 v[106:109], v[160:163], v[192:195], v[106:109]
	v_mfma_f32_16x16x32_bf16 v[94:97], v[152:155], v[200:203], v[94:97]
	v_mfma_f32_16x16x32_bf16 v[90:93], v[160:163], v[200:203], v[90:93]
	s_waitcnt lgkmcnt(0)
	v_mfma_f32_16x16x32_bf16 v[78:81], v[152:155], v[208:211], v[78:81]
	v_mfma_f32_16x16x32_bf16 v[74:77], v[160:163], v[208:211], v[74:77]
	s_setprio 0
	s_setprio 1
	v_mfma_f32_16x16x32_bf16 v[118:121], v[164:167], v[180:183], v[118:121]
	v_mfma_f32_16x16x32_bf16 v[114:117], v[172:175], v[180:183], v[114:117]
	v_mfma_f32_16x16x32_bf16 v[102:105], v[164:167], v[188:191], v[102:105]
	v_mfma_f32_16x16x32_bf16 v[98:101], v[172:175], v[188:191], v[98:101]
	v_mfma_f32_16x16x32_bf16 v[86:89], v[164:167], v[196:199], v[86:89]
	v_mfma_f32_16x16x32_bf16 v[82:85], v[172:175], v[196:199], v[82:85]
	v_mfma_f32_16x16x32_bf16 v[70:73], v[164:167], v[204:207], v[70:73]
	v_mfma_f32_16x16x32_bf16 v[66:69], v[172:175], v[204:207], v[66:69]
	v_mfma_f32_16x16x32_bf16 v[118:121], v[168:171], v[184:187], v[118:121]
	v_mfma_f32_16x16x32_bf16 v[114:117], v[176:179], v[184:187], v[114:117]
	v_mfma_f32_16x16x32_bf16 v[102:105], v[168:171], v[192:195], v[102:105]
	v_mov_b32_e32 v248, v176
	v_mov_b32_e32 v249, v177
	v_mfma_f32_16x16x32_bf16 v[98:101], v[176:179], v[192:195], v[98:101]
	v_mov_b32_e32 v250, v178
	v_mov_b32_e32 v251, v179
	v_mfma_f32_16x16x32_bf16 v[86:89], v[168:171], v[200:203], v[86:89]
	v_mov_b32_e32 v252, v208
	v_mov_b32_e32 v253, v209
	v_mfma_f32_16x16x32_bf16 v[82:85], v[176:179], v[200:203], v[82:85]
	v_mov_b32_e32 v254, v210
	v_mov_b32_e32 v255, v211
	v_mfma_f32_16x16x32_bf16 v[70:73], v[168:171], v[208:211], v[70:73]
	s_setprio 2
	s_barrier
; #define PG8_STAGE(bufoff, gbase, voff) do { _Pragma("unroll") for (int _i = 0; _i < 2; ++_i) \
;         asm volatile("s_mov_b32 m0, %2\n\ts_nop 0\n\tglobal_load_lds_dwordx4 %0, %1" :: "v"((voff)[_i]), "s"((const char*)(gbase)), "s"(ldsbase + (unsigned)(bufoff) + ldsw + (unsigned)_i * 8192u) : "memory", "m0"); } while (0)
; #define PG8_LDA(dst, b, h) do { _Pragma("unroll") for (int m = 0; m < 4; ++m) _Pragma("unroll") for (int k = 0; k < 2; ++k) dst[m][k] = *(const PG8_LAS bf16x8*)(lds + PG8_SA(b, h) + aoff + m * 2048 + k * 1024); } while (0)
; #define PG8_MMA(ai, bj, At, Bt) do { __builtin_amdgcn_s_setprio(1); _Pragma("unroll") for (int m = 0; m < 4; ++m) _Pragma("unroll") for (int n = 0; n < 2; ++n) _Pragma("unroll") for (int k = 0; k < 2; ++k) \
;         acc[ai][bj][m][n] = __builtin_amdgcn_mfma_f32_16x16x32_bf16(Bt[n][k], At[m][k], acc[ai][bj][m][n], 0, 0, 0); __builtin_amdgcn_s_setprio(0); } while (0)
; #define PG8_WAIT_V(n) asm volatile("s_waitcnt vmcnt(" #n ")" ::: "memory")
; #define PG8_WAIT_L(n) asm volatile("s_waitcnt lgkmcnt(" #n ")" ::: "memory")
; #define PG8_BAR __builtin_amdgcn_s_barrier()
; #define PG8_SCHED __builtin_amdgcn_sched_barrier(0)
; template <class Epi, class Sched, bool ALIGN_EPI = false, bool SP2 = false>
; __device__ __forceinline__ void gemm_phase(PG8_LAS unsigned char* lds, const Gemm g, const Sched& S, const Epi& E) {
;     ...
;             PG8_WAIT_V(8); PG8_WAIT_L(0); PG8_BAR; PG8_MMA(0, 0, At, B0); PG8_MMA(0, 1, At, B1); PG8_BAR; PG8_SCHED;
;             PG8_LDA(At, 1, 1); PG8_STAGE(PG8_SB(1, 0), b3, voffB); PG8_STAGE(PG8_SB(1, 1), b3 + hstep, voffB); PG8_STAGE(PG8_SA(1, 0), a3, voffA);
;             PG8_WAIT_V(8); PG8_WAIT_L(0); PG8_BAR; PG8_MMA(1, 0, At, B0); PG8_MMA(1, 1, At, B1); PG8_BAR; PG8_SCHED;
	v_mfma_f32_16x16x32_bf16 v[66:69], v[248:251], v[252:255], v[66:69]
	s_setprio 0
	ds_read_b128 v[180:183], v147 offset:49152
	ds_read_b128 v[184:187], v147 offset:50176
	ds_read_b128 v[188:191], v147 offset:51200
	ds_read_b128 v[192:195], v147 offset:52224
	ds_read_b128 v[196:199], v147 offset:53248
	ds_read_b128 v[200:203], v147 offset:54272
	ds_read_b128 v[204:207], v147 offset:55296
	ds_read_b128 v[208:211], v147 offset:56320
	s_add_u32 s48, s46, 0x80
	s_addc_u32 s49, s47, 0
	s_mov_b32 m0, s61
	s_nop 0
	global_load_lds_dwordx4 v140, s[48:49]
	s_add_u32 s46, s46, 0x100080
	s_mov_b32 m0, s62
	s_nop 0
	global_load_lds_dwordx4 v142, s[48:49]
	s_addc_u32 s47, s47, 0
	s_mov_b32 m0, s65
	s_nop 0
	global_load_lds_dwordx4 v140, s[46:47]
	s_nop 0
	s_mov_b32 m0, s66
	s_nop 0
	global_load_lds_dwordx4 v142, s[46:47]
	s_nop 0
	s_mov_b32 m0, s63
	s_nop 0
	global_load_lds_dwordx4 v1, s[44:45]
	s_nop 0
	s_mov_b32 m0, s64
	s_nop 0
	global_load_lds_dwordx4 v141, s[44:45]
	s_waitcnt vmcnt(8)
	s_waitcnt lgkmcnt(0)
	s_barrier
	s_setprio 1
	s_waitcnt lgkmcnt(7)
	v_mfma_f32_16x16x32_bf16 v[62:65], v[134:137], v[180:183], v[62:65]
	v_mfma_f32_16x16x32_bf16 v[58:61], v[156:159], v[180:183], v[58:61]
	s_waitcnt lgkmcnt(5)
	v_mfma_f32_16x16x32_bf16 v[46:49], v[134:137], v[188:191], v[46:49]
	v_mfma_f32_16x16x32_bf16 v[42:45], v[156:159], v[188:191], v[42:45]
	s_waitcnt lgkmcnt(3)
	v_mfma_f32_16x16x32_bf16 v[30:33], v[134:137], v[196:199], v[30:33]
	v_mfma_f32_16x16x32_bf16 v[26:29], v[156:159], v[196:199], v[26:29]
	s_waitcnt lgkmcnt(1)
	v_mfma_f32_16x16x32_bf16 v[14:17], v[134:137], v[204:207], v[14:17]
	v_mfma_f32_16x16x32_bf16 v[10:13], v[156:159], v[204:207], v[10:13]
	v_mfma_f32_16x16x32_bf16 v[62:65], v[152:155], v[184:187], v[62:65]
	v_mfma_f32_16x16x32_bf16 v[58:61], v[160:163], v[184:187], v[58:61]
	v_mfma_f32_16x16x32_bf16 v[46:49], v[152:155], v[192:195], v[46:49]
	v_mfma_f32_16x16x32_bf16 v[42:45], v[160:163], v[192:195], v[42:45]
	v_mfma_f32_16x16x32_bf16 v[30:33], v[152:155], v[200:203], v[30:33]
	v_mfma_f32_16x16x32_bf16 v[26:29], v[160:163], v[200:203], v[26:29]
	s_waitcnt lgkmcnt(0)
	v_mfma_f32_16x16x32_bf16 v[14:17], v[152:155], v[208:211], v[14:17]
	v_mfma_f32_16x16x32_bf16 v[10:13], v[160:163], v[208:211], v[10:13]
	s_setprio 0
	s_setprio 1
	v_mfma_f32_16x16x32_bf16 v[54:57], v[164:167], v[180:183], v[54:57]
	v_mfma_f32_16x16x32_bf16 v[50:53], v[172:175], v[180:183], v[50:53]
	v_mfma_f32_16x16x32_bf16 v[38:41], v[164:167], v[188:191], v[38:41]
	v_mfma_f32_16x16x32_bf16 v[34:37], v[172:175], v[188:191], v[34:37]
	v_mfma_f32_16x16x32_bf16 v[22:25], v[164:167], v[196:199], v[22:25]
	v_mfma_f32_16x16x32_bf16 v[18:21], v[172:175], v[196:199], v[18:21]
	v_mfma_f32_16x16x32_bf16 v[6:9], v[164:167], v[204:207], v[6:9]
	v_mfma_f32_16x16x32_bf16 v[2:5], v[172:175], v[204:207], v[2:5]
	v_mfma_f32_16x16x32_bf16 v[54:57], v[168:171], v[184:187], v[54:57]
	v_mfma_f32_16x16x32_bf16 v[50:53], v[176:179], v[184:187], v[50:53]
	v_mfma_f32_16x16x32_bf16 v[38:41], v[168:171], v[192:195], v[38:41]
	v_mov_b32_e32 v248, v176
	v_mov_b32_e32 v249, v177
	v_mfma_f32_16x16x32_bf16 v[34:37], v[176:179], v[192:195], v[34:37]
	v_mov_b32_e32 v250, v178
	v_mov_b32_e32 v251, v179
	v_mfma_f32_16x16x32_bf16 v[22:25], v[168:171], v[200:203], v[22:25]
	v_mov_b32_e32 v252, v208
	v_mov_b32_e32 v253, v209
	v_mfma_f32_16x16x32_bf16 v[18:21], v[176:179], v[200:203], v[18:21]
	v_mov_b32_e32 v254, v210
	v_mov_b32_e32 v255, v211
	v_mfma_f32_16x16x32_bf16 v[6:9], v[168:171], v[208:211], v[6:9]
	s_setprio 2
	s_barrier
	v_mfma_f32_16x16x32_bf16 v[2:5], v[248:251], v[252:255], v[2:5]
	s_setprio 0
	s_add_i32 s69, s69, 2
	s_add_u32 s53, s53, 0x100
	s_addc_u32 s58, s58, 0
	s_add_u32 s59, s59, 0x100
	s_addc_u32 s68, s68, 0
	s_add_u32 s42, s42, 0x100
	s_addc_u32 s43, s43, 0
	s_cmp_gt_u32 s69, 61
	s_cbranch_scc0 .LBB0_698
	s_and_b64 vcc, exec, s[14:15]
	s_cbranch_vccz .LBB0_701
	s_barrier

; #define PG8_STAGE(bufoff, gbase, voff) do { _Pragma("unroll") for (int _i = 0; _i < 2; ++_i) \
;         asm volatile("s_mov_b32 m0, %2\n\ts_nop 0\n\tglobal_load_lds_dwordx4 %0, %1" :: "v"((voff)[_i]), "s"((const char*)(gbase)), "s"(ldsbase + (unsigned)(bufoff) + ldsw + (unsigned)_i * 8192u) : "memory", "m0"); } while (0)
; #define PG8_LDA(dst, b, h) do { _Pragma("unroll") for (int m = 0; m < 4; ++m) _Pragma("unroll") for (int k = 0; k < 2; ++k) dst[m][k] = *(const PG8_LAS bf16x8*)(lds + PG8_SA(b, h) + aoff + m * 2048 + k * 1024); } while (0)
; #define PG8_LDB(dst, b, h) do { _Pragma("unroll") for (int n = 0; n < 2; ++n) _Pragma("unroll") for (int k = 0; k < 2; ++k) dst[n][k] = *(const PG8_LAS bf16x8*)(lds + PG8_SB(b, h) + boff + n * 2048 + k * 1024); } while (0)
; #define PG8_MMA(ai, bj, At, Bt) do { __builtin_amdgcn_s_setprio(1); _Pragma("unroll") for (int m = 0; m < 4; ++m) _Pragma("unroll") for (int n = 0; n < 2; ++n) _Pragma("unroll") for (int k = 0; k < 2; ++k) \
;         acc[ai][bj][m][n] = __builtin_amdgcn_mfma_f32_16x16x32_bf16(Bt[n][k], At[m][k], acc[ai][bj][m][n], 0, 0, 0); __builtin_amdgcn_s_setprio(0); } while (0)
; #define PG8_WAIT_V(n) asm volatile("s_waitcnt vmcnt(" #n ")" ::: "memory")
; #define PG8_WAIT_L(n) asm volatile("s_waitcnt lgkmcnt(" #n ")" ::: "memory")
; #define PG8_BAR __builtin_amdgcn_s_barrier()
; #define PG8_SCHED __builtin_amdgcn_sched_barrier(0)
; template <class Epi, class Sched, bool ALIGN_EPI = false, bool SP2 = false>
; __device__ __forceinline__ void gemm_phase(PG8_LAS unsigned char* lds, const Gemm g, const Sched& S, const Epi& E) {
;     ...
;             PG8_LDB(B0, 0, 0); PG8_LDB(B1, 0, 1); PG8_SCHED; PG8_LDA(At, 0, 0); PG8_STAGE(PG8_SA(1, 1), a1 + hstep, voffA);
;             PG8_WAIT_V(8); PG8_WAIT_L(0); PG8_BAR; PG8_MMA(0, 0, At, B0); PG8_MMA(0, 1, At, B1); PG8_BAR; PG8_SCHED;
;             PG8_LDA(At, 0, 1); PG8_STAGE(PG8_SB(0, 0), b2, voffB); PG8_STAGE(PG8_SB(0, 1), b2 + hstep, voffB); PG8_STAGE(PG8_SA(0, 0), a2, voffA);
.LBB0_789:
	v_add_u32_e32 v164, 0x10000, v149
	v_add_u32_e32 v180, 0x14000, v149
	s_add_u32 s8, s40, 0x100
	s_waitcnt lgkmcnt(0)
	ds_read_b128 v[152:155], v164
	ds_read_b128 v[156:159], v164 offset:1024
	ds_read_b128 v[160:163], v164 offset:2048
	ds_read_b128 v[164:167], v164 offset:3072
	ds_read_b128 v[168:171], v180
	ds_read_b128 v[172:175], v180 offset:1024
	ds_read_b128 v[176:179], v180 offset:2048
	ds_read_b128 v[180:183], v180 offset:3072
	s_addc_u32 s9, s41, 0
	s_and_b64 s[38:39], s[38:39], exec
	s_cselect_b32 s46, s59, s8
	s_cselect_b32 s47, s17, s9
	s_cselect_b32 s39, s15, s75
	s_cselect_b32 s38, s71, s74
	s_add_u32 s42, s46, 0x80
	s_addc_u32 s43, s47, 0
	s_add_u32 s44, s38, 0x80
	s_addc_u32 s45, s39, 0
	ds_read_b128 v[184:187], v150
	ds_read_b128 v[188:191], v150 offset:1024
	ds_read_b128 v[192:195], v150 offset:2048
	ds_read_b128 v[196:199], v150 offset:3072
	ds_read_b128 v[200:203], v150 offset:4096
	ds_read_b128 v[204:207], v150 offset:5120
	ds_read_b128 v[208:211], v150 offset:6144
	ds_read_b128 v[212:215], v150 offset:7168
	s_add_u32 s40, s40, 0x100080
	s_addc_u32 s41, s41, 0
	s_mov_b32 m0, s64
	s_nop 0
	global_load_lds_dwordx4 v139, s[40:41]
	s_nop 0
	s_mov_b32 m0, s65
	s_nop 0
	global_load_lds_dwordx4 v141, s[40:41]
	s_waitcnt vmcnt(8)
	s_waitcnt lgkmcnt(0)
	s_barrier
	s_setprio 1
	s_waitcnt lgkmcnt(7)
	v_mfma_f32_16x16x32_bf16 v[126:129], v[152:155], v[184:187], v[126:129]
	v_mfma_f32_16x16x32_bf16 v[122:125], v[160:163], v[184:187], v[122:125]
	s_waitcnt lgkmcnt(5)
	v_mfma_f32_16x16x32_bf16 v[110:113], v[152:155], v[192:195], v[110:113]
	v_mfma_f32_16x16x32_bf16 v[106:109], v[160:163], v[192:195], v[106:109]
	s_waitcnt lgkmcnt(3)
	v_mfma_f32_16x16x32_bf16 v[94:97], v[152:155], v[200:203], v[94:97]
	v_mfma_f32_16x16x32_bf16 v[90:93], v[160:163], v[200:203], v[90:93]
	s_waitcnt lgkmcnt(1)
	v_mfma_f32_16x16x32_bf16 v[78:81], v[152:155], v[208:211], v[78:81]
	v_mfma_f32_16x16x32_bf16 v[74:77], v[160:163], v[208:211], v[74:77]
	v_mfma_f32_16x16x32_bf16 v[126:129], v[156:159], v[188:191], v[126:129]
	v_mfma_f32_16x16x32_bf16 v[122:125], v[164:167], v[188:191], v[122:125]
	v_mfma_f32_16x16x32_bf16 v[110:113], v[156:159], v[196:199], v[110:113]
	v_mfma_f32_16x16x32_bf16 v[106:109], v[164:167], v[196:199], v[106:109]
	v_mfma_f32_16x16x32_bf16 v[94:97], v[156:159], v[204:207], v[94:97]
	v_mfma_f32_16x16x32_bf16 v[90:93], v[164:167], v[204:207], v[90:93]
	s_waitcnt lgkmcnt(0)
	v_mfma_f32_16x16x32_bf16 v[78:81], v[156:159], v[212:215], v[78:81]
	v_mfma_f32_16x16x32_bf16 v[74:77], v[164:167], v[212:215], v[74:77]
	s_setprio 0
	s_setprio 1
	v_mfma_f32_16x16x32_bf16 v[118:121], v[168:171], v[184:187], v[118:121]
	v_mfma_f32_16x16x32_bf16 v[114:117], v[176:179], v[184:187], v[114:117]
	v_mfma_f32_16x16x32_bf16 v[102:105], v[168:171], v[192:195], v[102:105]
	v_mfma_f32_16x16x32_bf16 v[98:101], v[176:179], v[192:195], v[98:101]
	v_mfma_f32_16x16x32_bf16 v[86:89], v[168:171], v[200:203], v[86:89]
	v_mfma_f32_16x16x32_bf16 v[82:85], v[176:179], v[200:203], v[82:85]
	v_mfma_f32_16x16x32_bf16 v[70:73], v[168:171], v[208:211], v[70:73]
	v_mfma_f32_16x16x32_bf16 v[66:69], v[176:179], v[208:211], v[66:69]
	v_mfma_f32_16x16x32_bf16 v[118:121], v[172:175], v[188:191], v[118:121]
	v_mfma_f32_16x16x32_bf16 v[114:117], v[180:183], v[188:191], v[114:117]
	v_mfma_f32_16x16x32_bf16 v[102:105], v[172:175], v[196:199], v[102:105]
	v_mov_b32_e32 v248, v180
	v_mov_b32_e32 v249, v181
	v_mfma_f32_16x16x32_bf16 v[98:101], v[180:183], v[196:199], v[98:101]
	v_mov_b32_e32 v250, v182
	v_mov_b32_e32 v251, v183
	v_mfma_f32_16x16x32_bf16 v[86:89], v[172:175], v[204:207], v[86:89]
	v_mov_b32_e32 v252, v212
	v_mov_b32_e32 v253, v213
	v_mfma_f32_16x16x32_bf16 v[82:85], v[180:183], v[204:207], v[82:85]
	v_mov_b32_e32 v254, v214
	v_mov_b32_e32 v255, v215
	v_mfma_f32_16x16x32_bf16 v[70:73], v[172:175], v[212:215], v[70:73]
	s_setprio 2
	s_barrier
	v_mfma_f32_16x16x32_bf16 v[66:69], v[248:251], v[252:255], v[66:69]
	s_setprio 0
	ds_read_b128 v[184:187], v150 offset:16384
	ds_read_b128 v[188:191], v150 offset:17408
	ds_read_b128 v[192:195], v150 offset:18432
	ds_read_b128 v[196:199], v150 offset:19456
	ds_read_b128 v[200:203], v150 offset:20480
	ds_read_b128 v[204:207], v150 offset:21504
	ds_read_b128 v[208:211], v150 offset:22528
	ds_read_b128 v[212:215], v150 offset:23552
	s_mov_b32 m0, s49
	s_nop 0
	global_load_lds_dwordx4 v140, s[38:39]
	s_add_u32 s40, s38, 0x100000
	s_mov_b32 m0, s50
	s_nop 0
	global_load_lds_dwordx4 v142, s[38:39]
	s_addc_u32 s41, s39, 0
	s_mov_b32 m0, s51
	s_nop 0
	global_load_lds_dwordx4 v140, s[40:41]
	s_nop 0
	s_mov_b32 m0, s52
	s_nop 0
	global_load_lds_dwordx4 v142, s[40:41]
	s_nop 0
	s_mov_b32 m0, s37
	s_nop 0
	global_load_lds_dwordx4 v139, s[46:47]
	s_nop 0
	s_mov_b32 m0, s53
	s_nop 0
	global_load_lds_dwordx4 v141, s[46:47]
	s_waitcnt vmcnt(8)
	s_waitcnt lgkmcnt(0)
	s_barrier
; #define PG8_STAGE(bufoff, gbase, voff) do { _Pragma("unroll") for (int _i = 0; _i < 2; ++_i) \
;         asm volatile("s_mov_b32 m0, %2\n\ts_nop 0\n\tglobal_load_lds_dwordx4 %0, %1" :: "v"((voff)[_i]), "s"((const char*)(gbase)), "s"(ldsbase + (unsigned)(bufoff) + ldsw + (unsigned)_i * 8192u) : "memory", "m0"); } while (0)
; #define PG8_LDA(dst, b, h) do { _Pragma("unroll") for (int m = 0; m < 4; ++m) _Pragma("unroll") for (int k = 0; k < 2; ++k) dst[m][k] = *(const PG8_LAS bf16x8*)(lds + PG8_SA(b, h) + aoff + m * 2048 + k * 1024); } while (0)
; #define PG8_LDB(dst, b, h) do { _Pragma("unroll") for (int n = 0; n < 2; ++n) _Pragma("unroll") for (int k = 0; k < 2; ++k) dst[n][k] = *(const PG8_LAS bf16x8*)(lds + PG8_SB(b, h) + boff + n * 2048 + k * 1024); } while (0)
; #define PG8_MMA(ai, bj, At, Bt) do { __builtin_amdgcn_s_setprio(1); _Pragma("unroll") for (int m = 0; m < 4; ++m) _Pragma("unroll") for (int n = 0; n < 2; ++n) _Pragma("unroll") for (int k = 0; k < 2; ++k) \
;         acc[ai][bj][m][n] = __builtin_amdgcn_mfma_f32_16x16x32_bf16(Bt[n][k], At[m][k], acc[ai][bj][m][n], 0, 0, 0); __builtin_amdgcn_s_setprio(0); } while (0)
; #define PG8_WAIT_V(n) asm volatile("s_waitcnt vmcnt(" #n ")" ::: "memory")
; #define PG8_WAIT_L(n) asm volatile("s_waitcnt lgkmcnt(" #n ")" ::: "memory")
; #define PG8_BAR __builtin_amdgcn_s_barrier()
; #define PG8_SCHED __builtin_amdgcn_sched_barrier(0)
; template <class Epi, class Sched, bool ALIGN_EPI = false, bool SP2 = false>
; __device__ __forceinline__ void gemm_phase(PG8_LAS unsigned char* lds, const Gemm g, const Sched& S, const Epi& E) {
;     ...
;             PG8_WAIT_V(8); PG8_WAIT_L(0); PG8_BAR; PG8_MMA(0, 0, At, B0); PG8_MMA(0, 1, At, B1); PG8_BAR; PG8_SCHED;
;             PG8_LDA(At, 0, 1); PG8_STAGE(PG8_SB(0, 0), b2, voffB); PG8_STAGE(PG8_SB(0, 1), b2 + hstep, voffB); PG8_STAGE(PG8_SA(0, 0), a2, voffA);
;             PG8_WAIT_V(8); PG8_WAIT_L(0); PG8_BAR; PG8_MMA(1, 0, At, B0); PG8_MMA(1, 1, At, B1); PG8_BAR; PG8_SCHED;
;             PG8_LDB(B0, 1, 0); PG8_LDB(B1, 1, 1); PG8_SCHED; PG8_LDA(At, 1, 0); PG8_STAGE(PG8_SA(0, 1), a2 + hstep, voffA);
;             PG8_WAIT_V(8); PG8_WAIT_L(0); PG8_BAR; PG8_MMA(0, 0, At, B0); PG8_MMA(0, 1, At, B1); PG8_BAR; PG8_SCHED;
;             PG8_LDA(At, 1, 1); PG8_STAGE(PG8_SB(1, 0), b3, voffB); PG8_STAGE(PG8_SB(1, 1), b3 + hstep, voffB); PG8_STAGE(PG8_SA(1, 0), a3, voffA);
	s_setprio 1
	s_waitcnt lgkmcnt(7)
	v_mfma_f32_16x16x32_bf16 v[62:65], v[152:155], v[184:187], v[62:65]
	v_mfma_f32_16x16x32_bf16 v[58:61], v[160:163], v[184:187], v[58:61]
	s_waitcnt lgkmcnt(5)
	v_mfma_f32_16x16x32_bf16 v[46:49], v[152:155], v[192:195], v[46:49]
	v_mfma_f32_16x16x32_bf16 v[42:45], v[160:163], v[192:195], v[42:45]
	s_waitcnt lgkmcnt(3)
	v_mfma_f32_16x16x32_bf16 v[30:33], v[152:155], v[200:203], v[30:33]
	v_mfma_f32_16x16x32_bf16 v[26:29], v[160:163], v[200:203], v[26:29]
	s_waitcnt lgkmcnt(1)
	v_mfma_f32_16x16x32_bf16 v[14:17], v[152:155], v[208:211], v[14:17]
	v_mfma_f32_16x16x32_bf16 v[10:13], v[160:163], v[208:211], v[10:13]
	v_mfma_f32_16x16x32_bf16 v[62:65], v[156:159], v[188:191], v[62:65]
	v_mfma_f32_16x16x32_bf16 v[58:61], v[164:167], v[188:191], v[58:61]
	v_mfma_f32_16x16x32_bf16 v[46:49], v[156:159], v[196:199], v[46:49]
	v_mfma_f32_16x16x32_bf16 v[42:45], v[164:167], v[196:199], v[42:45]
	v_mfma_f32_16x16x32_bf16 v[30:33], v[156:159], v[204:207], v[30:33]
	v_mfma_f32_16x16x32_bf16 v[26:29], v[164:167], v[204:207], v[26:29]
	s_waitcnt lgkmcnt(0)
	v_mfma_f32_16x16x32_bf16 v[14:17], v[156:159], v[212:215], v[14:17]
	v_mfma_f32_16x16x32_bf16 v[10:13], v[164:167], v[212:215], v[10:13]
	s_setprio 0
	s_setprio 1
	v_mfma_f32_16x16x32_bf16 v[54:57], v[168:171], v[184:187], v[54:57]
	v_mfma_f32_16x16x32_bf16 v[50:53], v[176:179], v[184:187], v[50:53]
	v_mfma_f32_16x16x32_bf16 v[38:41], v[168:171], v[192:195], v[38:41]
	v_mfma_f32_16x16x32_bf16 v[34:37], v[176:179], v[192:195], v[34:37]
	v_mfma_f32_16x16x32_bf16 v[22:25], v[168:171], v[200:203], v[22:25]
	v_mfma_f32_16x16x32_bf16 v[18:21], v[176:179], v[200:203], v[18:21]
	v_mfma_f32_16x16x32_bf16 v[6:9], v[168:171], v[208:211], v[6:9]
	v_mfma_f32_16x16x32_bf16 v[2:5], v[176:179], v[208:211], v[2:5]
	v_mfma_f32_16x16x32_bf16 v[54:57], v[172:175], v[188:191], v[54:57]
	v_mfma_f32_16x16x32_bf16 v[50:53], v[180:183], v[188:191], v[50:53]
	v_mfma_f32_16x16x32_bf16 v[38:41], v[172:175], v[196:199], v[38:41]
	v_mov_b32_e32 v248, v180
	v_mov_b32_e32 v249, v181
	v_mfma_f32_16x16x32_bf16 v[34:37], v[180:183], v[196:199], v[34:37]
	v_mov_b32_e32 v250, v182
	v_mov_b32_e32 v251, v183
	v_mfma_f32_16x16x32_bf16 v[22:25], v[172:175], v[204:207], v[22:25]
	v_mov_b32_e32 v252, v212
	v_mov_b32_e32 v253, v213
	v_mfma_f32_16x16x32_bf16 v[18:21], v[180:183], v[204:207], v[18:21]
	v_mov_b32_e32 v254, v214
	v_mov_b32_e32 v255, v215
	v_mfma_f32_16x16x32_bf16 v[6:9], v[172:175], v[212:215], v[6:9]
	s_setprio 2
	s_barrier
	v_mfma_f32_16x16x32_bf16 v[2:5], v[248:251], v[252:255], v[2:5]
	s_setprio 0
	v_add_u32_e32 v164, 0x18000, v149
	v_add_u32_e32 v180, 0x1c000, v149
	ds_read_b128 v[152:155], v164
	ds_read_b128 v[156:159], v164 offset:1024
	ds_read_b128 v[160:163], v164 offset:2048
	ds_read_b128 v[164:167], v164 offset:3072
	ds_read_b128 v[168:171], v180
	ds_read_b128 v[172:175], v180 offset:1024
	ds_read_b128 v[176:179], v180 offset:2048
	ds_read_b128 v[180:183], v180 offset:3072
	ds_read_b128 v[184:187], v150 offset:32768
	ds_read_b128 v[188:191], v150 offset:33792
	ds_read_b128 v[192:195], v150 offset:34816
	ds_read_b128 v[196:199], v150 offset:35840
	ds_read_b128 v[200:203], v150 offset:36864
	ds_read_b128 v[204:207], v150 offset:37888
	ds_read_b128 v[208:211], v150 offset:38912
	ds_read_b128 v[212:215], v150 offset:39936
	s_add_u32 s40, s46, 0x100000
	s_addc_u32 s41, s47, 0
	s_mov_b32 m0, s54
	s_nop 0
	global_load_lds_dwordx4 v139, s[40:41]
	s_nop 0
	s_mov_b32 m0, s55
	s_nop 0
	global_load_lds_dwordx4 v141, s[40:41]
	s_waitcnt vmcnt(8)
	s_waitcnt lgkmcnt(0)
	s_barrier
	s_setprio 1
	s_waitcnt lgkmcnt(7)
	v_mfma_f32_16x16x32_bf16 v[126:129], v[152:155], v[184:187], v[126:129]
	v_mfma_f32_16x16x32_bf16 v[122:125], v[160:163], v[184:187], v[122:125]
	s_waitcnt lgkmcnt(5)
	v_mfma_f32_16x16x32_bf16 v[110:113], v[152:155], v[192:195], v[110:113]
	v_mfma_f32_16x16x32_bf16 v[106:109], v[160:163], v[192:195], v[106:109]
	s_waitcnt lgkmcnt(3)
	v_mfma_f32_16x16x32_bf16 v[94:97], v[152:155], v[200:203], v[94:97]
	v_mfma_f32_16x16x32_bf16 v[90:93], v[160:163], v[200:203], v[90:93]
	s_waitcnt lgkmcnt(1)
	v_mfma_f32_16x16x32_bf16 v[78:81], v[152:155], v[208:211], v[78:81]
	v_mfma_f32_16x16x32_bf16 v[74:77], v[160:163], v[208:211], v[74:77]
	v_mfma_f32_16x16x32_bf16 v[126:129], v[156:159], v[188:191], v[126:129]
	v_mfma_f32_16x16x32_bf16 v[122:125], v[164:167], v[188:191], v[122:125]
	v_mfma_f32_16x16x32_bf16 v[110:113], v[156:159], v[196:199], v[110:113]
	v_mfma_f32_16x16x32_bf16 v[106:109], v[164:167], v[196:199], v[106:109]
	v_mfma_f32_16x16x32_bf16 v[94:97], v[156:159], v[204:207], v[94:97]
	v_mfma_f32_16x16x32_bf16 v[90:93], v[164:167], v[204:207], v[90:93]
	s_waitcnt lgkmcnt(0)
	v_mfma_f32_16x16x32_bf16 v[78:81], v[156:159], v[212:215], v[78:81]
	v_mfma_f32_16x16x32_bf16 v[74:77], v[164:167], v[212:215], v[74:77]
	s_setprio 0
	s_setprio 1
	v_mfma_f32_16x16x32_bf16 v[118:121], v[168:171], v[184:187], v[118:121]
	v_mfma_f32_16x16x32_bf16 v[114:117], v[176:179], v[184:187], v[114:117]
	v_mfma_f32_16x16x32_bf16 v[102:105], v[168:171], v[192:195], v[102:105]
	v_mfma_f32_16x16x32_bf16 v[98:101], v[176:179], v[192:195], v[98:101]
	v_mfma_f32_16x16x32_bf16 v[86:89], v[168:171], v[200:203], v[86:89]
	v_mfma_f32_16x16x32_bf16 v[82:85], v[176:179], v[200:203], v[82:85]
	v_mfma_f32_16x16x32_bf16 v[70:73], v[168:171], v[208:211], v[70:73]
	v_mfma_f32_16x16x32_bf16 v[66:69], v[176:179], v[208:211], v[66:69]
	v_mfma_f32_16x16x32_bf16 v[118:121], v[172:175], v[188:191], v[118:121]
	v_mfma_f32_16x16x32_bf16 v[114:117], v[180:183], v[188:191], v[114:117]
	v_mfma_f32_16x16x32_bf16 v[102:105], v[172:175], v[196:199], v[102:105]
	v_mov_b32_e32 v248, v180
	v_mov_b32_e32 v249, v181
	v_mfma_f32_16x16x32_bf16 v[98:101], v[180:183], v[196:199], v[98:101]
	v_mov_b32_e32 v250, v182
	v_mov_b32_e32 v251, v183
	v_mfma_f32_16x16x32_bf16 v[86:89], v[172:175], v[204:207], v[86:89]
	v_mov_b32_e32 v252, v212
	v_mov_b32_e32 v253, v213
	v_mfma_f32_16x16x32_bf16 v[82:85], v[180:183], v[204:207], v[82:85]
	v_mov_b32_e32 v254, v214
	v_mov_b32_e32 v255, v215
	v_mfma_f32_16x16x32_bf16 v[70:73], v[172:175], v[212:215], v[70:73]
	s_setprio 2
	s_barrier
; #define PG8_STAGE(bufoff, gbase, voff) do { _Pragma("unroll") for (int _i = 0; _i < 2; ++_i) \
;         asm volatile("s_mov_b32 m0, %2\n\ts_nop 0\n\tglobal_load_lds_dwordx4 %0, %1" :: "v"((voff)[_i]), "s"((const char*)(gbase)), "s"(ldsbase + (unsigned)(bufoff) + ldsw + (unsigned)_i * 8192u) : "memory", "m0"); } while (0)
; #define PG8_LDA(dst, b, h) do { _Pragma("unroll") for (int m = 0; m < 4; ++m) _Pragma("unroll") for (int k = 0; k < 2; ++k) dst[m][k] = *(const PG8_LAS bf16x8*)(lds + PG8_SA(b, h) + aoff + m * 2048 + k * 1024); } while (0)
; #define PG8_MMA(ai, bj, At, Bt) do { __builtin_amdgcn_s_setprio(1); _Pragma("unroll") for (int m = 0; m < 4; ++m) _Pragma("unroll") for (int n = 0; n < 2; ++n) _Pragma("unroll") for (int k = 0; k < 2; ++k) \
;         acc[ai][bj][m][n] = __builtin_amdgcn_mfma_f32_16x16x32_bf16(Bt[n][k], At[m][k], acc[ai][bj][m][n], 0, 0, 0); __builtin_amdgcn_s_setprio(0); } while (0)
; #define PG8_WAIT_V(n) asm volatile("s_waitcnt vmcnt(" #n ")" ::: "memory")
; #define PG8_WAIT_L(n) asm volatile("s_waitcnt lgkmcnt(" #n ")" ::: "memory")
; #define PG8_BAR __builtin_amdgcn_s_barrier()
; #define PG8_SCHED __builtin_amdgcn_sched_barrier(0)
; template <class Epi, class Sched, bool ALIGN_EPI = false, bool SP2 = false>
; __device__ __forceinline__ void gemm_phase(PG8_LAS unsigned char* lds, const Gemm g, const Sched& S, const Epi& E) {
;     ...
;             PG8_WAIT_V(8); PG8_WAIT_L(0); PG8_BAR; PG8_MMA(0, 0, At, B0); PG8_MMA(0, 1, At, B1); PG8_BAR; PG8_SCHED;
;             PG8_LDA(At, 1, 1); PG8_STAGE(PG8_SB(1, 0), b3, voffB); PG8_STAGE(PG8_SB(1, 1), b3 + hstep, voffB); PG8_STAGE(PG8_SA(1, 0), a3, voffA);
;             PG8_WAIT_V(8); PG8_WAIT_L(0); PG8_BAR; PG8_MMA(1, 0, At, B0); PG8_MMA(1, 1, At, B1); PG8_BAR; PG8_SCHED;
	v_mfma_f32_16x16x32_bf16 v[66:69], v[248:251], v[252:255], v[66:69]
	s_setprio 0
	ds_read_b128 v[184:187], v150 offset:49152
	ds_read_b128 v[188:191], v150 offset:50176
	ds_read_b128 v[192:195], v150 offset:51200
	ds_read_b128 v[196:199], v150 offset:52224
	ds_read_b128 v[200:203], v150 offset:53248
	ds_read_b128 v[204:207], v150 offset:54272
	ds_read_b128 v[208:211], v150 offset:55296
	ds_read_b128 v[212:215], v150 offset:56320
	s_mov_b32 m0, s56
	s_nop 0
	global_load_lds_dwordx4 v140, s[44:45]
	s_add_u32 s38, s38, 0x100080
	s_mov_b32 m0, s57
	s_nop 0
	global_load_lds_dwordx4 v142, s[44:45]
	s_addc_u32 s39, s39, 0
	s_mov_b32 m0, s62
	s_nop 0
	global_load_lds_dwordx4 v140, s[38:39]
	s_nop 0
	s_mov_b32 m0, s63
	s_nop 0
	global_load_lds_dwordx4 v142, s[38:39]
	s_nop 0
	s_mov_b32 m0, s60
	s_nop 0
	global_load_lds_dwordx4 v139, s[42:43]
	s_nop 0
	s_mov_b32 m0, s61
	s_nop 0
	global_load_lds_dwordx4 v141, s[42:43]
	s_waitcnt vmcnt(8)
	s_waitcnt lgkmcnt(0)
	s_barrier
	s_setprio 1
	s_waitcnt lgkmcnt(7)
	v_mfma_f32_16x16x32_bf16 v[62:65], v[152:155], v[184:187], v[62:65]
	v_mfma_f32_16x16x32_bf16 v[58:61], v[160:163], v[184:187], v[58:61]
	s_waitcnt lgkmcnt(5)
	v_mfma_f32_16x16x32_bf16 v[46:49], v[152:155], v[192:195], v[46:49]
	v_mfma_f32_16x16x32_bf16 v[42:45], v[160:163], v[192:195], v[42:45]
	s_waitcnt lgkmcnt(3)
	v_mfma_f32_16x16x32_bf16 v[30:33], v[152:155], v[200:203], v[30:33]
	v_mfma_f32_16x16x32_bf16 v[26:29], v[160:163], v[200:203], v[26:29]
	s_waitcnt lgkmcnt(1)
	v_mfma_f32_16x16x32_bf16 v[14:17], v[152:155], v[208:211], v[14:17]
	v_mfma_f32_16x16x32_bf16 v[10:13], v[160:163], v[208:211], v[10:13]
	v_mfma_f32_16x16x32_bf16 v[62:65], v[156:159], v[188:191], v[62:65]
	v_mfma_f32_16x16x32_bf16 v[58:61], v[164:167], v[188:191], v[58:61]
	v_mfma_f32_16x16x32_bf16 v[46:49], v[156:159], v[196:199], v[46:49]
	v_mfma_f32_16x16x32_bf16 v[42:45], v[164:167], v[196:199], v[42:45]
	v_mfma_f32_16x16x32_bf16 v[30:33], v[156:159], v[204:207], v[30:33]
	v_mfma_f32_16x16x32_bf16 v[26:29], v[164:167], v[204:207], v[26:29]
	s_waitcnt lgkmcnt(0)
	v_mfma_f32_16x16x32_bf16 v[14:17], v[156:159], v[212:215], v[14:17]
	v_mfma_f32_16x16x32_bf16 v[10:13], v[164:167], v[212:215], v[10:13]
	s_setprio 0
	s_setprio 1
	v_mfma_f32_16x16x32_bf16 v[54:57], v[168:171], v[184:187], v[54:57]
	v_mfma_f32_16x16x32_bf16 v[50:53], v[176:179], v[184:187], v[50:53]
	v_mfma_f32_16x16x32_bf16 v[38:41], v[168:171], v[192:195], v[38:41]
	v_mfma_f32_16x16x32_bf16 v[34:37], v[176:179], v[192:195], v[34:37]
	v_mfma_f32_16x16x32_bf16 v[22:25], v[168:171], v[200:203], v[22:25]
	v_mfma_f32_16x16x32_bf16 v[18:21], v[176:179], v[200:203], v[18:21]
	v_mfma_f32_16x16x32_bf16 v[6:9], v[168:171], v[208:211], v[6:9]
	v_mfma_f32_16x16x32_bf16 v[2:5], v[176:179], v[208:211], v[2:5]
	v_mfma_f32_16x16x32_bf16 v[54:57], v[172:175], v[188:191], v[54:57]
	v_mfma_f32_16x16x32_bf16 v[50:53], v[180:183], v[188:191], v[50:53]
	v_mfma_f32_16x16x32_bf16 v[38:41], v[172:175], v[196:199], v[38:41]
	v_mov_b32_e32 v248, v180
	v_mov_b32_e32 v249, v181
	v_mfma_f32_16x16x32_bf16 v[34:37], v[180:183], v[196:199], v[34:37]
	v_mov_b32_e32 v250, v182
	v_mov_b32_e32 v251, v183
	v_mfma_f32_16x16x32_bf16 v[22:25], v[172:175], v[204:207], v[22:25]
	v_mov_b32_e32 v252, v212
	v_mov_b32_e32 v253, v213
	v_mfma_f32_16x16x32_bf16 v[18:21], v[180:183], v[204:207], v[18:21]
	v_mov_b32_e32 v254, v214
	v_mov_b32_e32 v255, v215
	v_mfma_f32_16x16x32_bf16 v[6:9], v[172:175], v[212:215], v[6:9]
	s_setprio 2
	s_barrier
	v_mfma_f32_16x16x32_bf16 v[2:5], v[248:251], v[252:255], v[2:5]
	s_setprio 0
	s_add_i32 s76, s76, 2
	s_add_u32 s74, s74, 0x100
	s_addc_u32 s75, s75, 0
	s_cmp_gt_u32 s76, 61
	s_cbranch_scc1 .LBB0_780
	s_mov_b64 s[40:41], s[8:9]
	s_branch .LBB0_784

; #define PG8_STAGE(bufoff, gbase, voff) do { _Pragma("unroll") for (int _i = 0; _i < 2; ++_i) \
;         asm volatile("s_mov_b32 m0, %2\n\ts_nop 0\n\tglobal_load_lds_dwordx4 %0, %1" :: "v"((voff)[_i]), "s"((const char*)(gbase)), "s"(ldsbase + (unsigned)(bufoff) + ldsw + (unsigned)_i * 8192u) : "memory", "m0"); } while (0)
; #define PG8_LDA(dst, b, h) do { _Pragma("unroll") for (int m = 0; m < 4; ++m) _Pragma("unroll") for (int k = 0; k < 2; ++k) dst[m][k] = *(const PG8_LAS bf16x8*)(lds + PG8_SA(b, h) + aoff + m * 2048 + k * 1024); } while (0)
; #define PG8_LDB(dst, b, h) do { _Pragma("unroll") for (int n = 0; n < 2; ++n) _Pragma("unroll") for (int k = 0; k < 2; ++k) dst[n][k] = *(const PG8_LAS bf16x8*)(lds + PG8_SB(b, h) + boff + n * 2048 + k * 1024); } while (0)
; #define PG8_MMA(ai, bj, At, Bt) do { __builtin_amdgcn_s_setprio(1); _Pragma("unroll") for (int m = 0; m < 4; ++m) _Pragma("unroll") for (int n = 0; n < 2; ++n) _Pragma("unroll") for (int k = 0; k < 2; ++k) \
;         acc[ai][bj][m][n] = __builtin_amdgcn_mfma_f32_16x16x32_bf16(Bt[n][k], At[m][k], acc[ai][bj][m][n], 0, 0, 0); __builtin_amdgcn_s_setprio(0); } while (0)
; #define PG8_WAIT_V(n) asm volatile("s_waitcnt vmcnt(" #n ")" ::: "memory")
; #define PG8_WAIT_L(n) asm volatile("s_waitcnt lgkmcnt(" #n ")" ::: "memory")
; #define PG8_BAR __builtin_amdgcn_s_barrier()
; #define PG8_SCHED __builtin_amdgcn_sched_barrier(0)
; template <class Epi, class Sched, bool ALIGN_EPI = false, bool SP2 = false>
; __device__ __forceinline__ void gemm_phase(PG8_LAS unsigned char* lds, const Gemm g, const Sched& S, const Epi& E) {
;     ...
;             PG8_LDB(B0, 0, 0); PG8_LDB(B1, 0, 1); PG8_SCHED; PG8_LDA(At, 0, 0); PG8_STAGE(PG8_SA(1, 1), a1 + hstep, voffA);
;             PG8_WAIT_V(8); PG8_WAIT_L(0); PG8_BAR; PG8_MMA(0, 0, At, B0); PG8_MMA(0, 1, At, B1); PG8_BAR; PG8_SCHED;
;             PG8_LDA(At, 0, 1); PG8_STAGE(PG8_SB(0, 0), b2, voffB); PG8_STAGE(PG8_SB(0, 1), b2 + hstep, voffB); PG8_STAGE(PG8_SA(0, 0), a2, voffA);
.LBB0_873:
	ds_read_b128 v[134:137], v145
	ds_read_b128 v[150:153], v145 offset:1024
	ds_read_b128 v[154:157], v145 offset:2048
	ds_read_b128 v[158:161], v145 offset:3072
	ds_read_b128 v[162:165], v146
	ds_read_b128 v[166:169], v146 offset:1024
	ds_read_b128 v[170:173], v146 offset:2048
	ds_read_b128 v[174:177], v146 offset:3072
	s_add_u32 s38, s36, 0x100
	s_addc_u32 s39, s37, 0
	s_cmpk_eq_i32 s69, 0xa8
	s_cselect_b32 s44, s4, s38
	s_cselect_b32 s45, s5, s39
	s_cselect_b32 s42, s22, s67
	s_cselect_b32 s43, s23, s68
	s_add_u32 s40, s44, 0x80
	s_addc_u32 s41, s45, 0
	ds_read_b128 v[178:181], v147
	ds_read_b128 v[182:185], v147 offset:1024
	ds_read_b128 v[186:189], v147 offset:2048
	ds_read_b128 v[190:193], v147 offset:3072
	ds_read_b128 v[194:197], v147 offset:4096
	ds_read_b128 v[198:201], v147 offset:5120
	ds_read_b128 v[202:205], v147 offset:6144
	ds_read_b128 v[206:209], v147 offset:7168
	s_add_u32 s36, s36, 0x2b0080
	s_addc_u32 s37, s37, 0
	s_mov_b32 m0, s60
	s_nop 0
	global_load_lds_dwordx4 v1, s[36:37]
	s_nop 0
	s_mov_b32 m0, s61
	s_nop 0
	global_load_lds_dwordx4 v141, s[36:37]
	s_waitcnt vmcnt(8)
	s_waitcnt lgkmcnt(0)
	s_barrier
	s_setprio 1
	s_waitcnt lgkmcnt(7)
	v_mfma_f32_16x16x32_bf16 v[126:129], v[134:137], v[178:181], v[126:129]
	v_mfma_f32_16x16x32_bf16 v[122:125], v[154:157], v[178:181], v[122:125]
	s_waitcnt lgkmcnt(5)
	v_mfma_f32_16x16x32_bf16 v[110:113], v[134:137], v[186:189], v[110:113]
	v_mfma_f32_16x16x32_bf16 v[106:109], v[154:157], v[186:189], v[106:109]
	s_waitcnt lgkmcnt(3)
	v_mfma_f32_16x16x32_bf16 v[94:97], v[134:137], v[194:197], v[94:97]
	v_mfma_f32_16x16x32_bf16 v[90:93], v[154:157], v[194:197], v[90:93]
	s_waitcnt lgkmcnt(1)
	v_mfma_f32_16x16x32_bf16 v[78:81], v[134:137], v[202:205], v[78:81]
	v_mfma_f32_16x16x32_bf16 v[74:77], v[154:157], v[202:205], v[74:77]
	v_mfma_f32_16x16x32_bf16 v[126:129], v[150:153], v[182:185], v[126:129]
	v_mfma_f32_16x16x32_bf16 v[122:125], v[158:161], v[182:185], v[122:125]
	v_mfma_f32_16x16x32_bf16 v[110:113], v[150:153], v[190:193], v[110:113]
	v_mfma_f32_16x16x32_bf16 v[106:109], v[158:161], v[190:193], v[106:109]
	v_mfma_f32_16x16x32_bf16 v[94:97], v[150:153], v[198:201], v[94:97]
	v_mfma_f32_16x16x32_bf16 v[90:93], v[158:161], v[198:201], v[90:93]
	s_waitcnt lgkmcnt(0)
	v_mfma_f32_16x16x32_bf16 v[78:81], v[150:153], v[206:209], v[78:81]
	v_mfma_f32_16x16x32_bf16 v[74:77], v[158:161], v[206:209], v[74:77]
	s_setprio 0
	s_setprio 1
	v_mfma_f32_16x16x32_bf16 v[118:121], v[162:165], v[178:181], v[118:121]
	v_mfma_f32_16x16x32_bf16 v[114:117], v[170:173], v[178:181], v[114:117]
	v_mfma_f32_16x16x32_bf16 v[102:105], v[162:165], v[186:189], v[102:105]
	v_mfma_f32_16x16x32_bf16 v[98:101], v[170:173], v[186:189], v[98:101]
	v_mfma_f32_16x16x32_bf16 v[86:89], v[162:165], v[194:197], v[86:89]
	v_mfma_f32_16x16x32_bf16 v[82:85], v[170:173], v[194:197], v[82:85]
	v_mfma_f32_16x16x32_bf16 v[70:73], v[162:165], v[202:205], v[70:73]
	v_mfma_f32_16x16x32_bf16 v[66:69], v[170:173], v[202:205], v[66:69]
	v_mfma_f32_16x16x32_bf16 v[118:121], v[166:169], v[182:185], v[118:121]
	v_mfma_f32_16x16x32_bf16 v[114:117], v[174:177], v[182:185], v[114:117]
	v_mfma_f32_16x16x32_bf16 v[102:105], v[166:169], v[190:193], v[102:105]
	v_mov_b32_e32 v248, v174
	v_mov_b32_e32 v249, v175
	v_mfma_f32_16x16x32_bf16 v[98:101], v[174:177], v[190:193], v[98:101]
	v_mov_b32_e32 v250, v176
	v_mov_b32_e32 v251, v177
	v_mfma_f32_16x16x32_bf16 v[86:89], v[166:169], v[198:201], v[86:89]
	v_mov_b32_e32 v252, v206
	v_mov_b32_e32 v253, v207
	v_mfma_f32_16x16x32_bf16 v[82:85], v[174:177], v[198:201], v[82:85]
	v_mov_b32_e32 v254, v208
	v_mov_b32_e32 v255, v209
	v_mfma_f32_16x16x32_bf16 v[70:73], v[166:169], v[206:209], v[70:73]
	s_setprio 2
	s_barrier
	v_mfma_f32_16x16x32_bf16 v[66:69], v[248:251], v[252:255], v[66:69]
	s_setprio 0
	ds_read_b128 v[178:181], v147 offset:16384
	ds_read_b128 v[182:185], v147 offset:17408
	ds_read_b128 v[186:189], v147 offset:18432
	ds_read_b128 v[190:193], v147 offset:19456
	ds_read_b128 v[194:197], v147 offset:20480
	ds_read_b128 v[198:201], v147 offset:21504
	ds_read_b128 v[202:205], v147 offset:22528
	ds_read_b128 v[206:209], v147 offset:23552
	s_mov_b32 m0, s47
	s_nop 0
	global_load_lds_dwordx4 v140, s[42:43]
	s_add_u32 s36, s42, 0x2b0000
	s_mov_b32 m0, s48
	s_nop 0
	global_load_lds_dwordx4 v142, s[42:43]
	s_addc_u32 s37, s43, 0
	s_mov_b32 m0, s49
	s_nop 0
	global_load_lds_dwordx4 v140, s[36:37]
	s_nop 0
	s_mov_b32 m0, s50
	s_nop 0
	global_load_lds_dwordx4 v142, s[36:37]
	s_nop 0
	s_mov_b32 m0, s46
	s_nop 0
	global_load_lds_dwordx4 v1, s[44:45]
	s_nop 0
	s_mov_b32 m0, s51
	s_nop 0
	global_load_lds_dwordx4 v141, s[44:45]
	s_waitcnt vmcnt(8)
	s_waitcnt lgkmcnt(0)
	s_barrier
; #define PG8_STAGE(bufoff, gbase, voff) do { _Pragma("unroll") for (int _i = 0; _i < 2; ++_i) \
;         asm volatile("s_mov_b32 m0, %2\n\ts_nop 0\n\tglobal_load_lds_dwordx4 %0, %1" :: "v"((voff)[_i]), "s"((const char*)(gbase)), "s"(ldsbase + (unsigned)(bufoff) + ldsw + (unsigned)_i * 8192u) : "memory", "m0"); } while (0)
; #define PG8_LDA(dst, b, h) do { _Pragma("unroll") for (int m = 0; m < 4; ++m) _Pragma("unroll") for (int k = 0; k < 2; ++k) dst[m][k] = *(const PG8_LAS bf16x8*)(lds + PG8_SA(b, h) + aoff + m * 2048 + k * 1024); } while (0)
; #define PG8_LDB(dst, b, h) do { _Pragma("unroll") for (int n = 0; n < 2; ++n) _Pragma("unroll") for (int k = 0; k < 2; ++k) dst[n][k] = *(const PG8_LAS bf16x8*)(lds + PG8_SB(b, h) + boff + n * 2048 + k * 1024); } while (0)
; #define PG8_MMA(ai, bj, At, Bt) do { __builtin_amdgcn_s_setprio(1); _Pragma("unroll") for (int m = 0; m < 4; ++m) _Pragma("unroll") for (int n = 0; n < 2; ++n) _Pragma("unroll") for (int k = 0; k < 2; ++k) \
;         acc[ai][bj][m][n] = __builtin_amdgcn_mfma_f32_16x16x32_bf16(Bt[n][k], At[m][k], acc[ai][bj][m][n], 0, 0, 0); __builtin_amdgcn_s_setprio(0); } while (0)
; #define PG8_WAIT_V(n) asm volatile("s_waitcnt vmcnt(" #n ")" ::: "memory")
; #define PG8_WAIT_L(n) asm volatile("s_waitcnt lgkmcnt(" #n ")" ::: "memory")
; #define PG8_BAR __builtin_amdgcn_s_barrier()
; #define PG8_SCHED __builtin_amdgcn_sched_barrier(0)
; template <class Epi, class Sched, bool ALIGN_EPI = false, bool SP2 = false>
; __device__ __forceinline__ void gemm_phase(PG8_LAS unsigned char* lds, const Gemm g, const Sched& S, const Epi& E) {
;     ...
;             PG8_WAIT_V(8); PG8_WAIT_L(0); PG8_BAR; PG8_MMA(0, 0, At, B0); PG8_MMA(0, 1, At, B1); PG8_BAR; PG8_SCHED;
;             PG8_LDA(At, 0, 1); PG8_STAGE(PG8_SB(0, 0), b2, voffB); PG8_STAGE(PG8_SB(0, 1), b2 + hstep, voffB); PG8_STAGE(PG8_SA(0, 0), a2, voffA);
;             PG8_WAIT_V(8); PG8_WAIT_L(0); PG8_BAR; PG8_MMA(1, 0, At, B0); PG8_MMA(1, 1, At, B1); PG8_BAR; PG8_SCHED;
;             PG8_LDB(B0, 1, 0); PG8_LDB(B1, 1, 1); PG8_SCHED; PG8_LDA(At, 1, 0); PG8_STAGE(PG8_SA(0, 1), a2 + hstep, voffA);
;             PG8_WAIT_V(8); PG8_WAIT_L(0); PG8_BAR; PG8_MMA(0, 0, At, B0); PG8_MMA(0, 1, At, B1); PG8_BAR; PG8_SCHED;
;             PG8_LDA(At, 1, 1); PG8_STAGE(PG8_SB(1, 0), b3, voffB); PG8_STAGE(PG8_SB(1, 1), b3 + hstep, voffB); PG8_STAGE(PG8_SA(1, 0), a3, voffA);
	s_setprio 1
	s_waitcnt lgkmcnt(7)
	v_mfma_f32_16x16x32_bf16 v[62:65], v[134:137], v[178:181], v[62:65]
	v_mfma_f32_16x16x32_bf16 v[58:61], v[154:157], v[178:181], v[58:61]
	s_waitcnt lgkmcnt(5)
	v_mfma_f32_16x16x32_bf16 v[46:49], v[134:137], v[186:189], v[46:49]
	v_mfma_f32_16x16x32_bf16 v[42:45], v[154:157], v[186:189], v[42:45]
	s_waitcnt lgkmcnt(3)
	v_mfma_f32_16x16x32_bf16 v[30:33], v[134:137], v[194:197], v[30:33]
	v_mfma_f32_16x16x32_bf16 v[26:29], v[154:157], v[194:197], v[26:29]
	s_waitcnt lgkmcnt(1)
	v_mfma_f32_16x16x32_bf16 v[14:17], v[134:137], v[202:205], v[14:17]
	v_mfma_f32_16x16x32_bf16 v[10:13], v[154:157], v[202:205], v[10:13]
	v_mfma_f32_16x16x32_bf16 v[62:65], v[150:153], v[182:185], v[62:65]
	v_mfma_f32_16x16x32_bf16 v[58:61], v[158:161], v[182:185], v[58:61]
	v_mfma_f32_16x16x32_bf16 v[46:49], v[150:153], v[190:193], v[46:49]
	v_mfma_f32_16x16x32_bf16 v[42:45], v[158:161], v[190:193], v[42:45]
	v_mfma_f32_16x16x32_bf16 v[30:33], v[150:153], v[198:201], v[30:33]
	v_mfma_f32_16x16x32_bf16 v[26:29], v[158:161], v[198:201], v[26:29]
	s_waitcnt lgkmcnt(0)
	v_mfma_f32_16x16x32_bf16 v[14:17], v[150:153], v[206:209], v[14:17]
	v_mfma_f32_16x16x32_bf16 v[10:13], v[158:161], v[206:209], v[10:13]
	s_setprio 0
	s_setprio 1
	v_mfma_f32_16x16x32_bf16 v[54:57], v[162:165], v[178:181], v[54:57]
	v_mfma_f32_16x16x32_bf16 v[50:53], v[170:173], v[178:181], v[50:53]
	v_mfma_f32_16x16x32_bf16 v[38:41], v[162:165], v[186:189], v[38:41]
	v_mfma_f32_16x16x32_bf16 v[34:37], v[170:173], v[186:189], v[34:37]
	v_mfma_f32_16x16x32_bf16 v[22:25], v[162:165], v[194:197], v[22:25]
	v_mfma_f32_16x16x32_bf16 v[18:21], v[170:173], v[194:197], v[18:21]
	v_mfma_f32_16x16x32_bf16 v[6:9], v[162:165], v[202:205], v[6:9]
	v_mfma_f32_16x16x32_bf16 v[2:5], v[170:173], v[202:205], v[2:5]
	v_mfma_f32_16x16x32_bf16 v[54:57], v[166:169], v[182:185], v[54:57]
	v_mfma_f32_16x16x32_bf16 v[50:53], v[174:177], v[182:185], v[50:53]
	v_mfma_f32_16x16x32_bf16 v[38:41], v[166:169], v[190:193], v[38:41]
	v_mov_b32_e32 v248, v174
	v_mov_b32_e32 v249, v175
	v_mfma_f32_16x16x32_bf16 v[34:37], v[174:177], v[190:193], v[34:37]
	v_mov_b32_e32 v250, v176
	v_mov_b32_e32 v251, v177
	v_mfma_f32_16x16x32_bf16 v[22:25], v[166:169], v[198:201], v[22:25]
	v_mov_b32_e32 v252, v206
	v_mov_b32_e32 v253, v207
	v_mfma_f32_16x16x32_bf16 v[18:21], v[174:177], v[198:201], v[18:21]
	v_mov_b32_e32 v254, v208
	v_mov_b32_e32 v255, v209
	v_mfma_f32_16x16x32_bf16 v[6:9], v[166:169], v[206:209], v[6:9]
	s_setprio 2
	s_barrier
	v_mfma_f32_16x16x32_bf16 v[2:5], v[248:251], v[252:255], v[2:5]
	s_setprio 0
	ds_read_b128 v[134:137], v148
	ds_read_b128 v[150:153], v148 offset:1024
	ds_read_b128 v[154:157], v148 offset:2048
	ds_read_b128 v[158:161], v148 offset:3072
	ds_read_b128 v[162:165], v149
	ds_read_b128 v[166:169], v149 offset:1024
	ds_read_b128 v[170:173], v149 offset:2048
	ds_read_b128 v[174:177], v149 offset:3072
	ds_read_b128 v[178:181], v147 offset:32768
	ds_read_b128 v[182:185], v147 offset:33792
	ds_read_b128 v[186:189], v147 offset:34816
	ds_read_b128 v[190:193], v147 offset:35840
	ds_read_b128 v[194:197], v147 offset:36864
	ds_read_b128 v[198:201], v147 offset:37888
	ds_read_b128 v[202:205], v147 offset:38912
	ds_read_b128 v[206:209], v147 offset:39936
	s_add_u32 s36, s44, 0x2b0000
	s_addc_u32 s37, s45, 0
	s_mov_b32 m0, s52
	s_nop 0
	global_load_lds_dwordx4 v1, s[36:37]
	s_nop 0
	s_mov_b32 m0, s53
	s_nop 0
	global_load_lds_dwordx4 v141, s[36:37]
	s_waitcnt vmcnt(8)
	s_waitcnt lgkmcnt(0)
	s_barrier
	s_setprio 1
	s_waitcnt lgkmcnt(7)
	v_mfma_f32_16x16x32_bf16 v[126:129], v[134:137], v[178:181], v[126:129]
	v_mfma_f32_16x16x32_bf16 v[122:125], v[154:157], v[178:181], v[122:125]
	s_waitcnt lgkmcnt(5)
	v_mfma_f32_16x16x32_bf16 v[110:113], v[134:137], v[186:189], v[110:113]
	v_mfma_f32_16x16x32_bf16 v[106:109], v[154:157], v[186:189], v[106:109]
	s_waitcnt lgkmcnt(3)
	v_mfma_f32_16x16x32_bf16 v[94:97], v[134:137], v[194:197], v[94:97]
	v_mfma_f32_16x16x32_bf16 v[90:93], v[154:157], v[194:197], v[90:93]
	s_waitcnt lgkmcnt(1)
	v_mfma_f32_16x16x32_bf16 v[78:81], v[134:137], v[202:205], v[78:81]
	v_mfma_f32_16x16x32_bf16 v[74:77], v[154:157], v[202:205], v[74:77]
	v_mfma_f32_16x16x32_bf16 v[126:129], v[150:153], v[182:185], v[126:129]
	v_mfma_f32_16x16x32_bf16 v[122:125], v[158:161], v[182:185], v[122:125]
	v_mfma_f32_16x16x32_bf16 v[110:113], v[150:153], v[190:193], v[110:113]
	v_mfma_f32_16x16x32_bf16 v[106:109], v[158:161], v[190:193], v[106:109]
	v_mfma_f32_16x16x32_bf16 v[94:97], v[150:153], v[198:201], v[94:97]
	v_mfma_f32_16x16x32_bf16 v[90:93], v[158:161], v[198:201], v[90:93]
	s_waitcnt lgkmcnt(0)
	v_mfma_f32_16x16x32_bf16 v[78:81], v[150:153], v[206:209], v[78:81]
	v_mfma_f32_16x16x32_bf16 v[74:77], v[158:161], v[206:209], v[74:77]
	s_setprio 0
	s_setprio 1
	v_mfma_f32_16x16x32_bf16 v[118:121], v[162:165], v[178:181], v[118:121]
	v_mfma_f32_16x16x32_bf16 v[114:117], v[170:173], v[178:181], v[114:117]
	v_mfma_f32_16x16x32_bf16 v[102:105], v[162:165], v[186:189], v[102:105]
	v_mfma_f32_16x16x32_bf16 v[98:101], v[170:173], v[186:189], v[98:101]
	v_mfma_f32_16x16x32_bf16 v[86:89], v[162:165], v[194:197], v[86:89]
	v_mfma_f32_16x16x32_bf16 v[82:85], v[170:173], v[194:197], v[82:85]
	v_mfma_f32_16x16x32_bf16 v[70:73], v[162:165], v[202:205], v[70:73]
	v_mfma_f32_16x16x32_bf16 v[66:69], v[170:173], v[202:205], v[66:69]
	v_mfma_f32_16x16x32_bf16 v[118:121], v[166:169], v[182:185], v[118:121]
	v_mfma_f32_16x16x32_bf16 v[114:117], v[174:177], v[182:185], v[114:117]
	v_mfma_f32_16x16x32_bf16 v[102:105], v[166:169], v[190:193], v[102:105]
	v_mov_b32_e32 v248, v174
	v_mov_b32_e32 v249, v175
	v_mfma_f32_16x16x32_bf16 v[98:101], v[174:177], v[190:193], v[98:101]
	v_mov_b32_e32 v250, v176
	v_mov_b32_e32 v251, v177
	v_mfma_f32_16x16x32_bf16 v[86:89], v[166:169], v[198:201], v[86:89]
	v_mov_b32_e32 v252, v206
	v_mov_b32_e32 v253, v207
	v_mfma_f32_16x16x32_bf16 v[82:85], v[174:177], v[198:201], v[82:85]
	v_mov_b32_e32 v254, v208
	v_mov_b32_e32 v255, v209
	v_mfma_f32_16x16x32_bf16 v[70:73], v[166:169], v[206:209], v[70:73]
	s_setprio 2
	s_barrier
; #define PG8_STAGE(bufoff, gbase, voff) do { _Pragma("unroll") for (int _i = 0; _i < 2; ++_i) \
;         asm volatile("s_mov_b32 m0, %2\n\ts_nop 0\n\tglobal_load_lds_dwordx4 %0, %1" :: "v"((voff)[_i]), "s"((const char*)(gbase)), "s"(ldsbase + (unsigned)(bufoff) + ldsw + (unsigned)_i * 8192u) : "memory", "m0"); } while (0)
; #define PG8_LDA(dst, b, h) do { _Pragma("unroll") for (int m = 0; m < 4; ++m) _Pragma("unroll") for (int k = 0; k < 2; ++k) dst[m][k] = *(const PG8_LAS bf16x8*)(lds + PG8_SA(b, h) + aoff + m * 2048 + k * 1024); } while (0)
; #define PG8_MMA(ai, bj, At, Bt) do { __builtin_amdgcn_s_setprio(1); _Pragma("unroll") for (int m = 0; m < 4; ++m) _Pragma("unroll") for (int n = 0; n < 2; ++n) _Pragma("unroll") for (int k = 0; k < 2; ++k) \
;         acc[ai][bj][m][n] = __builtin_amdgcn_mfma_f32_16x16x32_bf16(Bt[n][k], At[m][k], acc[ai][bj][m][n], 0, 0, 0); __builtin_amdgcn_s_setprio(0); } while (0)
; #define PG8_WAIT_V(n) asm volatile("s_waitcnt vmcnt(" #n ")" ::: "memory")
; #define PG8_WAIT_L(n) asm volatile("s_waitcnt lgkmcnt(" #n ")" ::: "memory")
; #define PG8_BAR __builtin_amdgcn_s_barrier()
; #define PG8_SCHED __builtin_amdgcn_sched_barrier(0)
; template <class Epi, class Sched, bool ALIGN_EPI = false, bool SP2 = false>
; __device__ __forceinline__ void gemm_phase(PG8_LAS unsigned char* lds, const Gemm g, const Sched& S, const Epi& E) {
;     ...
;             PG8_WAIT_V(8); PG8_WAIT_L(0); PG8_BAR; PG8_MMA(0, 0, At, B0); PG8_MMA(0, 1, At, B1); PG8_BAR; PG8_SCHED;
;             PG8_LDA(At, 1, 1); PG8_STAGE(PG8_SB(1, 0), b3, voffB); PG8_STAGE(PG8_SB(1, 1), b3 + hstep, voffB); PG8_STAGE(PG8_SA(1, 0), a3, voffA);
;             PG8_WAIT_V(8); PG8_WAIT_L(0); PG8_BAR; PG8_MMA(1, 0, At, B0); PG8_MMA(1, 1, At, B1); PG8_BAR; PG8_SCHED;
	v_mfma_f32_16x16x32_bf16 v[66:69], v[248:251], v[252:255], v[66:69]
	s_setprio 0
	ds_read_b128 v[178:181], v147 offset:49152
	ds_read_b128 v[182:185], v147 offset:50176
	ds_read_b128 v[186:189], v147 offset:51200
	ds_read_b128 v[190:193], v147 offset:52224
	ds_read_b128 v[194:197], v147 offset:53248
	ds_read_b128 v[198:201], v147 offset:54272
	ds_read_b128 v[202:205], v147 offset:55296
	ds_read_b128 v[206:209], v147 offset:56320
	s_add_u32 s36, s42, 0x80
	s_addc_u32 s37, s43, 0
	s_mov_b32 m0, s54
	s_nop 0
	global_load_lds_dwordx4 v140, s[36:37]
	s_nop 0
	s_mov_b32 m0, s55
	s_nop 0
	global_load_lds_dwordx4 v142, s[36:37]
	s_add_u32 s36, s42, 0x2b0080
	s_addc_u32 s37, s43, 0
	s_mov_b32 m0, s58
	s_nop 0
	global_load_lds_dwordx4 v140, s[36:37]
	s_nop 0
	s_mov_b32 m0, s59
	s_nop 0
	global_load_lds_dwordx4 v142, s[36:37]
	s_nop 0
	s_mov_b32 m0, s56
	s_nop 0
	global_load_lds_dwordx4 v1, s[40:41]
	s_nop 0
	s_mov_b32 m0, s57
	s_nop 0
	global_load_lds_dwordx4 v141, s[40:41]
	s_waitcnt vmcnt(8)
	s_waitcnt lgkmcnt(0)
	s_barrier
	s_setprio 1
	s_waitcnt lgkmcnt(7)
	v_mfma_f32_16x16x32_bf16 v[62:65], v[134:137], v[178:181], v[62:65]
	v_mfma_f32_16x16x32_bf16 v[58:61], v[154:157], v[178:181], v[58:61]
	s_waitcnt lgkmcnt(5)
	v_mfma_f32_16x16x32_bf16 v[46:49], v[134:137], v[186:189], v[46:49]
	v_mfma_f32_16x16x32_bf16 v[42:45], v[154:157], v[186:189], v[42:45]
	s_waitcnt lgkmcnt(3)
	v_mfma_f32_16x16x32_bf16 v[30:33], v[134:137], v[194:197], v[30:33]
	v_mfma_f32_16x16x32_bf16 v[26:29], v[154:157], v[194:197], v[26:29]
	s_waitcnt lgkmcnt(1)
	v_mfma_f32_16x16x32_bf16 v[14:17], v[134:137], v[202:205], v[14:17]
	v_mfma_f32_16x16x32_bf16 v[10:13], v[154:157], v[202:205], v[10:13]
	v_mfma_f32_16x16x32_bf16 v[62:65], v[150:153], v[182:185], v[62:65]
	v_mfma_f32_16x16x32_bf16 v[58:61], v[158:161], v[182:185], v[58:61]
	v_mfma_f32_16x16x32_bf16 v[46:49], v[150:153], v[190:193], v[46:49]
	v_mfma_f32_16x16x32_bf16 v[42:45], v[158:161], v[190:193], v[42:45]
	v_mfma_f32_16x16x32_bf16 v[30:33], v[150:153], v[198:201], v[30:33]
	v_mfma_f32_16x16x32_bf16 v[26:29], v[158:161], v[198:201], v[26:29]
	s_waitcnt lgkmcnt(0)
	v_mfma_f32_16x16x32_bf16 v[14:17], v[150:153], v[206:209], v[14:17]
	v_mfma_f32_16x16x32_bf16 v[10:13], v[158:161], v[206:209], v[10:13]
	s_setprio 0
	s_setprio 1
	v_mfma_f32_16x16x32_bf16 v[54:57], v[162:165], v[178:181], v[54:57]
	v_mfma_f32_16x16x32_bf16 v[50:53], v[170:173], v[178:181], v[50:53]
	v_mfma_f32_16x16x32_bf16 v[38:41], v[162:165], v[186:189], v[38:41]
	v_mfma_f32_16x16x32_bf16 v[34:37], v[170:173], v[186:189], v[34:37]
	v_mfma_f32_16x16x32_bf16 v[22:25], v[162:165], v[194:197], v[22:25]
	v_mfma_f32_16x16x32_bf16 v[18:21], v[170:173], v[194:197], v[18:21]
	v_mfma_f32_16x16x32_bf16 v[6:9], v[162:165], v[202:205], v[6:9]
	v_mfma_f32_16x16x32_bf16 v[2:5], v[170:173], v[202:205], v[2:5]
	v_mfma_f32_16x16x32_bf16 v[54:57], v[166:169], v[182:185], v[54:57]
	v_mfma_f32_16x16x32_bf16 v[50:53], v[174:177], v[182:185], v[50:53]
	v_mfma_f32_16x16x32_bf16 v[38:41], v[166:169], v[190:193], v[38:41]
	v_mov_b32_e32 v248, v174
	v_mov_b32_e32 v249, v175
	v_mfma_f32_16x16x32_bf16 v[34:37], v[174:177], v[190:193], v[34:37]
	v_mov_b32_e32 v250, v176
	v_mov_b32_e32 v251, v177
	v_mfma_f32_16x16x32_bf16 v[22:25], v[166:169], v[198:201], v[22:25]
	v_mov_b32_e32 v252, v206
	v_mov_b32_e32 v253, v207
	v_mfma_f32_16x16x32_bf16 v[18:21], v[174:177], v[198:201], v[18:21]
	v_mov_b32_e32 v254, v208
	v_mov_b32_e32 v255, v209
	v_mfma_f32_16x16x32_bf16 v[6:9], v[166:169], v[206:209], v[6:9]
	s_setprio 2
	s_barrier
	v_mfma_f32_16x16x32_bf16 v[2:5], v[248:251], v[252:255], v[2:5]
	s_setprio 0
	s_add_i32 s69, s69, 2
	s_add_u32 s67, s67, 0x100
	s_addc_u32 s68, s68, 0
	s_cmpk_gt_u32 s69, 0xa9
	s_mov_b64 s[36:37], s[38:39]
	s_cbranch_scc0 .LBB0_873
	s_and_b64 vcc, exec, s[10:11]
	s_cbranch_vccz .LBB0_876
	s_barrier

; __global__ void __launch_bounds__(NWAVES * 64, 2) fwd(Args args) {
;     extern __shared__ __attribute__((aligned(16))) unsigned char lds[];
	.amdhsa_kernel _Z3fwd4Args
		.amdhsa_group_segment_fixed_size 0
		.amdhsa_private_segment_fixed_size 0
		.amdhsa_kernarg_size 448
		.amdhsa_user_sgpr_count 2
		.amdhsa_user_sgpr_dispatch_ptr 0
		.amdhsa_user_sgpr_queue_ptr 0
		.amdhsa_user_sgpr_kernarg_segment_ptr 1
		.amdhsa_user_sgpr_dispatch_id 0
		.amdhsa_user_sgpr_kernarg_preload_length 0
		.amdhsa_user_sgpr_kernarg_preload_offset 0
		.amdhsa_user_sgpr_private_segment_size 0
		.amdhsa_uses_dynamic_stack 0
		.amdhsa_enable_private_segment 0
		.amdhsa_system_sgpr_workgroup_id_x 1
		.amdhsa_system_sgpr_workgroup_id_y 0
		.amdhsa_system_sgpr_workgroup_id_z 0
		.amdhsa_system_sgpr_workgroup_info 0
		.amdhsa_system_vgpr_workitem_id 0
		.amdhsa_next_free_vgpr 256
		.amdhsa_next_free_sgpr 98
		.amdhsa_accum_offset 256
		.amdhsa_reserve_vcc 1
		.amdhsa_float_round_mode_32 0
		.amdhsa_float_round_mode_16_64 0
		.amdhsa_float_denorm_mode_32 3
		.amdhsa_float_denorm_mode_16_64 3
		.amdhsa_dx10_clamp 1
		.amdhsa_ieee_mode 1
		.amdhsa_fp16_overflow 0
		.amdhsa_tg_split 0
		.amdhsa_exception_fp_ieee_invalid_op 0
		.amdhsa_exception_fp_denorm_src 0
		.amdhsa_exception_fp_ieee_div_zero 0
		.amdhsa_exception_fp_ieee_overflow 0
		.amdhsa_exception_fp_ieee_underflow 0
		.amdhsa_exception_fp_ieee_inexact 0
		.amdhsa_exception_int_div_zero 0
	.end_amdhsa_kernel

; __global__ void __launch_bounds__(NWAVES * 64, 2) fwd(Args args) {
amdhsa.kernels:
  - .agpr_count:     0
    .args:
      - .offset:         0
        .size:           192
        .value_kind:     by_value
      - .offset:         192
        .size:           4
        .value_kind:     hidden_block_count_x
      - .offset:         196
        .size:           4
        .value_kind:     hidden_block_count_y
      - .offset:         200
        .size:           4
        .value_kind:     hidden_block_count_z
      - .offset:         204
        .size:           2
        .value_kind:     hidden_group_size_x
      - .offset:         206
        .size:           2
        .value_kind:     hidden_group_size_y
      - .offset:         208
        .size:           2
        .value_kind:     hidden_group_size_z
      - .offset:         210
        .size:           2
        .value_kind:     hidden_remainder_x
      - .offset:         212
        .size:           2
        .value_kind:     hidden_remainder_y
      - .offset:         214
        .size:           2
        .value_kind:     hidden_remainder_z
      - .offset:         232
        .size:           8
        .value_kind:     hidden_global_offset_x
      - .offset:         240
        .size:           8
        .value_kind:     hidden_global_offset_y
      - .offset:         248
        .size:           8
        .value_kind:     hidden_global_offset_z
      - .offset:         256
        .size:           2
        .value_kind:     hidden_grid_dims
      - .offset:         312
        .size:           4
        .value_kind:     hidden_dynamic_lds_size
    .group_segment_fixed_size: 0
    .kernarg_segment_align: 8
    .kernarg_segment_size: 448
    .language:       OpenCL C
    .language_version:
      - 2
      - 0
    .max_flat_workgroup_size: 512
    .name:           _Z3fwd4Args
    .private_segment_fixed_size: 0
    .sgpr_count:     104
    .sgpr_spill_count: 30
    .symbol:         _Z3fwd4Args.kd
    .uniform_work_group_size: 1
    .uses_dynamic_stack: false
    .vgpr_count:     256
    .vgpr_spill_count: 0
    .wavefront_size: 64
